# plus BranchF mid-K gate prefetch 4 groups ahead, final RMSNorm x-chunk loads hoisted with counted waits, BranchF epilogue gate prefetch
# speedup vs baseline: 1.0104x; 1.0104x over previous
.LBB0_1135:
	s_andn2_b64 vcc, exec, s[2:3]
	s_cbranch_vccnz .LBB0_1137
	v_mov_b32_e32 v0, v150
	v_mov_b32_e32 v2, v151
	s_cmpk_eq_i32 s56, 0x800
	v_lshl_add_u32 v144, v2, 2, s68
	v_add_u32_e32 v0, s69, v0
	v_mov_b64_e32 v[2:3], s[46:47]
	s_cselect_b32 s10, 0, 0x1000
	v_ashrrev_i32_e32 v145, 31, v144
	v_mad_i64_i32 v[146:147], s[2:3], v0, s78, v[2:3]
	v_lshl_add_u64 v[146:147], v[146:147], 0, s[10:11]
	v_lshlrev_b64 v[144:145], 1, v[144:145]
	v_lshl_add_u64 v[146:147], v[146:147], 0, v[144:145]
	v_mov_b32_e32 v244, v0
	v_mad_i64_i32 v[244:245], s[2:3], v244, s78, v[2:3]
	v_lshl_add_u64 v[244:245], v[244:245], 0, s[10:11]
	v_lshl_add_u64 v[244:245], v[244:245], 0, v[144:145]
	v_add_co_u32_e32 v246, vcc, s89, v244
	s_nop 1
	v_addc_co_u32_e32 v247, vcc, 0, v245, vcc
	global_load_dwordx2 v[164:165], v[244:245], off
	global_load_dwordx2 v[166:167], v[246:247], off
	global_load_dwordx2 v[168:169], v[246:247], off offset:32
	global_load_dwordx2 v[170:171], v[244:245], off offset:32
	global_load_dwordx2 v[172:173], v[244:245], off offset:256
	global_load_dwordx2 v[174:175], v[246:247], off offset:256
	global_load_dwordx2 v[176:177], v[246:247], off offset:288
	global_load_dwordx2 v[178:179], v[244:245], off offset:288
	v_add_u32_e32 v244, 0x10, v0
	v_mad_i64_i32 v[244:245], s[2:3], v244, s78, v[2:3]
	v_lshl_add_u64 v[244:245], v[244:245], 0, s[10:11]
	v_lshl_add_u64 v[244:245], v[244:245], 0, v[144:145]
	v_add_co_u32_e32 v246, vcc, s89, v244
	s_nop 1
	v_addc_co_u32_e32 v247, vcc, 0, v245, vcc
	global_load_dwordx2 v[180:181], v[244:245], off
	global_load_dwordx2 v[182:183], v[246:247], off
	global_load_dwordx2 v[184:185], v[246:247], off offset:32
	global_load_dwordx2 v[186:187], v[244:245], off offset:32
	global_load_dwordx2 v[188:189], v[244:245], off offset:256
	global_load_dwordx2 v[190:191], v[246:247], off offset:256
	global_load_dwordx2 v[192:193], v[246:247], off offset:288
	global_load_dwordx2 v[194:195], v[244:245], off offset:288
	v_add_u32_e32 v244, 0x20, v0
	v_mad_i64_i32 v[244:245], s[2:3], v244, s78, v[2:3]
	v_lshl_add_u64 v[244:245], v[244:245], 0, s[10:11]
	v_lshl_add_u64 v[244:245], v[244:245], 0, v[144:145]
	v_add_co_u32_e32 v246, vcc, s89, v244
	s_nop 1
	v_addc_co_u32_e32 v247, vcc, 0, v245, vcc
	global_load_dwordx2 v[196:197], v[244:245], off
	global_load_dwordx2 v[198:199], v[246:247], off
	global_load_dwordx2 v[200:201], v[246:247], off offset:32
	global_load_dwordx2 v[202:203], v[244:245], off offset:32
	global_load_dwordx2 v[204:205], v[244:245], off offset:256
	global_load_dwordx2 v[206:207], v[246:247], off offset:256
	global_load_dwordx2 v[208:209], v[246:247], off offset:288
	global_load_dwordx2 v[218:219], v[244:245], off offset:288
	v_add_u32_e32 v244, 0x30, v0
	v_mad_i64_i32 v[244:245], s[2:3], v244, s78, v[2:3]
	v_lshl_add_u64 v[244:245], v[244:245], 0, s[10:11]
	v_lshl_add_u64 v[244:245], v[244:245], 0, v[144:145]
	v_add_co_u32_e32 v246, vcc, s89, v244
	s_nop 1
	v_addc_co_u32_e32 v247, vcc, 0, v245, vcc
	global_load_dwordx2 v[220:221], v[244:245], off
	global_load_dwordx2 v[222:223], v[246:247], off
	global_load_dwordx2 v[224:225], v[246:247], off offset:32
	global_load_dwordx2 v[232:233], v[244:245], off offset:32
	global_load_dwordx2 v[234:235], v[244:245], off offset:256
	global_load_dwordx2 v[236:237], v[246:247], off offset:256
	global_load_dwordx2 v[238:239], v[246:247], off offset:288
	global_load_dwordx2 v[240:241], v[244:245], off offset:288
	s_waitcnt vmcnt(31)
	v_mov_b32_e32 v156, v164
	v_mov_b32_e32 v157, v165
	v_add_co_u32_e32 v148, vcc, s89, v146
	s_nop 1
	v_addc_co_u32_e32 v149, vcc, 0, v147, vcc
	s_waitcnt vmcnt(30)
	v_mov_b32_e32 v158, v166
	v_mov_b32_e32 v159, v167
	s_nop 0
	v_lshlrev_b32_e32 v161, 16, v156
	v_and_b32_e32 v156, 0xffff0000, v156
	v_mul_f32_e32 v156, 0xbfb8aa3b, v156
	v_exp_f32_e32 v156, v156
	v_mul_f32_e32 v161, 0xbfb8aa3b, v161
	v_exp_f32_e32 v161, v161
	v_lshlrev_b32_e32 v160, 16, v158
	v_add_f32_e32 v156, 1.0, v156
	v_and_b32_e32 v158, 0xffff0000, v158
	v_rcp_f32_e32 v163, v156
	v_lshlrev_b32_e32 v156, 16, v159
	v_add_f32_e32 v161, 1.0, v161
	v_mul_f32_e32 v158, 0xbfb8aa3b, v158
	v_mul_f32_e32 v156, 0xbfb8aa3b, v156
	v_rcp_f32_e32 v162, v161
	v_exp_f32_e32 v161, v158
	v_exp_f32_e32 v158, v156
	v_lshlrev_b32_e32 v156, 16, v157
	v_and_b32_e32 v157, 0xffff0000, v157
	v_mul_f32_e32 v156, 0xbfb8aa3b, v156
	v_mul_f32_e32 v157, 0xbfb8aa3b, v157
	v_exp_f32_e32 v156, v156
	v_exp_f32_e32 v157, v157
	v_and_b32_e32 v159, 0xffff0000, v159
	v_mul_f32_e32 v159, 0xbfb8aa3b, v159
	v_add_f32_e32 v156, 1.0, v156
	v_exp_f32_e32 v159, v159
	v_add_f32_e32 v157, 1.0, v157
	v_rcp_f32_e32 v156, v156
	v_rcp_f32_e32 v157, v157
	v_pk_add_f32 v[158:159], v[158:159], 1.0 op_sel_hi:[1,0]
	v_mul_f32_e32 v160, 0xbfb8aa3b, v160
	v_exp_f32_e32 v160, v160
	v_pk_mul_f32 v[156:157], v[158:159], v[156:157]
	v_pk_add_f32 v[160:161], v[160:161], 1.0 op_sel_hi:[1,0]
	v_pk_mul_f32 v[130:131], v[130:131], v[156:157]
	s_waitcnt vmcnt(29)
	v_mov_b32_e32 v156, v168
	v_mov_b32_e32 v157, v169
	s_waitcnt vmcnt(28)
	v_mov_b32_e32 v158, v170
	v_mov_b32_e32 v159, v171
	v_pk_mul_f32 v[160:161], v[160:161], v[162:163]
	s_nop 0
	v_pk_mul_f32 v[128:129], v[128:129], v[160:161]
	s_nop 0
	v_lshlrev_b32_e32 v160, 16, v156
	v_lshlrev_b32_e32 v161, 16, v158
	v_mul_f32_e32 v161, 0xbfb8aa3b, v161
	v_exp_f32_e32 v161, v161
	v_and_b32_e32 v156, 0xffff0000, v156
	v_mul_f32_e32 v156, 0xbfb8aa3b, v156
	v_mul_f32_e32 v160, 0xbfb8aa3b, v160
	v_add_f32_e32 v161, 1.0, v161
	v_rcp_f32_e32 v162, v161
	v_exp_f32_e32 v161, v156
	v_and_b32_e32 v156, 0xffff0000, v158
	v_mul_f32_e32 v156, 0xbfb8aa3b, v156
	v_exp_f32_e32 v156, v156
	v_lshlrev_b32_e32 v158, 16, v159
	v_and_b32_e32 v159, 0xffff0000, v159
	v_mul_f32_e32 v158, 0xbfb8aa3b, v158
	v_mul_f32_e32 v159, 0xbfb8aa3b, v159
	v_exp_f32_e32 v158, v158
	v_exp_f32_e32 v159, v159
	v_add_f32_e32 v156, 1.0, v156
	v_rcp_f32_e32 v163, v156
	v_lshlrev_b32_e32 v156, 16, v157
	v_and_b32_e32 v157, 0xffff0000, v157
	v_mul_f32_e32 v156, 0xbfb8aa3b, v156
	v_mul_f32_e32 v157, 0xbfb8aa3b, v157
	v_exp_f32_e32 v156, v156
	v_add_f32_e32 v158, 1.0, v158
	v_exp_f32_e32 v157, v157
	v_add_f32_e32 v159, 1.0, v159
	v_rcp_f32_e32 v158, v158
	v_rcp_f32_e32 v159, v159
	v_pk_add_f32 v[156:157], v[156:157], 1.0 op_sel_hi:[1,0]
	v_exp_f32_e32 v160, v160
	v_pk_mul_f32 v[156:157], v[156:157], v[158:159]
	s_nop 0
	v_pk_mul_f32 v[126:127], v[126:127], v[156:157]
	s_waitcnt vmcnt(27)
	v_mov_b32_e32 v156, v172
	v_mov_b32_e32 v157, v173
	s_waitcnt vmcnt(26)
	v_mov_b32_e32 v158, v174
	v_mov_b32_e32 v159, v175
	s_nop 0
	s_waitcnt vmcnt(25)
	v_mov_b32_e32 v148, v176
	v_mov_b32_e32 v149, v177
	s_nop 0
	s_waitcnt vmcnt(24)
	v_mov_b32_e32 v146, v178
	v_mov_b32_e32 v147, v179
	v_add_u32_e32 v244, 0x80, v0
	v_mad_i64_i32 v[244:245], s[2:3], v244, s78, v[2:3]
	v_lshl_add_u64 v[244:245], v[244:245], 0, s[10:11]
	v_lshl_add_u64 v[244:245], v[244:245], 0, v[144:145]
	v_add_co_u32_e32 v246, vcc, s89, v244
	s_nop 1
	v_addc_co_u32_e32 v247, vcc, 0, v245, vcc
	global_load_dwordx2 v[164:165], v[244:245], off
	global_load_dwordx2 v[166:167], v[246:247], off
	global_load_dwordx2 v[168:169], v[246:247], off offset:32
	global_load_dwordx2 v[170:171], v[244:245], off offset:32
	global_load_dwordx2 v[172:173], v[244:245], off offset:256
	global_load_dwordx2 v[174:175], v[246:247], off offset:256
	global_load_dwordx2 v[176:177], v[246:247], off offset:288
	global_load_dwordx2 v[178:179], v[244:245], off offset:288
	v_pk_add_f32 v[160:161], v[160:161], 1.0 op_sel_hi:[1,0]
	s_nop 0
	v_pk_mul_f32 v[160:161], v[160:161], v[162:163]
	s_nop 0
	v_pk_mul_f32 v[124:125], v[124:125], v[160:161]
	s_nop 0
	v_lshlrev_b32_e32 v161, 16, v156
	v_and_b32_e32 v156, 0xffff0000, v156
	v_mul_f32_e32 v156, 0xbfb8aa3b, v156
	v_exp_f32_e32 v156, v156
	v_mul_f32_e32 v161, 0xbfb8aa3b, v161
	v_exp_f32_e32 v161, v161
	v_lshlrev_b32_e32 v160, 16, v158
	v_add_f32_e32 v156, 1.0, v156
	v_and_b32_e32 v158, 0xffff0000, v158
	v_rcp_f32_e32 v163, v156
	v_lshlrev_b32_e32 v156, 16, v159
	v_add_f32_e32 v161, 1.0, v161
	v_mul_f32_e32 v158, 0xbfb8aa3b, v158
	v_mul_f32_e32 v156, 0xbfb8aa3b, v156
	v_rcp_f32_e32 v162, v161
	v_exp_f32_e32 v161, v158
	v_exp_f32_e32 v158, v156
	v_lshlrev_b32_e32 v156, 16, v157
	v_and_b32_e32 v157, 0xffff0000, v157
	v_mul_f32_e32 v156, 0xbfb8aa3b, v156
	v_mul_f32_e32 v157, 0xbfb8aa3b, v157
	v_exp_f32_e32 v156, v156
	v_exp_f32_e32 v157, v157
	v_and_b32_e32 v159, 0xffff0000, v159
	v_mul_f32_e32 v159, 0xbfb8aa3b, v159
	v_add_f32_e32 v156, 1.0, v156
	v_exp_f32_e32 v159, v159
	v_add_f32_e32 v157, 1.0, v157
	v_rcp_f32_e32 v156, v156
	v_rcp_f32_e32 v157, v157
	v_pk_add_f32 v[158:159], v[158:159], 1.0 op_sel_hi:[1,0]
	v_mul_f32_e32 v160, 0xbfb8aa3b, v160
	v_exp_f32_e32 v160, v160
	v_pk_mul_f32 v[156:157], v[158:159], v[156:157]
	v_pk_add_f32 v[160:161], v[160:161], 1.0 op_sel_hi:[1,0]
	v_pk_mul_f32 v[122:123], v[122:123], v[156:157]
	v_lshlrev_b32_e32 v157, 16, v146
	v_and_b32_e32 v146, 0xffff0000, v146
	v_mul_f32_e32 v146, 0xbfb8aa3b, v146
	v_exp_f32_e32 v146, v146
	v_mul_f32_e32 v157, 0xbfb8aa3b, v157
	v_exp_f32_e32 v157, v157
	v_lshlrev_b32_e32 v156, 16, v148
	v_add_f32_e32 v146, 1.0, v146
	v_and_b32_e32 v148, 0xffff0000, v148
	v_rcp_f32_e32 v159, v146
	v_lshlrev_b32_e32 v146, 16, v149
	v_add_f32_e32 v157, 1.0, v157
	v_mul_f32_e32 v148, 0xbfb8aa3b, v148
	v_mul_f32_e32 v146, 0xbfb8aa3b, v146
	v_rcp_f32_e32 v158, v157
	v_exp_f32_e32 v157, v148
	v_exp_f32_e32 v148, v146
	v_lshlrev_b32_e32 v146, 16, v147
	v_and_b32_e32 v147, 0xffff0000, v147
	v_mul_f32_e32 v146, 0xbfb8aa3b, v146
	v_mul_f32_e32 v147, 0xbfb8aa3b, v147
	v_exp_f32_e32 v146, v146
	v_exp_f32_e32 v147, v147
	v_and_b32_e32 v149, 0xffff0000, v149
	v_mul_f32_e32 v149, 0xbfb8aa3b, v149
	v_add_f32_e32 v146, 1.0, v146
	v_exp_f32_e32 v149, v149
	v_add_f32_e32 v147, 1.0, v147
	v_rcp_f32_e32 v146, v146
	v_rcp_f32_e32 v147, v147
	v_mul_f32_e32 v156, 0xbfb8aa3b, v156
	v_exp_f32_e32 v156, v156
	v_pk_add_f32 v[148:149], v[148:149], 1.0 op_sel_hi:[1,0]
	v_pk_mul_f32 v[160:161], v[160:161], v[162:163]
	v_pk_mul_f32 v[146:147], v[148:149], v[146:147]
	v_pk_add_f32 v[156:157], v[156:157], 1.0 op_sel_hi:[1,0]
	v_pk_mul_f32 v[118:119], v[118:119], v[146:147]
	v_add_u32_e32 v146, 16, v0
	v_mad_i64_i32 v[146:147], s[2:3], v146, s78, v[2:3]
	v_lshl_add_u64 v[146:147], v[146:147], 0, s[10:11]
	v_pk_mul_f32 v[156:157], v[156:157], v[158:159]
	v_lshl_add_u64 v[146:147], v[146:147], 0, v[144:145]
	v_pk_mul_f32 v[116:117], v[116:117], v[156:157]
	s_waitcnt vmcnt(31)
	v_mov_b32_e32 v156, v180
	v_mov_b32_e32 v157, v181
	v_add_co_u32_e32 v148, vcc, s89, v146
	v_pk_mul_f32 v[120:121], v[120:121], v[160:161]
	s_nop 0
	v_addc_co_u32_e32 v149, vcc, 0, v147, vcc
	s_waitcnt vmcnt(30)
	v_mov_b32_e32 v158, v182
	v_mov_b32_e32 v159, v183
	s_nop 0
	v_lshlrev_b32_e32 v161, 16, v156
	v_and_b32_e32 v156, 0xffff0000, v156
	v_mul_f32_e32 v156, 0xbfb8aa3b, v156
	v_exp_f32_e32 v156, v156
	v_mul_f32_e32 v161, 0xbfb8aa3b, v161
	v_exp_f32_e32 v161, v161
	v_lshlrev_b32_e32 v160, 16, v158
	v_add_f32_e32 v156, 1.0, v156
	v_and_b32_e32 v158, 0xffff0000, v158
	v_rcp_f32_e32 v163, v156
	v_lshlrev_b32_e32 v156, 16, v159
	v_add_f32_e32 v161, 1.0, v161
	v_mul_f32_e32 v158, 0xbfb8aa3b, v158
	v_mul_f32_e32 v156, 0xbfb8aa3b, v156
	v_rcp_f32_e32 v162, v161
	v_exp_f32_e32 v161, v158
	v_exp_f32_e32 v158, v156
	v_lshlrev_b32_e32 v156, 16, v157
	v_and_b32_e32 v157, 0xffff0000, v157
	v_mul_f32_e32 v156, 0xbfb8aa3b, v156
	v_mul_f32_e32 v157, 0xbfb8aa3b, v157
	v_exp_f32_e32 v156, v156
	v_exp_f32_e32 v157, v157
	v_and_b32_e32 v159, 0xffff0000, v159
	v_mul_f32_e32 v159, 0xbfb8aa3b, v159
	v_add_f32_e32 v156, 1.0, v156
	v_exp_f32_e32 v159, v159
	v_add_f32_e32 v157, 1.0, v157
	v_rcp_f32_e32 v156, v156
	v_rcp_f32_e32 v157, v157
	v_pk_add_f32 v[158:159], v[158:159], 1.0 op_sel_hi:[1,0]
	v_mul_f32_e32 v160, 0xbfb8aa3b, v160
	v_exp_f32_e32 v160, v160
	v_pk_mul_f32 v[156:157], v[158:159], v[156:157]
	v_pk_add_f32 v[160:161], v[160:161], 1.0 op_sel_hi:[1,0]
	v_pk_mul_f32 v[114:115], v[114:115], v[156:157]
	s_waitcnt vmcnt(29)
	v_mov_b32_e32 v156, v184
	v_mov_b32_e32 v157, v185
	s_waitcnt vmcnt(28)
	v_mov_b32_e32 v158, v186
	v_mov_b32_e32 v159, v187
	v_pk_mul_f32 v[160:161], v[160:161], v[162:163]
	s_nop 0
	v_pk_mul_f32 v[112:113], v[112:113], v[160:161]
	s_nop 0
	v_lshlrev_b32_e32 v160, 16, v156
	v_lshlrev_b32_e32 v161, 16, v158
	v_mul_f32_e32 v161, 0xbfb8aa3b, v161
	v_exp_f32_e32 v161, v161
	v_and_b32_e32 v156, 0xffff0000, v156
	v_mul_f32_e32 v156, 0xbfb8aa3b, v156
	v_mul_f32_e32 v160, 0xbfb8aa3b, v160
	v_add_f32_e32 v161, 1.0, v161
	v_rcp_f32_e32 v162, v161
	v_exp_f32_e32 v161, v156
	v_and_b32_e32 v156, 0xffff0000, v158
	v_mul_f32_e32 v156, 0xbfb8aa3b, v156
	v_exp_f32_e32 v156, v156
	v_lshlrev_b32_e32 v158, 16, v159
	v_and_b32_e32 v159, 0xffff0000, v159
	v_mul_f32_e32 v158, 0xbfb8aa3b, v158
	v_mul_f32_e32 v159, 0xbfb8aa3b, v159
	v_exp_f32_e32 v158, v158
	v_exp_f32_e32 v159, v159
	v_add_f32_e32 v156, 1.0, v156
	v_rcp_f32_e32 v163, v156
	v_lshlrev_b32_e32 v156, 16, v157
	v_and_b32_e32 v157, 0xffff0000, v157
	v_mul_f32_e32 v156, 0xbfb8aa3b, v156
	v_mul_f32_e32 v157, 0xbfb8aa3b, v157
	v_exp_f32_e32 v156, v156
	v_add_f32_e32 v158, 1.0, v158
	v_exp_f32_e32 v157, v157
	v_add_f32_e32 v159, 1.0, v159
	v_rcp_f32_e32 v158, v158
	v_rcp_f32_e32 v159, v159
	v_pk_add_f32 v[156:157], v[156:157], 1.0 op_sel_hi:[1,0]
	v_exp_f32_e32 v160, v160
	v_pk_mul_f32 v[156:157], v[156:157], v[158:159]
	s_nop 0
	v_pk_mul_f32 v[110:111], v[110:111], v[156:157]
	s_waitcnt vmcnt(27)
	v_mov_b32_e32 v156, v188
	v_mov_b32_e32 v157, v189
	s_waitcnt vmcnt(26)
	v_mov_b32_e32 v158, v190
	v_mov_b32_e32 v159, v191
	s_nop 0
	s_waitcnt vmcnt(25)
	v_mov_b32_e32 v148, v192
	v_mov_b32_e32 v149, v193
	s_nop 0
	s_waitcnt vmcnt(24)
	v_mov_b32_e32 v146, v194
	v_mov_b32_e32 v147, v195
	v_add_u32_e32 v244, 0x90, v0
	v_mad_i64_i32 v[244:245], s[2:3], v244, s78, v[2:3]
	v_lshl_add_u64 v[244:245], v[244:245], 0, s[10:11]
	v_lshl_add_u64 v[244:245], v[244:245], 0, v[144:145]
	v_add_co_u32_e32 v246, vcc, s89, v244
	s_nop 1
	v_addc_co_u32_e32 v247, vcc, 0, v245, vcc
	global_load_dwordx2 v[180:181], v[244:245], off
	global_load_dwordx2 v[182:183], v[246:247], off
	global_load_dwordx2 v[184:185], v[246:247], off offset:32
	global_load_dwordx2 v[186:187], v[244:245], off offset:32
	global_load_dwordx2 v[188:189], v[244:245], off offset:256
	global_load_dwordx2 v[190:191], v[246:247], off offset:256
	global_load_dwordx2 v[192:193], v[246:247], off offset:288
	global_load_dwordx2 v[194:195], v[244:245], off offset:288
	v_pk_add_f32 v[160:161], v[160:161], 1.0 op_sel_hi:[1,0]
	s_nop 0
	v_pk_mul_f32 v[160:161], v[160:161], v[162:163]
	s_nop 0
	v_pk_mul_f32 v[108:109], v[108:109], v[160:161]
	s_nop 0
	v_lshlrev_b32_e32 v161, 16, v156
	v_and_b32_e32 v156, 0xffff0000, v156
	v_mul_f32_e32 v156, 0xbfb8aa3b, v156
	v_exp_f32_e32 v156, v156
	v_mul_f32_e32 v161, 0xbfb8aa3b, v161
	v_exp_f32_e32 v161, v161
	v_lshlrev_b32_e32 v160, 16, v158
	v_add_f32_e32 v156, 1.0, v156
	v_and_b32_e32 v158, 0xffff0000, v158
	v_rcp_f32_e32 v163, v156
	v_lshlrev_b32_e32 v156, 16, v159
	v_add_f32_e32 v161, 1.0, v161
	v_mul_f32_e32 v158, 0xbfb8aa3b, v158
	v_mul_f32_e32 v156, 0xbfb8aa3b, v156
	v_rcp_f32_e32 v162, v161
	v_exp_f32_e32 v161, v158
	v_exp_f32_e32 v158, v156
	v_lshlrev_b32_e32 v156, 16, v157
	v_and_b32_e32 v157, 0xffff0000, v157
	v_mul_f32_e32 v156, 0xbfb8aa3b, v156
	v_mul_f32_e32 v157, 0xbfb8aa3b, v157
	v_exp_f32_e32 v156, v156
	v_exp_f32_e32 v157, v157
	v_and_b32_e32 v159, 0xffff0000, v159
	v_mul_f32_e32 v159, 0xbfb8aa3b, v159
	v_add_f32_e32 v156, 1.0, v156
	v_exp_f32_e32 v159, v159
	v_add_f32_e32 v157, 1.0, v157
	v_rcp_f32_e32 v156, v156
	v_rcp_f32_e32 v157, v157
	v_pk_add_f32 v[158:159], v[158:159], 1.0 op_sel_hi:[1,0]
	v_mul_f32_e32 v160, 0xbfb8aa3b, v160
	v_exp_f32_e32 v160, v160
	v_pk_mul_f32 v[156:157], v[158:159], v[156:157]
	v_pk_add_f32 v[160:161], v[160:161], 1.0 op_sel_hi:[1,0]
	v_pk_mul_f32 v[106:107], v[106:107], v[156:157]
	v_lshlrev_b32_e32 v157, 16, v146
	v_and_b32_e32 v146, 0xffff0000, v146
	v_mul_f32_e32 v146, 0xbfb8aa3b, v146
	v_exp_f32_e32 v146, v146
	v_mul_f32_e32 v157, 0xbfb8aa3b, v157
	v_exp_f32_e32 v157, v157
	v_lshlrev_b32_e32 v156, 16, v148
	v_add_f32_e32 v146, 1.0, v146
	v_and_b32_e32 v148, 0xffff0000, v148
	v_rcp_f32_e32 v159, v146
	v_lshlrev_b32_e32 v146, 16, v149
	v_add_f32_e32 v157, 1.0, v157
	v_mul_f32_e32 v148, 0xbfb8aa3b, v148
	v_mul_f32_e32 v146, 0xbfb8aa3b, v146
	v_rcp_f32_e32 v158, v157
	v_exp_f32_e32 v157, v148
	v_exp_f32_e32 v148, v146
	v_lshlrev_b32_e32 v146, 16, v147
	v_and_b32_e32 v147, 0xffff0000, v147
	v_mul_f32_e32 v146, 0xbfb8aa3b, v146
	v_mul_f32_e32 v147, 0xbfb8aa3b, v147
	v_exp_f32_e32 v146, v146
	v_exp_f32_e32 v147, v147
	v_and_b32_e32 v149, 0xffff0000, v149
	v_mul_f32_e32 v149, 0xbfb8aa3b, v149
	v_add_f32_e32 v146, 1.0, v146
	v_exp_f32_e32 v149, v149
	v_add_f32_e32 v147, 1.0, v147
	v_rcp_f32_e32 v146, v146
	v_rcp_f32_e32 v147, v147
	v_mul_f32_e32 v156, 0xbfb8aa3b, v156
	v_exp_f32_e32 v156, v156
	v_pk_add_f32 v[148:149], v[148:149], 1.0 op_sel_hi:[1,0]
	v_pk_mul_f32 v[160:161], v[160:161], v[162:163]
	v_pk_mul_f32 v[146:147], v[148:149], v[146:147]
	v_pk_add_f32 v[156:157], v[156:157], 1.0 op_sel_hi:[1,0]
	v_pk_mul_f32 v[102:103], v[102:103], v[146:147]
	v_add_u32_e32 v146, 32, v0
	v_mad_i64_i32 v[146:147], s[2:3], v146, s78, v[2:3]
	v_lshl_add_u64 v[146:147], v[146:147], 0, s[10:11]
	v_pk_mul_f32 v[156:157], v[156:157], v[158:159]
	v_lshl_add_u64 v[146:147], v[146:147], 0, v[144:145]
	v_pk_mul_f32 v[100:101], v[100:101], v[156:157]
	s_waitcnt vmcnt(31)
	v_mov_b32_e32 v156, v196
	v_mov_b32_e32 v157, v197
	v_add_co_u32_e32 v148, vcc, s89, v146
	v_pk_mul_f32 v[104:105], v[104:105], v[160:161]
	s_nop 0
	v_addc_co_u32_e32 v149, vcc, 0, v147, vcc
	s_waitcnt vmcnt(30)
	v_mov_b32_e32 v158, v198
	v_mov_b32_e32 v159, v199
	s_nop 0
	v_lshlrev_b32_e32 v161, 16, v156
	v_and_b32_e32 v156, 0xffff0000, v156
	v_mul_f32_e32 v156, 0xbfb8aa3b, v156
	v_exp_f32_e32 v156, v156
	v_mul_f32_e32 v161, 0xbfb8aa3b, v161
	v_exp_f32_e32 v161, v161
	v_lshlrev_b32_e32 v160, 16, v158
	v_add_f32_e32 v156, 1.0, v156
	v_and_b32_e32 v158, 0xffff0000, v158
	v_rcp_f32_e32 v163, v156
	v_lshlrev_b32_e32 v156, 16, v159
	v_add_f32_e32 v161, 1.0, v161
	v_mul_f32_e32 v158, 0xbfb8aa3b, v158
	v_mul_f32_e32 v156, 0xbfb8aa3b, v156
	v_rcp_f32_e32 v162, v161
	v_exp_f32_e32 v161, v158
	v_exp_f32_e32 v158, v156
	v_lshlrev_b32_e32 v156, 16, v157
	v_and_b32_e32 v157, 0xffff0000, v157
	v_mul_f32_e32 v156, 0xbfb8aa3b, v156
	v_mul_f32_e32 v157, 0xbfb8aa3b, v157
	v_exp_f32_e32 v156, v156
	v_exp_f32_e32 v157, v157
	v_and_b32_e32 v159, 0xffff0000, v159
	v_mul_f32_e32 v159, 0xbfb8aa3b, v159
	v_add_f32_e32 v156, 1.0, v156
	v_exp_f32_e32 v159, v159
	v_add_f32_e32 v157, 1.0, v157
	v_rcp_f32_e32 v156, v156
	v_rcp_f32_e32 v157, v157
	v_pk_add_f32 v[158:159], v[158:159], 1.0 op_sel_hi:[1,0]
	v_mul_f32_e32 v160, 0xbfb8aa3b, v160
	v_exp_f32_e32 v160, v160
	v_pk_mul_f32 v[156:157], v[158:159], v[156:157]
	v_pk_add_f32 v[160:161], v[160:161], 1.0 op_sel_hi:[1,0]
	v_pk_mul_f32 v[98:99], v[98:99], v[156:157]
	s_waitcnt vmcnt(29)
	v_mov_b32_e32 v156, v200
	v_mov_b32_e32 v157, v201
	s_waitcnt vmcnt(28)
	v_mov_b32_e32 v158, v202
	v_mov_b32_e32 v159, v203
	v_pk_mul_f32 v[160:161], v[160:161], v[162:163]
	s_nop 0
	v_pk_mul_f32 v[96:97], v[96:97], v[160:161]
	s_nop 0
	v_lshlrev_b32_e32 v160, 16, v156
	v_lshlrev_b32_e32 v161, 16, v158
	v_mul_f32_e32 v161, 0xbfb8aa3b, v161
	v_exp_f32_e32 v161, v161
	v_and_b32_e32 v156, 0xffff0000, v156
	v_mul_f32_e32 v156, 0xbfb8aa3b, v156
	v_mul_f32_e32 v160, 0xbfb8aa3b, v160
	v_add_f32_e32 v161, 1.0, v161
	v_rcp_f32_e32 v162, v161
	v_exp_f32_e32 v161, v156
	v_and_b32_e32 v156, 0xffff0000, v158
	v_mul_f32_e32 v156, 0xbfb8aa3b, v156
	v_exp_f32_e32 v156, v156
	v_lshlrev_b32_e32 v158, 16, v159
	v_and_b32_e32 v159, 0xffff0000, v159
	v_mul_f32_e32 v158, 0xbfb8aa3b, v158
	v_mul_f32_e32 v159, 0xbfb8aa3b, v159
	v_exp_f32_e32 v158, v158
	v_exp_f32_e32 v159, v159
	v_add_f32_e32 v156, 1.0, v156
	v_rcp_f32_e32 v163, v156
	v_lshlrev_b32_e32 v156, 16, v157
	v_and_b32_e32 v157, 0xffff0000, v157
	v_mul_f32_e32 v156, 0xbfb8aa3b, v156
	v_mul_f32_e32 v157, 0xbfb8aa3b, v157
	v_exp_f32_e32 v156, v156
	v_add_f32_e32 v158, 1.0, v158
	v_exp_f32_e32 v157, v157
	v_add_f32_e32 v159, 1.0, v159
	v_rcp_f32_e32 v158, v158
	v_rcp_f32_e32 v159, v159
	v_pk_add_f32 v[156:157], v[156:157], 1.0 op_sel_hi:[1,0]
	v_exp_f32_e32 v160, v160
	v_pk_mul_f32 v[156:157], v[156:157], v[158:159]
	s_nop 0
	v_pk_mul_f32 v[94:95], v[94:95], v[156:157]
	s_waitcnt vmcnt(27)
	v_mov_b32_e32 v156, v204
	v_mov_b32_e32 v157, v205
	s_waitcnt vmcnt(26)
	v_mov_b32_e32 v158, v206
	v_mov_b32_e32 v159, v207
	s_nop 0
	s_waitcnt vmcnt(25)
	v_mov_b32_e32 v148, v208
	v_mov_b32_e32 v149, v209
	s_nop 0
	s_waitcnt vmcnt(24)
	v_mov_b32_e32 v146, v218
	v_mov_b32_e32 v147, v219
	v_add_u32_e32 v244, 0xa0, v0
	v_mad_i64_i32 v[244:245], s[2:3], v244, s78, v[2:3]
	v_lshl_add_u64 v[244:245], v[244:245], 0, s[10:11]
	v_lshl_add_u64 v[244:245], v[244:245], 0, v[144:145]
	v_add_co_u32_e32 v246, vcc, s89, v244
	s_nop 1
	v_addc_co_u32_e32 v247, vcc, 0, v245, vcc
	global_load_dwordx2 v[196:197], v[244:245], off
	global_load_dwordx2 v[198:199], v[246:247], off
	global_load_dwordx2 v[200:201], v[246:247], off offset:32
	global_load_dwordx2 v[202:203], v[244:245], off offset:32
	global_load_dwordx2 v[204:205], v[244:245], off offset:256
	global_load_dwordx2 v[206:207], v[246:247], off offset:256
	global_load_dwordx2 v[208:209], v[246:247], off offset:288
	global_load_dwordx2 v[218:219], v[244:245], off offset:288
	v_pk_add_f32 v[160:161], v[160:161], 1.0 op_sel_hi:[1,0]
	s_nop 0
	v_pk_mul_f32 v[160:161], v[160:161], v[162:163]
	s_nop 0
	v_pk_mul_f32 v[92:93], v[92:93], v[160:161]
	s_nop 0
	v_lshlrev_b32_e32 v161, 16, v156
	v_and_b32_e32 v156, 0xffff0000, v156
	v_mul_f32_e32 v156, 0xbfb8aa3b, v156
	v_exp_f32_e32 v156, v156
	v_mul_f32_e32 v161, 0xbfb8aa3b, v161
	v_exp_f32_e32 v161, v161
	v_lshlrev_b32_e32 v160, 16, v158
	v_add_f32_e32 v156, 1.0, v156
	v_and_b32_e32 v158, 0xffff0000, v158
	v_rcp_f32_e32 v163, v156
	v_lshlrev_b32_e32 v156, 16, v159
	v_add_f32_e32 v161, 1.0, v161
	v_mul_f32_e32 v158, 0xbfb8aa3b, v158
	v_mul_f32_e32 v156, 0xbfb8aa3b, v156
	v_rcp_f32_e32 v162, v161
	v_exp_f32_e32 v161, v158
	v_exp_f32_e32 v158, v156
	v_lshlrev_b32_e32 v156, 16, v157
	v_and_b32_e32 v157, 0xffff0000, v157
	v_mul_f32_e32 v156, 0xbfb8aa3b, v156
	v_mul_f32_e32 v157, 0xbfb8aa3b, v157
	v_exp_f32_e32 v156, v156
	v_exp_f32_e32 v157, v157
	v_and_b32_e32 v159, 0xffff0000, v159
	v_mul_f32_e32 v159, 0xbfb8aa3b, v159
	v_add_f32_e32 v156, 1.0, v156
	v_exp_f32_e32 v159, v159
	v_add_f32_e32 v157, 1.0, v157
	v_rcp_f32_e32 v156, v156
	v_rcp_f32_e32 v157, v157
	v_pk_add_f32 v[158:159], v[158:159], 1.0 op_sel_hi:[1,0]
	v_mul_f32_e32 v160, 0xbfb8aa3b, v160
	v_exp_f32_e32 v160, v160
	v_pk_mul_f32 v[156:157], v[158:159], v[156:157]
	v_pk_add_f32 v[160:161], v[160:161], 1.0 op_sel_hi:[1,0]
	v_pk_mul_f32 v[90:91], v[90:91], v[156:157]
	v_lshlrev_b32_e32 v157, 16, v146
	v_and_b32_e32 v146, 0xffff0000, v146
	v_mul_f32_e32 v146, 0xbfb8aa3b, v146
	v_exp_f32_e32 v146, v146
	v_mul_f32_e32 v157, 0xbfb8aa3b, v157
	v_exp_f32_e32 v157, v157
	v_lshlrev_b32_e32 v156, 16, v148
	v_add_f32_e32 v146, 1.0, v146
	v_and_b32_e32 v148, 0xffff0000, v148
	v_rcp_f32_e32 v159, v146
	v_lshlrev_b32_e32 v146, 16, v149
	v_add_f32_e32 v157, 1.0, v157
	v_mul_f32_e32 v148, 0xbfb8aa3b, v148
	v_mul_f32_e32 v146, 0xbfb8aa3b, v146
	v_rcp_f32_e32 v158, v157
	v_exp_f32_e32 v157, v148
	v_exp_f32_e32 v148, v146
	v_lshlrev_b32_e32 v146, 16, v147
	v_and_b32_e32 v147, 0xffff0000, v147
	v_mul_f32_e32 v146, 0xbfb8aa3b, v146
	v_mul_f32_e32 v147, 0xbfb8aa3b, v147
	v_exp_f32_e32 v146, v146
	v_exp_f32_e32 v147, v147
	v_and_b32_e32 v149, 0xffff0000, v149
	v_mul_f32_e32 v149, 0xbfb8aa3b, v149
	v_add_f32_e32 v146, 1.0, v146
	v_exp_f32_e32 v149, v149
	v_add_f32_e32 v147, 1.0, v147
	v_rcp_f32_e32 v146, v146
	v_rcp_f32_e32 v147, v147
	v_mul_f32_e32 v156, 0xbfb8aa3b, v156
	v_exp_f32_e32 v156, v156
	v_pk_add_f32 v[148:149], v[148:149], 1.0 op_sel_hi:[1,0]
	v_pk_mul_f32 v[160:161], v[160:161], v[162:163]
	v_pk_mul_f32 v[146:147], v[148:149], v[146:147]
	v_pk_add_f32 v[156:157], v[156:157], 1.0 op_sel_hi:[1,0]
	v_pk_mul_f32 v[86:87], v[86:87], v[146:147]
	v_add_u32_e32 v146, 48, v0
	v_mad_i64_i32 v[146:147], s[2:3], v146, s78, v[2:3]
	v_lshl_add_u64 v[146:147], v[146:147], 0, s[10:11]
	v_pk_mul_f32 v[156:157], v[156:157], v[158:159]
	v_lshl_add_u64 v[146:147], v[146:147], 0, v[144:145]
	v_pk_mul_f32 v[84:85], v[84:85], v[156:157]
	s_waitcnt vmcnt(31)
	v_mov_b32_e32 v156, v220
	v_mov_b32_e32 v157, v221
	v_add_co_u32_e32 v148, vcc, s89, v146
	v_pk_mul_f32 v[88:89], v[88:89], v[160:161]
	s_nop 0
	v_addc_co_u32_e32 v149, vcc, 0, v147, vcc
	s_waitcnt vmcnt(30)
	v_mov_b32_e32 v158, v222
	v_mov_b32_e32 v159, v223
	s_nop 0
	v_lshlrev_b32_e32 v161, 16, v156
	v_and_b32_e32 v156, 0xffff0000, v156
	v_mul_f32_e32 v156, 0xbfb8aa3b, v156
	v_exp_f32_e32 v156, v156
	v_mul_f32_e32 v161, 0xbfb8aa3b, v161
	v_exp_f32_e32 v161, v161
	v_lshlrev_b32_e32 v160, 16, v158
	v_add_f32_e32 v156, 1.0, v156
	v_and_b32_e32 v158, 0xffff0000, v158
	v_rcp_f32_e32 v163, v156
	v_lshlrev_b32_e32 v156, 16, v159
	v_add_f32_e32 v161, 1.0, v161
	v_mul_f32_e32 v158, 0xbfb8aa3b, v158
	v_mul_f32_e32 v156, 0xbfb8aa3b, v156
	v_rcp_f32_e32 v162, v161
	v_exp_f32_e32 v161, v158
	v_exp_f32_e32 v158, v156
	v_lshlrev_b32_e32 v156, 16, v157
	v_and_b32_e32 v157, 0xffff0000, v157
	v_mul_f32_e32 v156, 0xbfb8aa3b, v156
	v_mul_f32_e32 v157, 0xbfb8aa3b, v157
	v_exp_f32_e32 v156, v156
	v_exp_f32_e32 v157, v157
	v_and_b32_e32 v159, 0xffff0000, v159
	v_mul_f32_e32 v159, 0xbfb8aa3b, v159
	v_add_f32_e32 v156, 1.0, v156
	v_exp_f32_e32 v159, v159
	v_add_f32_e32 v157, 1.0, v157
	v_rcp_f32_e32 v156, v156
	v_rcp_f32_e32 v157, v157
	v_pk_add_f32 v[158:159], v[158:159], 1.0 op_sel_hi:[1,0]
	v_mul_f32_e32 v160, 0xbfb8aa3b, v160
	v_exp_f32_e32 v160, v160
	v_pk_mul_f32 v[156:157], v[158:159], v[156:157]
	v_pk_add_f32 v[160:161], v[160:161], 1.0 op_sel_hi:[1,0]
	v_pk_mul_f32 v[82:83], v[82:83], v[156:157]
	s_waitcnt vmcnt(29)
	v_mov_b32_e32 v156, v224
	v_mov_b32_e32 v157, v225
	s_waitcnt vmcnt(28)
	v_mov_b32_e32 v158, v232
	v_mov_b32_e32 v159, v233
	v_pk_mul_f32 v[160:161], v[160:161], v[162:163]
	s_nop 0
	v_pk_mul_f32 v[80:81], v[80:81], v[160:161]
	s_nop 0
	v_lshlrev_b32_e32 v160, 16, v156
	v_lshlrev_b32_e32 v161, 16, v158
	v_mul_f32_e32 v161, 0xbfb8aa3b, v161
	v_exp_f32_e32 v161, v161
	v_and_b32_e32 v156, 0xffff0000, v156
	v_mul_f32_e32 v156, 0xbfb8aa3b, v156
	v_mul_f32_e32 v160, 0xbfb8aa3b, v160
	v_add_f32_e32 v161, 1.0, v161
	v_rcp_f32_e32 v162, v161
	v_exp_f32_e32 v161, v156
	v_and_b32_e32 v156, 0xffff0000, v158
	v_mul_f32_e32 v156, 0xbfb8aa3b, v156
	v_exp_f32_e32 v156, v156
	v_lshlrev_b32_e32 v158, 16, v159
	v_and_b32_e32 v159, 0xffff0000, v159
	v_mul_f32_e32 v158, 0xbfb8aa3b, v158
	v_mul_f32_e32 v159, 0xbfb8aa3b, v159
	v_exp_f32_e32 v158, v158
	v_exp_f32_e32 v159, v159
	v_add_f32_e32 v156, 1.0, v156
	v_rcp_f32_e32 v163, v156
	v_lshlrev_b32_e32 v156, 16, v157
	v_and_b32_e32 v157, 0xffff0000, v157
	v_mul_f32_e32 v156, 0xbfb8aa3b, v156
	v_mul_f32_e32 v157, 0xbfb8aa3b, v157
	v_exp_f32_e32 v156, v156
	v_add_f32_e32 v158, 1.0, v158
	v_exp_f32_e32 v157, v157
	v_add_f32_e32 v159, 1.0, v159
	v_rcp_f32_e32 v158, v158
	v_rcp_f32_e32 v159, v159
	v_pk_add_f32 v[156:157], v[156:157], 1.0 op_sel_hi:[1,0]
	v_exp_f32_e32 v160, v160
	v_pk_mul_f32 v[156:157], v[156:157], v[158:159]
	s_nop 0
	v_pk_mul_f32 v[78:79], v[78:79], v[156:157]
	s_waitcnt vmcnt(27)
	v_mov_b32_e32 v156, v234
	v_mov_b32_e32 v157, v235
	s_waitcnt vmcnt(26)
	v_mov_b32_e32 v158, v236
	v_mov_b32_e32 v159, v237
	s_nop 0
	s_waitcnt vmcnt(25)
	v_mov_b32_e32 v148, v238
	v_mov_b32_e32 v149, v239
	s_nop 0
	s_waitcnt vmcnt(24)
	v_mov_b32_e32 v146, v240
	v_mov_b32_e32 v147, v241
	v_add_u32_e32 v244, 0xb0, v0
	v_mad_i64_i32 v[244:245], s[2:3], v244, s78, v[2:3]
	v_lshl_add_u64 v[244:245], v[244:245], 0, s[10:11]
	v_lshl_add_u64 v[244:245], v[244:245], 0, v[144:145]
	v_add_co_u32_e32 v246, vcc, s89, v244
	s_nop 1
	v_addc_co_u32_e32 v247, vcc, 0, v245, vcc
	global_load_dwordx2 v[220:221], v[246:247], off
	global_load_dwordx2 v[222:223], v[244:245], off
	global_load_dwordx2 v[224:225], v[246:247], off offset:32
	global_load_dwordx2 v[232:233], v[244:245], off offset:32
	global_load_dwordx2 v[234:235], v[244:245], off offset:256
	global_load_dwordx2 v[236:237], v[246:247], off offset:256
	global_load_dwordx2 v[238:239], v[246:247], off offset:288
	global_load_dwordx2 v[240:241], v[244:245], off offset:288
	v_pk_add_f32 v[160:161], v[160:161], 1.0 op_sel_hi:[1,0]
	s_nop 0
	v_pk_mul_f32 v[160:161], v[160:161], v[162:163]
	s_nop 0
	v_pk_mul_f32 v[76:77], v[76:77], v[160:161]
	s_nop 0
	v_lshlrev_b32_e32 v161, 16, v156
	v_and_b32_e32 v156, 0xffff0000, v156
	v_mul_f32_e32 v156, 0xbfb8aa3b, v156
	v_exp_f32_e32 v156, v156
	v_mul_f32_e32 v161, 0xbfb8aa3b, v161
	v_exp_f32_e32 v161, v161
	v_lshlrev_b32_e32 v160, 16, v158
	v_add_f32_e32 v156, 1.0, v156
	v_and_b32_e32 v158, 0xffff0000, v158
	v_rcp_f32_e32 v163, v156
	v_lshlrev_b32_e32 v156, 16, v159
	v_add_f32_e32 v161, 1.0, v161
	v_mul_f32_e32 v158, 0xbfb8aa3b, v158
	v_mul_f32_e32 v156, 0xbfb8aa3b, v156
	v_rcp_f32_e32 v162, v161
	v_exp_f32_e32 v161, v158
	v_exp_f32_e32 v158, v156
	v_lshlrev_b32_e32 v156, 16, v157
	v_and_b32_e32 v157, 0xffff0000, v157
	v_mul_f32_e32 v156, 0xbfb8aa3b, v156
	v_mul_f32_e32 v157, 0xbfb8aa3b, v157
	v_exp_f32_e32 v156, v156
	v_exp_f32_e32 v157, v157
	v_and_b32_e32 v159, 0xffff0000, v159
	v_mul_f32_e32 v159, 0xbfb8aa3b, v159
	v_add_f32_e32 v156, 1.0, v156
	v_exp_f32_e32 v159, v159
	v_add_f32_e32 v157, 1.0, v157
	v_rcp_f32_e32 v156, v156
	v_rcp_f32_e32 v157, v157
	v_pk_add_f32 v[158:159], v[158:159], 1.0 op_sel_hi:[1,0]
	v_mul_f32_e32 v160, 0xbfb8aa3b, v160
	v_exp_f32_e32 v160, v160
	v_pk_mul_f32 v[156:157], v[158:159], v[156:157]
	v_pk_add_f32 v[160:161], v[160:161], 1.0 op_sel_hi:[1,0]
	v_pk_mul_f32 v[74:75], v[74:75], v[156:157]
	v_lshlrev_b32_e32 v157, 16, v146
	v_and_b32_e32 v146, 0xffff0000, v146
	v_mul_f32_e32 v146, 0xbfb8aa3b, v146
	v_exp_f32_e32 v146, v146
	v_mul_f32_e32 v157, 0xbfb8aa3b, v157
	v_exp_f32_e32 v157, v157
	v_lshlrev_b32_e32 v156, 16, v148
	v_add_f32_e32 v146, 1.0, v146
	v_and_b32_e32 v148, 0xffff0000, v148
	v_rcp_f32_e32 v159, v146
	v_lshlrev_b32_e32 v146, 16, v149
	v_add_f32_e32 v157, 1.0, v157
	v_mul_f32_e32 v148, 0xbfb8aa3b, v148
	v_mul_f32_e32 v146, 0xbfb8aa3b, v146
	v_rcp_f32_e32 v158, v157
	v_exp_f32_e32 v157, v148
	v_exp_f32_e32 v148, v146
	v_lshlrev_b32_e32 v146, 16, v147
	v_and_b32_e32 v147, 0xffff0000, v147
	v_mul_f32_e32 v146, 0xbfb8aa3b, v146
	v_mul_f32_e32 v147, 0xbfb8aa3b, v147
	v_exp_f32_e32 v146, v146
	v_exp_f32_e32 v147, v147
	v_and_b32_e32 v149, 0xffff0000, v149
	v_mul_f32_e32 v149, 0xbfb8aa3b, v149
	v_add_f32_e32 v146, 1.0, v146
	v_exp_f32_e32 v149, v149
	v_add_f32_e32 v147, 1.0, v147
	v_rcp_f32_e32 v146, v146
	v_rcp_f32_e32 v147, v147
	v_mul_f32_e32 v156, 0xbfb8aa3b, v156
	v_exp_f32_e32 v156, v156
	v_pk_add_f32 v[148:149], v[148:149], 1.0 op_sel_hi:[1,0]
	v_pk_mul_f32 v[160:161], v[160:161], v[162:163]
	v_pk_mul_f32 v[146:147], v[148:149], v[146:147]
	v_pk_add_f32 v[156:157], v[156:157], 1.0 op_sel_hi:[1,0]
	v_pk_mul_f32 v[70:71], v[70:71], v[146:147]
	v_add_u32_e32 v146, 0x80, v0
	v_mad_i64_i32 v[146:147], s[2:3], v146, s78, v[2:3]
	v_lshl_add_u64 v[146:147], v[146:147], 0, s[10:11]
	v_pk_mul_f32 v[156:157], v[156:157], v[158:159]
	v_lshl_add_u64 v[146:147], v[146:147], 0, v[144:145]
	v_pk_mul_f32 v[68:69], v[68:69], v[156:157]
	s_waitcnt vmcnt(31)
	v_mov_b32_e32 v156, v164
	v_mov_b32_e32 v157, v165
	v_add_co_u32_e32 v148, vcc, s89, v146
	v_pk_mul_f32 v[72:73], v[72:73], v[160:161]
	s_nop 0
	v_addc_co_u32_e32 v149, vcc, 0, v147, vcc
	s_waitcnt vmcnt(30)
	v_mov_b32_e32 v158, v166
	v_mov_b32_e32 v159, v167
	s_nop 0
	v_lshlrev_b32_e32 v161, 16, v156
	v_and_b32_e32 v156, 0xffff0000, v156
	v_mul_f32_e32 v156, 0xbfb8aa3b, v156
	v_exp_f32_e32 v156, v156
	v_mul_f32_e32 v161, 0xbfb8aa3b, v161
	v_exp_f32_e32 v161, v161
	v_lshlrev_b32_e32 v160, 16, v158
	v_add_f32_e32 v156, 1.0, v156
	v_and_b32_e32 v158, 0xffff0000, v158
	v_rcp_f32_e32 v163, v156
	v_lshlrev_b32_e32 v156, 16, v159
	v_add_f32_e32 v161, 1.0, v161
	v_mul_f32_e32 v158, 0xbfb8aa3b, v158
	v_mul_f32_e32 v156, 0xbfb8aa3b, v156
	v_rcp_f32_e32 v162, v161
	v_exp_f32_e32 v161, v158
	v_exp_f32_e32 v158, v156
	v_lshlrev_b32_e32 v156, 16, v157
	v_and_b32_e32 v157, 0xffff0000, v157
	v_mul_f32_e32 v156, 0xbfb8aa3b, v156
	v_mul_f32_e32 v157, 0xbfb8aa3b, v157
	v_exp_f32_e32 v156, v156
	v_exp_f32_e32 v157, v157
	v_and_b32_e32 v159, 0xffff0000, v159
	v_mul_f32_e32 v159, 0xbfb8aa3b, v159
	v_add_f32_e32 v156, 1.0, v156
	v_exp_f32_e32 v159, v159
	v_add_f32_e32 v157, 1.0, v157
	v_rcp_f32_e32 v156, v156
	v_rcp_f32_e32 v157, v157
	v_pk_add_f32 v[158:159], v[158:159], 1.0 op_sel_hi:[1,0]
	v_mul_f32_e32 v160, 0xbfb8aa3b, v160
	v_exp_f32_e32 v160, v160
	v_pk_mul_f32 v[156:157], v[158:159], v[156:157]
	v_pk_add_f32 v[160:161], v[160:161], 1.0 op_sel_hi:[1,0]
	v_pk_mul_f32 v[66:67], v[66:67], v[156:157]
	s_waitcnt vmcnt(29)
	v_mov_b32_e32 v156, v168
	v_mov_b32_e32 v157, v169
	s_waitcnt vmcnt(28)
	v_mov_b32_e32 v158, v170
	v_mov_b32_e32 v159, v171
	v_pk_mul_f32 v[160:161], v[160:161], v[162:163]
	s_nop 0
	v_pk_mul_f32 v[64:65], v[64:65], v[160:161]
	s_nop 0
	v_lshlrev_b32_e32 v160, 16, v156
	v_lshlrev_b32_e32 v161, 16, v158
	v_mul_f32_e32 v161, 0xbfb8aa3b, v161
	v_exp_f32_e32 v161, v161
	v_and_b32_e32 v156, 0xffff0000, v156
	v_mul_f32_e32 v156, 0xbfb8aa3b, v156
	v_mul_f32_e32 v160, 0xbfb8aa3b, v160
	v_add_f32_e32 v161, 1.0, v161
	v_rcp_f32_e32 v162, v161
	v_exp_f32_e32 v161, v156
	v_and_b32_e32 v156, 0xffff0000, v158
	v_mul_f32_e32 v156, 0xbfb8aa3b, v156
	v_exp_f32_e32 v156, v156
	v_lshlrev_b32_e32 v158, 16, v159
	v_and_b32_e32 v159, 0xffff0000, v159
	v_mul_f32_e32 v158, 0xbfb8aa3b, v158
	v_mul_f32_e32 v159, 0xbfb8aa3b, v159
	v_exp_f32_e32 v158, v158
	v_exp_f32_e32 v159, v159
	v_add_f32_e32 v156, 1.0, v156
	v_rcp_f32_e32 v163, v156
	v_lshlrev_b32_e32 v156, 16, v157
	v_and_b32_e32 v157, 0xffff0000, v157
	v_mul_f32_e32 v156, 0xbfb8aa3b, v156
	v_mul_f32_e32 v157, 0xbfb8aa3b, v157
	v_exp_f32_e32 v156, v156
	v_add_f32_e32 v158, 1.0, v158
	v_exp_f32_e32 v157, v157
	v_add_f32_e32 v159, 1.0, v159
	v_rcp_f32_e32 v158, v158
	v_rcp_f32_e32 v159, v159
	v_pk_add_f32 v[156:157], v[156:157], 1.0 op_sel_hi:[1,0]
	v_exp_f32_e32 v160, v160
	v_pk_mul_f32 v[156:157], v[156:157], v[158:159]
	s_nop 0
	v_pk_mul_f32 v[62:63], v[62:63], v[156:157]
	s_waitcnt vmcnt(27)
	v_mov_b32_e32 v156, v172
	v_mov_b32_e32 v157, v173
	s_waitcnt vmcnt(26)
	v_mov_b32_e32 v158, v174
	v_mov_b32_e32 v159, v175
	s_nop 0
	s_waitcnt vmcnt(25)
	v_mov_b32_e32 v148, v176
	v_mov_b32_e32 v149, v177
	s_nop 0
	s_waitcnt vmcnt(24)
	v_mov_b32_e32 v146, v178
	v_mov_b32_e32 v147, v179
	v_pk_add_f32 v[160:161], v[160:161], 1.0 op_sel_hi:[1,0]
	s_nop 0
	v_pk_mul_f32 v[160:161], v[160:161], v[162:163]
	s_nop 0
	v_pk_mul_f32 v[60:61], v[60:61], v[160:161]
	s_nop 0
	v_lshlrev_b32_e32 v161, 16, v156
	v_and_b32_e32 v156, 0xffff0000, v156
	v_mul_f32_e32 v156, 0xbfb8aa3b, v156
	v_exp_f32_e32 v156, v156
	v_mul_f32_e32 v161, 0xbfb8aa3b, v161
	v_exp_f32_e32 v161, v161
	v_lshlrev_b32_e32 v160, 16, v158
	v_add_f32_e32 v156, 1.0, v156
	v_and_b32_e32 v158, 0xffff0000, v158
	v_rcp_f32_e32 v163, v156
	v_lshlrev_b32_e32 v156, 16, v159
	v_add_f32_e32 v161, 1.0, v161
	v_mul_f32_e32 v158, 0xbfb8aa3b, v158
	v_mul_f32_e32 v156, 0xbfb8aa3b, v156
	v_rcp_f32_e32 v162, v161
	v_exp_f32_e32 v161, v158
	v_exp_f32_e32 v158, v156
	v_lshlrev_b32_e32 v156, 16, v157
	v_and_b32_e32 v157, 0xffff0000, v157
	v_mul_f32_e32 v156, 0xbfb8aa3b, v156
	v_mul_f32_e32 v157, 0xbfb8aa3b, v157
	v_exp_f32_e32 v156, v156
	v_exp_f32_e32 v157, v157
	v_and_b32_e32 v159, 0xffff0000, v159
	v_mul_f32_e32 v159, 0xbfb8aa3b, v159
	v_add_f32_e32 v156, 1.0, v156
	v_exp_f32_e32 v159, v159
	v_add_f32_e32 v157, 1.0, v157
	v_rcp_f32_e32 v156, v156
	v_rcp_f32_e32 v157, v157
	v_pk_add_f32 v[158:159], v[158:159], 1.0 op_sel_hi:[1,0]
	v_mul_f32_e32 v160, 0xbfb8aa3b, v160
	v_exp_f32_e32 v160, v160
	v_pk_mul_f32 v[156:157], v[158:159], v[156:157]
	v_pk_add_f32 v[160:161], v[160:161], 1.0 op_sel_hi:[1,0]
	v_pk_mul_f32 v[58:59], v[58:59], v[156:157]
	v_lshlrev_b32_e32 v157, 16, v146
	v_and_b32_e32 v146, 0xffff0000, v146
	v_mul_f32_e32 v146, 0xbfb8aa3b, v146
	v_exp_f32_e32 v146, v146
	v_mul_f32_e32 v157, 0xbfb8aa3b, v157
	v_exp_f32_e32 v157, v157
	v_lshlrev_b32_e32 v156, 16, v148
	v_add_f32_e32 v146, 1.0, v146
	v_and_b32_e32 v148, 0xffff0000, v148
	v_rcp_f32_e32 v159, v146
	v_lshlrev_b32_e32 v146, 16, v149
	v_add_f32_e32 v157, 1.0, v157
	v_mul_f32_e32 v148, 0xbfb8aa3b, v148
	v_mul_f32_e32 v146, 0xbfb8aa3b, v146
	v_rcp_f32_e32 v158, v157
	v_exp_f32_e32 v157, v148
	v_exp_f32_e32 v148, v146
	v_lshlrev_b32_e32 v146, 16, v147
	v_and_b32_e32 v147, 0xffff0000, v147
	v_mul_f32_e32 v146, 0xbfb8aa3b, v146
	v_mul_f32_e32 v147, 0xbfb8aa3b, v147
	v_exp_f32_e32 v146, v146
	v_exp_f32_e32 v147, v147
	v_and_b32_e32 v149, 0xffff0000, v149
	v_mul_f32_e32 v149, 0xbfb8aa3b, v149
	v_add_f32_e32 v146, 1.0, v146
	v_exp_f32_e32 v149, v149
	v_add_f32_e32 v147, 1.0, v147
	v_rcp_f32_e32 v146, v146
	v_rcp_f32_e32 v147, v147
	v_mul_f32_e32 v156, 0xbfb8aa3b, v156
	v_exp_f32_e32 v156, v156
	v_pk_add_f32 v[148:149], v[148:149], 1.0 op_sel_hi:[1,0]
	v_pk_mul_f32 v[160:161], v[160:161], v[162:163]
	v_pk_mul_f32 v[146:147], v[148:149], v[146:147]
	v_pk_add_f32 v[156:157], v[156:157], 1.0 op_sel_hi:[1,0]
	v_pk_mul_f32 v[54:55], v[54:55], v[146:147]
	v_add_u32_e32 v146, 0x90, v0
	v_mad_i64_i32 v[146:147], s[2:3], v146, s78, v[2:3]
	v_lshl_add_u64 v[146:147], v[146:147], 0, s[10:11]
	v_pk_mul_f32 v[156:157], v[156:157], v[158:159]
	v_lshl_add_u64 v[146:147], v[146:147], 0, v[144:145]
	v_pk_mul_f32 v[52:53], v[52:53], v[156:157]
	s_waitcnt vmcnt(23)
	v_mov_b32_e32 v156, v180
	v_mov_b32_e32 v157, v181
	v_add_co_u32_e32 v148, vcc, s89, v146
	v_pk_mul_f32 v[56:57], v[56:57], v[160:161]
	s_nop 0
	v_addc_co_u32_e32 v149, vcc, 0, v147, vcc
	s_waitcnt vmcnt(22)
	v_mov_b32_e32 v158, v182
	v_mov_b32_e32 v159, v183
	s_nop 0
	v_lshlrev_b32_e32 v161, 16, v156
	v_and_b32_e32 v156, 0xffff0000, v156
	v_mul_f32_e32 v156, 0xbfb8aa3b, v156
	v_exp_f32_e32 v156, v156
	v_mul_f32_e32 v161, 0xbfb8aa3b, v161
	v_exp_f32_e32 v161, v161
	v_lshlrev_b32_e32 v160, 16, v158
	v_add_f32_e32 v156, 1.0, v156
	v_and_b32_e32 v158, 0xffff0000, v158
	v_rcp_f32_e32 v163, v156
	v_lshlrev_b32_e32 v156, 16, v159
	v_add_f32_e32 v161, 1.0, v161
	v_mul_f32_e32 v158, 0xbfb8aa3b, v158
	v_mul_f32_e32 v156, 0xbfb8aa3b, v156
	v_rcp_f32_e32 v162, v161
	v_exp_f32_e32 v161, v158
	v_exp_f32_e32 v158, v156
	v_lshlrev_b32_e32 v156, 16, v157
	v_and_b32_e32 v157, 0xffff0000, v157
	v_mul_f32_e32 v156, 0xbfb8aa3b, v156
	v_mul_f32_e32 v157, 0xbfb8aa3b, v157
	v_exp_f32_e32 v156, v156
	v_exp_f32_e32 v157, v157
	v_and_b32_e32 v159, 0xffff0000, v159
	v_mul_f32_e32 v159, 0xbfb8aa3b, v159
	v_add_f32_e32 v156, 1.0, v156
	v_exp_f32_e32 v159, v159
	v_add_f32_e32 v157, 1.0, v157
	v_rcp_f32_e32 v156, v156
	v_rcp_f32_e32 v157, v157
	v_pk_add_f32 v[158:159], v[158:159], 1.0 op_sel_hi:[1,0]
	v_mul_f32_e32 v160, 0xbfb8aa3b, v160
	v_exp_f32_e32 v160, v160
	v_pk_mul_f32 v[156:157], v[158:159], v[156:157]
	v_pk_add_f32 v[160:161], v[160:161], 1.0 op_sel_hi:[1,0]
	v_pk_mul_f32 v[50:51], v[50:51], v[156:157]
	s_waitcnt vmcnt(21)
	v_mov_b32_e32 v156, v184
	v_mov_b32_e32 v157, v185
	s_waitcnt vmcnt(20)
	v_mov_b32_e32 v158, v186
	v_mov_b32_e32 v159, v187
	v_pk_mul_f32 v[160:161], v[160:161], v[162:163]
	s_nop 0
	v_pk_mul_f32 v[48:49], v[48:49], v[160:161]
	s_nop 0
	v_lshlrev_b32_e32 v160, 16, v156
	v_lshlrev_b32_e32 v161, 16, v158
	v_mul_f32_e32 v161, 0xbfb8aa3b, v161
	v_exp_f32_e32 v161, v161
	v_and_b32_e32 v156, 0xffff0000, v156
	v_mul_f32_e32 v156, 0xbfb8aa3b, v156
	v_mul_f32_e32 v160, 0xbfb8aa3b, v160
	v_add_f32_e32 v161, 1.0, v161
	v_rcp_f32_e32 v162, v161
	v_exp_f32_e32 v161, v156
	v_and_b32_e32 v156, 0xffff0000, v158
	v_mul_f32_e32 v156, 0xbfb8aa3b, v156
	v_exp_f32_e32 v156, v156
	v_lshlrev_b32_e32 v158, 16, v159
	v_and_b32_e32 v159, 0xffff0000, v159
	v_mul_f32_e32 v158, 0xbfb8aa3b, v158
	v_mul_f32_e32 v159, 0xbfb8aa3b, v159
	v_exp_f32_e32 v158, v158
	v_exp_f32_e32 v159, v159
	v_add_f32_e32 v156, 1.0, v156
	v_rcp_f32_e32 v163, v156
	v_lshlrev_b32_e32 v156, 16, v157
	v_and_b32_e32 v157, 0xffff0000, v157
	v_mul_f32_e32 v156, 0xbfb8aa3b, v156
	v_mul_f32_e32 v157, 0xbfb8aa3b, v157
	v_exp_f32_e32 v156, v156
	v_add_f32_e32 v158, 1.0, v158
	v_exp_f32_e32 v157, v157
	v_add_f32_e32 v159, 1.0, v159
	v_rcp_f32_e32 v158, v158
	v_rcp_f32_e32 v159, v159
	v_pk_add_f32 v[156:157], v[156:157], 1.0 op_sel_hi:[1,0]
	v_exp_f32_e32 v160, v160
	v_pk_mul_f32 v[156:157], v[156:157], v[158:159]
	s_nop 0
	v_pk_mul_f32 v[46:47], v[46:47], v[156:157]
	s_waitcnt vmcnt(19)
	v_mov_b32_e32 v156, v188
	v_mov_b32_e32 v157, v189
	s_waitcnt vmcnt(18)
	v_mov_b32_e32 v158, v190
	v_mov_b32_e32 v159, v191
	s_nop 0
	s_waitcnt vmcnt(17)
	v_mov_b32_e32 v148, v192
	v_mov_b32_e32 v149, v193
	s_nop 0
	s_waitcnt vmcnt(16)
	v_mov_b32_e32 v146, v194
	v_mov_b32_e32 v147, v195
	v_pk_add_f32 v[160:161], v[160:161], 1.0 op_sel_hi:[1,0]
	s_nop 0
	v_pk_mul_f32 v[160:161], v[160:161], v[162:163]
	s_nop 0
	v_pk_mul_f32 v[44:45], v[44:45], v[160:161]
	s_nop 0
	v_lshlrev_b32_e32 v161, 16, v156
	v_and_b32_e32 v156, 0xffff0000, v156
	v_mul_f32_e32 v156, 0xbfb8aa3b, v156
	v_exp_f32_e32 v156, v156
	v_mul_f32_e32 v161, 0xbfb8aa3b, v161
	v_exp_f32_e32 v161, v161
	v_lshlrev_b32_e32 v160, 16, v158
	v_add_f32_e32 v156, 1.0, v156
	v_and_b32_e32 v158, 0xffff0000, v158
	v_rcp_f32_e32 v163, v156
	v_lshlrev_b32_e32 v156, 16, v159
	v_add_f32_e32 v161, 1.0, v161
	v_mul_f32_e32 v158, 0xbfb8aa3b, v158
	v_mul_f32_e32 v156, 0xbfb8aa3b, v156
	v_rcp_f32_e32 v162, v161
	v_exp_f32_e32 v161, v158
	v_exp_f32_e32 v158, v156
	v_lshlrev_b32_e32 v156, 16, v157
	v_and_b32_e32 v157, 0xffff0000, v157
	v_mul_f32_e32 v156, 0xbfb8aa3b, v156
	v_mul_f32_e32 v157, 0xbfb8aa3b, v157
	v_exp_f32_e32 v156, v156
	v_exp_f32_e32 v157, v157
	v_and_b32_e32 v159, 0xffff0000, v159
	v_mul_f32_e32 v159, 0xbfb8aa3b, v159
	v_add_f32_e32 v156, 1.0, v156
	v_exp_f32_e32 v159, v159
	v_add_f32_e32 v157, 1.0, v157
	v_rcp_f32_e32 v156, v156
	v_rcp_f32_e32 v157, v157
	v_pk_add_f32 v[158:159], v[158:159], 1.0 op_sel_hi:[1,0]
	v_mul_f32_e32 v160, 0xbfb8aa3b, v160
	v_exp_f32_e32 v160, v160
	v_pk_mul_f32 v[156:157], v[158:159], v[156:157]
	v_pk_add_f32 v[160:161], v[160:161], 1.0 op_sel_hi:[1,0]
	v_pk_mul_f32 v[42:43], v[42:43], v[156:157]
	v_lshlrev_b32_e32 v157, 16, v146
	v_and_b32_e32 v146, 0xffff0000, v146
	v_mul_f32_e32 v146, 0xbfb8aa3b, v146
	v_exp_f32_e32 v146, v146
	v_mul_f32_e32 v157, 0xbfb8aa3b, v157
	v_exp_f32_e32 v157, v157
	v_lshlrev_b32_e32 v156, 16, v148
	v_add_f32_e32 v146, 1.0, v146
	v_and_b32_e32 v148, 0xffff0000, v148
	v_rcp_f32_e32 v159, v146
	v_lshlrev_b32_e32 v146, 16, v149
	v_add_f32_e32 v157, 1.0, v157
	v_mul_f32_e32 v148, 0xbfb8aa3b, v148
	v_mul_f32_e32 v146, 0xbfb8aa3b, v146
	v_rcp_f32_e32 v158, v157
	v_exp_f32_e32 v157, v148
	v_exp_f32_e32 v148, v146
	v_lshlrev_b32_e32 v146, 16, v147
	v_and_b32_e32 v147, 0xffff0000, v147
	v_mul_f32_e32 v146, 0xbfb8aa3b, v146
	v_mul_f32_e32 v147, 0xbfb8aa3b, v147
	v_exp_f32_e32 v146, v146
	v_exp_f32_e32 v147, v147
	v_and_b32_e32 v149, 0xffff0000, v149
	v_mul_f32_e32 v149, 0xbfb8aa3b, v149
	v_add_f32_e32 v146, 1.0, v146
	v_exp_f32_e32 v149, v149
	v_add_f32_e32 v147, 1.0, v147
	v_rcp_f32_e32 v146, v146
	v_rcp_f32_e32 v147, v147
	v_mul_f32_e32 v156, 0xbfb8aa3b, v156
	v_exp_f32_e32 v156, v156
	v_pk_add_f32 v[148:149], v[148:149], 1.0 op_sel_hi:[1,0]
	v_pk_mul_f32 v[160:161], v[160:161], v[162:163]
	v_pk_mul_f32 v[146:147], v[148:149], v[146:147]
	v_pk_add_f32 v[156:157], v[156:157], 1.0 op_sel_hi:[1,0]
	v_pk_mul_f32 v[38:39], v[38:39], v[146:147]
	v_add_u32_e32 v146, 0xa0, v0
	v_mad_i64_i32 v[146:147], s[2:3], v146, s78, v[2:3]
	v_lshl_add_u64 v[146:147], v[146:147], 0, s[10:11]
	v_pk_mul_f32 v[156:157], v[156:157], v[158:159]
	v_lshl_add_u64 v[146:147], v[146:147], 0, v[144:145]
	v_pk_mul_f32 v[36:37], v[36:37], v[156:157]
	s_waitcnt vmcnt(15)
	v_mov_b32_e32 v156, v196
	v_mov_b32_e32 v157, v197
	v_add_co_u32_e32 v148, vcc, s89, v146
	v_pk_mul_f32 v[40:41], v[40:41], v[160:161]
	s_nop 0
	v_addc_co_u32_e32 v149, vcc, 0, v147, vcc
	s_waitcnt vmcnt(14)
	v_mov_b32_e32 v158, v198
	v_mov_b32_e32 v159, v199
	v_add_u32_e32 v0, 0xb0, v0
	v_mad_i64_i32 v[2:3], s[2:3], v0, s78, v[2:3]
	v_lshl_add_u64 v[2:3], v[2:3], 0, s[10:11]
	v_lshl_add_u64 v[2:3], v[2:3], 0, v[144:145]
	v_add_co_u32_e32 v144, vcc, s89, v2
	s_nop 0
	v_lshlrev_b32_e32 v161, 16, v156
	v_and_b32_e32 v156, 0xffff0000, v156
	v_mul_f32_e32 v156, 0xbfb8aa3b, v156
	v_exp_f32_e32 v156, v156
	v_mul_f32_e32 v161, 0xbfb8aa3b, v161
	v_exp_f32_e32 v161, v161
	v_lshlrev_b32_e32 v160, 16, v158
	v_add_f32_e32 v156, 1.0, v156
	v_and_b32_e32 v158, 0xffff0000, v158
	v_rcp_f32_e32 v163, v156
	v_lshlrev_b32_e32 v156, 16, v159
	v_add_f32_e32 v161, 1.0, v161
	v_mul_f32_e32 v158, 0xbfb8aa3b, v158
	v_mul_f32_e32 v156, 0xbfb8aa3b, v156
	v_rcp_f32_e32 v162, v161
	v_exp_f32_e32 v161, v158
	v_exp_f32_e32 v158, v156
	v_lshlrev_b32_e32 v156, 16, v157
	v_and_b32_e32 v157, 0xffff0000, v157
	v_mul_f32_e32 v156, 0xbfb8aa3b, v156
	v_mul_f32_e32 v157, 0xbfb8aa3b, v157
	v_exp_f32_e32 v156, v156
	v_exp_f32_e32 v157, v157
	v_and_b32_e32 v159, 0xffff0000, v159
	v_mul_f32_e32 v159, 0xbfb8aa3b, v159
	v_add_f32_e32 v156, 1.0, v156
	v_exp_f32_e32 v159, v159
	v_add_f32_e32 v157, 1.0, v157
	v_rcp_f32_e32 v156, v156
	v_rcp_f32_e32 v157, v157
	v_pk_add_f32 v[158:159], v[158:159], 1.0 op_sel_hi:[1,0]
	v_mul_f32_e32 v160, 0xbfb8aa3b, v160
	v_exp_f32_e32 v160, v160
	v_pk_mul_f32 v[156:157], v[158:159], v[156:157]
	v_addc_co_u32_e32 v145, vcc, 0, v3, vcc
	v_pk_mul_f32 v[34:35], v[34:35], v[156:157]
	s_waitcnt vmcnt(13)
	v_mov_b32_e32 v156, v200
	v_mov_b32_e32 v157, v201
	s_waitcnt vmcnt(12)
	v_mov_b32_e32 v158, v202
	v_mov_b32_e32 v159, v203
	v_pk_add_f32 v[160:161], v[160:161], 1.0 op_sel_hi:[1,0]
	s_nop 0
	v_pk_mul_f32 v[160:161], v[160:161], v[162:163]
	s_nop 0
	v_pk_mul_f32 v[32:33], v[32:33], v[160:161]
	s_nop 0
	v_lshlrev_b32_e32 v160, 16, v156
	v_lshlrev_b32_e32 v161, 16, v158
	v_mul_f32_e32 v161, 0xbfb8aa3b, v161
	v_exp_f32_e32 v161, v161
	v_and_b32_e32 v156, 0xffff0000, v156
	v_mul_f32_e32 v156, 0xbfb8aa3b, v156
	v_mul_f32_e32 v160, 0xbfb8aa3b, v160
	v_add_f32_e32 v161, 1.0, v161
	v_rcp_f32_e32 v162, v161
	v_exp_f32_e32 v161, v156
	v_and_b32_e32 v156, 0xffff0000, v158
	v_mul_f32_e32 v156, 0xbfb8aa3b, v156
	v_exp_f32_e32 v156, v156
	v_lshlrev_b32_e32 v158, 16, v159
	v_and_b32_e32 v159, 0xffff0000, v159
	v_mul_f32_e32 v158, 0xbfb8aa3b, v158
	v_mul_f32_e32 v159, 0xbfb8aa3b, v159
	v_exp_f32_e32 v158, v158
	v_exp_f32_e32 v159, v159
	v_add_f32_e32 v156, 1.0, v156
	v_rcp_f32_e32 v163, v156
	v_lshlrev_b32_e32 v156, 16, v157
	v_and_b32_e32 v157, 0xffff0000, v157
	v_mul_f32_e32 v156, 0xbfb8aa3b, v156
	v_mul_f32_e32 v157, 0xbfb8aa3b, v157
	v_exp_f32_e32 v156, v156
	v_add_f32_e32 v158, 1.0, v158
	v_exp_f32_e32 v157, v157
	v_add_f32_e32 v159, 1.0, v159
	v_rcp_f32_e32 v158, v158
	v_rcp_f32_e32 v159, v159
	v_pk_add_f32 v[156:157], v[156:157], 1.0 op_sel_hi:[1,0]
	v_exp_f32_e32 v160, v160
	v_pk_mul_f32 v[156:157], v[156:157], v[158:159]
	s_nop 0
	v_pk_mul_f32 v[30:31], v[30:31], v[156:157]
	s_waitcnt vmcnt(11)
	v_mov_b32_e32 v156, v204
	v_mov_b32_e32 v157, v205
	s_waitcnt vmcnt(10)
	v_mov_b32_e32 v158, v206
	v_mov_b32_e32 v159, v207
	s_nop 0
	s_waitcnt vmcnt(9)
	v_mov_b32_e32 v148, v208
	v_mov_b32_e32 v149, v209
	s_nop 0
	s_waitcnt vmcnt(8)
	v_mov_b32_e32 v146, v218
	v_mov_b32_e32 v147, v219
	v_pk_add_f32 v[160:161], v[160:161], 1.0 op_sel_hi:[1,0]
	s_nop 0
	v_pk_mul_f32 v[160:161], v[160:161], v[162:163]
	s_nop 0
	v_pk_mul_f32 v[28:29], v[28:29], v[160:161]
	s_nop 0
	v_lshlrev_b32_e32 v161, 16, v156
	v_and_b32_e32 v156, 0xffff0000, v156
	v_mul_f32_e32 v156, 0xbfb8aa3b, v156
	v_exp_f32_e32 v156, v156
	v_mul_f32_e32 v161, 0xbfb8aa3b, v161
	v_exp_f32_e32 v161, v161
	v_lshlrev_b32_e32 v160, 16, v158
	v_add_f32_e32 v156, 1.0, v156
	v_and_b32_e32 v158, 0xffff0000, v158
	v_rcp_f32_e32 v163, v156
	v_lshlrev_b32_e32 v156, 16, v159
	v_add_f32_e32 v161, 1.0, v161
	v_mul_f32_e32 v158, 0xbfb8aa3b, v158
	v_mul_f32_e32 v156, 0xbfb8aa3b, v156
	v_rcp_f32_e32 v162, v161
	v_exp_f32_e32 v161, v158
	v_exp_f32_e32 v158, v156
	v_lshlrev_b32_e32 v156, 16, v157
	v_and_b32_e32 v157, 0xffff0000, v157
	v_mul_f32_e32 v156, 0xbfb8aa3b, v156
	v_mul_f32_e32 v157, 0xbfb8aa3b, v157
	v_exp_f32_e32 v156, v156
	v_exp_f32_e32 v157, v157
	v_and_b32_e32 v159, 0xffff0000, v159
	v_mul_f32_e32 v159, 0xbfb8aa3b, v159
	v_add_f32_e32 v156, 1.0, v156
	v_exp_f32_e32 v159, v159
	v_add_f32_e32 v157, 1.0, v157
	v_rcp_f32_e32 v156, v156
	v_rcp_f32_e32 v157, v157
	v_pk_add_f32 v[158:159], v[158:159], 1.0 op_sel_hi:[1,0]
	v_mul_f32_e32 v160, 0xbfb8aa3b, v160
	v_exp_f32_e32 v160, v160
	v_pk_mul_f32 v[156:157], v[158:159], v[156:157]
	v_pk_add_f32 v[160:161], v[160:161], 1.0 op_sel_hi:[1,0]
	v_pk_mul_f32 v[26:27], v[26:27], v[156:157]
	v_lshlrev_b32_e32 v157, 16, v146
	v_and_b32_e32 v146, 0xffff0000, v146
	v_mul_f32_e32 v146, 0xbfb8aa3b, v146
	v_exp_f32_e32 v146, v146
	v_mul_f32_e32 v157, 0xbfb8aa3b, v157
	v_exp_f32_e32 v157, v157
	v_lshlrev_b32_e32 v156, 16, v148
	v_add_f32_e32 v146, 1.0, v146
	v_and_b32_e32 v148, 0xffff0000, v148
	v_rcp_f32_e32 v159, v146
	v_lshlrev_b32_e32 v146, 16, v149
	v_add_f32_e32 v157, 1.0, v157
	v_mul_f32_e32 v148, 0xbfb8aa3b, v148
	v_mul_f32_e32 v146, 0xbfb8aa3b, v146
	v_rcp_f32_e32 v158, v157
	v_exp_f32_e32 v157, v148
	v_exp_f32_e32 v148, v146
	v_lshlrev_b32_e32 v146, 16, v147
	v_and_b32_e32 v147, 0xffff0000, v147
	v_mul_f32_e32 v146, 0xbfb8aa3b, v146
	v_mul_f32_e32 v147, 0xbfb8aa3b, v147
	v_exp_f32_e32 v146, v146
	v_exp_f32_e32 v147, v147
	v_and_b32_e32 v149, 0xffff0000, v149
	v_mul_f32_e32 v149, 0xbfb8aa3b, v149
	v_add_f32_e32 v146, 1.0, v146
	v_exp_f32_e32 v149, v149
	v_add_f32_e32 v147, 1.0, v147
	v_rcp_f32_e32 v146, v146
	v_rcp_f32_e32 v147, v147
	v_pk_add_f32 v[148:149], v[148:149], 1.0 op_sel_hi:[1,0]
	v_mul_f32_e32 v156, 0xbfb8aa3b, v156
	v_exp_f32_e32 v156, v156
	v_pk_mul_f32 v[146:147], v[148:149], v[146:147]
	s_waitcnt vmcnt(7)
	v_mov_b32_e32 v148, v220
	v_mov_b32_e32 v149, v221
	v_pk_mul_f32 v[22:23], v[22:23], v[146:147]
	s_waitcnt vmcnt(6)
	v_mov_b32_e32 v146, v222
	v_mov_b32_e32 v147, v223
	v_pk_add_f32 v[156:157], v[156:157], 1.0 op_sel_hi:[1,0]
	v_pk_mul_f32 v[160:161], v[160:161], v[162:163]
	v_pk_mul_f32 v[156:157], v[156:157], v[158:159]
	v_pk_mul_f32 v[24:25], v[24:25], v[160:161]
	v_pk_mul_f32 v[20:21], v[20:21], v[156:157]
	s_nop 0
	v_lshlrev_b32_e32 v0, 16, v148
	v_mul_f32_e32 v0, 0xbfb8aa3b, v0
	v_exp_f32_e32 v156, v0
	v_lshlrev_b32_e32 v0, 16, v146
	v_mul_f32_e32 v0, 0xbfb8aa3b, v0
	v_exp_f32_e32 v0, v0
	s_nop 0
	v_add_f32_e32 v0, 1.0, v0
	v_rcp_f32_e32 v158, v0
	v_and_b32_e32 v0, 0xffff0000, v148
	v_mul_f32_e32 v0, 0xbfb8aa3b, v0
	v_exp_f32_e32 v157, v0
	v_and_b32_e32 v0, 0xffff0000, v146
	v_mul_f32_e32 v0, 0xbfb8aa3b, v0
	v_exp_f32_e32 v0, v0
	v_pk_add_f32 v[156:157], v[156:157], 1.0 op_sel_hi:[1,0]
	v_add_f32_e32 v0, 1.0, v0
	v_rcp_f32_e32 v159, v0
	v_lshlrev_b32_e32 v0, 16, v149
	v_mul_f32_e32 v0, 0xbfb8aa3b, v0
	v_exp_f32_e32 v148, v0
	v_lshlrev_b32_e32 v0, 16, v147
	v_mul_f32_e32 v0, 0xbfb8aa3b, v0
	v_exp_f32_e32 v0, v0
	v_pk_mul_f32 v[156:157], v[156:157], v[158:159]
	v_add_f32_e32 v0, 1.0, v0
	v_rcp_f32_e32 v146, v0
	v_and_b32_e32 v0, 0xffff0000, v149
	v_mul_f32_e32 v0, 0xbfb8aa3b, v0
	v_exp_f32_e32 v149, v0
	v_and_b32_e32 v0, 0xffff0000, v147
	v_mul_f32_e32 v0, 0xbfb8aa3b, v0
	v_exp_f32_e32 v0, v0
	v_pk_add_f32 v[148:149], v[148:149], 1.0 op_sel_hi:[1,0]
	v_pk_mul_f32 v[16:17], v[16:17], v[156:157]
	v_add_f32_e32 v0, 1.0, v0
	v_rcp_f32_e32 v147, v0
	s_nop 0
	v_pk_mul_f32 v[146:147], v[148:149], v[146:147]
	s_nop 0
	v_pk_mul_f32 v[18:19], v[18:19], v[146:147]
	s_waitcnt vmcnt(5)
	v_mov_b32_e32 v146, v224
	v_mov_b32_e32 v147, v225
	s_waitcnt vmcnt(4)
	v_mov_b32_e32 v148, v232
	v_mov_b32_e32 v149, v233
	s_nop 0
	v_lshlrev_b32_e32 v0, 16, v146
	v_mul_f32_e32 v0, 0xbfb8aa3b, v0
	v_exp_f32_e32 v156, v0
	v_lshlrev_b32_e32 v0, 16, v148
	v_mul_f32_e32 v0, 0xbfb8aa3b, v0
	v_exp_f32_e32 v0, v0
	s_nop 0
	v_add_f32_e32 v0, 1.0, v0
	v_rcp_f32_e32 v158, v0
	v_and_b32_e32 v0, 0xffff0000, v146
	v_mul_f32_e32 v0, 0xbfb8aa3b, v0
	v_exp_f32_e32 v157, v0
	v_and_b32_e32 v0, 0xffff0000, v148
	v_mul_f32_e32 v0, 0xbfb8aa3b, v0
	v_exp_f32_e32 v0, v0
	v_pk_add_f32 v[156:157], v[156:157], 1.0 op_sel_hi:[1,0]
	v_add_f32_e32 v0, 1.0, v0
	v_rcp_f32_e32 v159, v0
	v_lshlrev_b32_e32 v0, 16, v147
	v_mul_f32_e32 v0, 0xbfb8aa3b, v0
	v_exp_f32_e32 v146, v0
	v_lshlrev_b32_e32 v0, 16, v149
	v_mul_f32_e32 v0, 0xbfb8aa3b, v0
	v_exp_f32_e32 v0, v0
	v_pk_mul_f32 v[156:157], v[156:157], v[158:159]
	v_add_f32_e32 v0, 1.0, v0
	v_rcp_f32_e32 v148, v0
	v_and_b32_e32 v0, 0xffff0000, v147
	v_mul_f32_e32 v0, 0xbfb8aa3b, v0
	v_exp_f32_e32 v147, v0
	v_and_b32_e32 v0, 0xffff0000, v149
	v_mul_f32_e32 v0, 0xbfb8aa3b, v0
	v_exp_f32_e32 v0, v0
	v_pk_add_f32 v[146:147], v[146:147], 1.0 op_sel_hi:[1,0]
	v_pk_mul_f32 v[12:13], v[12:13], v[156:157]
	v_add_f32_e32 v0, 1.0, v0
	v_rcp_f32_e32 v149, v0
	s_nop 0
	v_pk_mul_f32 v[146:147], v[146:147], v[148:149]
	s_nop 0
	v_pk_mul_f32 v[14:15], v[14:15], v[146:147]
	s_waitcnt vmcnt(3)
	v_mov_b32_e32 v146, v234
	v_mov_b32_e32 v147, v235
	s_waitcnt vmcnt(2)
	v_mov_b32_e32 v148, v236
	v_mov_b32_e32 v149, v237
	s_nop 0
	v_lshlrev_b32_e32 v0, 16, v148
	v_mul_f32_e32 v0, 0xbfb8aa3b, v0
	v_exp_f32_e32 v156, v0
	v_lshlrev_b32_e32 v0, 16, v146
	v_mul_f32_e32 v0, 0xbfb8aa3b, v0
	v_exp_f32_e32 v0, v0
	s_nop 0
	v_add_f32_e32 v0, 1.0, v0
	v_rcp_f32_e32 v158, v0
	v_and_b32_e32 v0, 0xffff0000, v148
	v_mul_f32_e32 v0, 0xbfb8aa3b, v0
	v_exp_f32_e32 v157, v0
	v_and_b32_e32 v0, 0xffff0000, v146
	v_mul_f32_e32 v0, 0xbfb8aa3b, v0
	v_exp_f32_e32 v0, v0
	v_pk_add_f32 v[156:157], v[156:157], 1.0 op_sel_hi:[1,0]
	v_add_f32_e32 v0, 1.0, v0
	v_rcp_f32_e32 v159, v0
	v_lshlrev_b32_e32 v0, 16, v149
	v_mul_f32_e32 v0, 0xbfb8aa3b, v0
	v_exp_f32_e32 v148, v0
	v_lshlrev_b32_e32 v0, 16, v147
	v_mul_f32_e32 v0, 0xbfb8aa3b, v0
	v_exp_f32_e32 v0, v0
	v_pk_mul_f32 v[156:157], v[156:157], v[158:159]
	v_add_f32_e32 v0, 1.0, v0
	v_rcp_f32_e32 v146, v0
	v_and_b32_e32 v0, 0xffff0000, v149
	v_mul_f32_e32 v0, 0xbfb8aa3b, v0
	v_exp_f32_e32 v149, v0
	v_and_b32_e32 v0, 0xffff0000, v147
	v_mul_f32_e32 v0, 0xbfb8aa3b, v0
	v_exp_f32_e32 v0, v0
	v_pk_add_f32 v[148:149], v[148:149], 1.0 op_sel_hi:[1,0]
	v_pk_mul_f32 v[8:9], v[8:9], v[156:157]
	v_add_f32_e32 v0, 1.0, v0
	v_rcp_f32_e32 v147, v0
	s_nop 0
	v_pk_mul_f32 v[146:147], v[148:149], v[146:147]
	s_nop 0
	v_pk_mul_f32 v[10:11], v[10:11], v[146:147]
	s_waitcnt vmcnt(1)
	v_mov_b32_e32 v144, v238
	v_mov_b32_e32 v145, v239
	s_nop 0
	s_waitcnt vmcnt(0)
	v_mov_b32_e32 v146, v240
	v_mov_b32_e32 v147, v241
	s_nop 0
	v_lshlrev_b32_e32 v0, 16, v144
	v_mul_f32_e32 v0, 0xbfb8aa3b, v0
	v_exp_f32_e32 v2, v0
	v_lshlrev_b32_e32 v0, 16, v146
	v_mul_f32_e32 v0, 0xbfb8aa3b, v0
	v_exp_f32_e32 v0, v0
	s_nop 0
	v_add_f32_e32 v0, 1.0, v0
	v_rcp_f32_e32 v148, v0
	v_and_b32_e32 v0, 0xffff0000, v144
	v_mul_f32_e32 v0, 0xbfb8aa3b, v0
	v_exp_f32_e32 v3, v0
	v_and_b32_e32 v0, 0xffff0000, v146
	v_mul_f32_e32 v0, 0xbfb8aa3b, v0
	v_exp_f32_e32 v0, v0
	v_pk_add_f32 v[2:3], v[2:3], 1.0 op_sel_hi:[1,0]
	v_add_f32_e32 v0, 1.0, v0
	v_rcp_f32_e32 v149, v0
	v_lshlrev_b32_e32 v0, 16, v145
	v_mul_f32_e32 v0, 0xbfb8aa3b, v0
	v_exp_f32_e32 v144, v0
	v_lshlrev_b32_e32 v0, 16, v147
	v_mul_f32_e32 v0, 0xbfb8aa3b, v0
	v_exp_f32_e32 v0, v0
	v_pk_mul_f32 v[2:3], v[2:3], v[148:149]
	v_add_f32_e32 v0, 1.0, v0
	v_rcp_f32_e32 v146, v0
	v_and_b32_e32 v0, 0xffff0000, v145
	v_mul_f32_e32 v0, 0xbfb8aa3b, v0
	v_exp_f32_e32 v145, v0
	v_and_b32_e32 v0, 0xffff0000, v147
	v_mul_f32_e32 v0, 0xbfb8aa3b, v0
	v_exp_f32_e32 v0, v0
	v_pk_add_f32 v[144:145], v[144:145], 1.0 op_sel_hi:[1,0]
	v_pk_mul_f32 v[4:5], v[4:5], v[2:3]
	v_add_f32_e32 v0, 1.0, v0
	v_rcp_f32_e32 v147, v0
	s_nop 0
	v_pk_mul_f32 v[144:145], v[144:145], v[146:147]
	s_nop 0
	v_pk_mul_f32 v[6:7], v[6:7], v[144:145]

.LBB0_1141:
	v_add_u32_e32 v140, s66, v152
	v_or_b32_e32 v146, s67, v154
	v_mov_b64_e32 v[142:143], s[46:47]
	v_mad_i64_i32 v[2:3], s[2:3], v140, s78, v[142:143]
	v_ashrrev_i32_e32 v147, 31, v146
	v_lshl_add_u64 v[144:145], v[2:3], 0, s[24:25]
	v_lshlrev_b64 v[2:3], 1, v[146:147]
	v_lshl_add_u64 v[156:157], v[144:145], 0, v[2:3]
	global_load_dwordx2 v[162:163], v[156:157], off
	global_load_dwordx2 v[164:165], v[156:157], off offset:32
	global_load_dwordx2 v[166:167], v[156:157], off offset:256
	global_load_dwordx2 v[168:169], v[156:157], off offset:288
	v_add_u32_e32 v244, 0x10, v140
	v_mad_i64_i32 v[244:245], s[2:3], v244, s78, v[142:143]
	v_lshl_add_u64 v[244:245], v[244:245], 0, s[24:25]
	v_lshl_add_u64 v[244:245], v[244:245], 0, v[2:3]
	global_load_dwordx2 v[170:171], v[244:245], off
	global_load_dwordx2 v[172:173], v[244:245], off offset:32
	global_load_dwordx2 v[174:175], v[244:245], off offset:256
	global_load_dwordx2 v[178:179], v[244:245], off offset:288
	v_add_u32_e32 v244, 0x20, v140
	v_mad_i64_i32 v[244:245], s[2:3], v244, s78, v[142:143]
	v_lshl_add_u64 v[244:245], v[244:245], 0, s[24:25]
	v_lshl_add_u64 v[244:245], v[244:245], 0, v[2:3]
	global_load_dwordx2 v[180:181], v[244:245], off
	global_load_dwordx2 v[182:183], v[244:245], off offset:32
	global_load_dwordx2 v[184:185], v[244:245], off offset:256
	global_load_dwordx2 v[186:187], v[244:245], off offset:288
	v_add_u32_e32 v244, 0x30, v140
	v_mad_i64_i32 v[244:245], s[2:3], v244, s78, v[142:143]
	v_lshl_add_u64 v[244:245], v[244:245], 0, s[24:25]
	v_lshl_add_u64 v[244:245], v[244:245], 0, v[2:3]
	global_load_dwordx2 v[188:189], v[244:245], off
	global_load_dwordx2 v[190:191], v[244:245], off offset:32
	global_load_dwordx2 v[192:193], v[244:245], off offset:256
	global_load_dwordx2 v[194:195], v[244:245], off offset:288
	v_add_u32_e32 v244, 0x80, v140
	v_mad_i64_i32 v[244:245], s[2:3], v244, s78, v[142:143]
	v_lshl_add_u64 v[244:245], v[244:245], 0, s[24:25]
	v_lshl_add_u64 v[244:245], v[244:245], 0, v[2:3]
	global_load_dwordx2 v[196:197], v[244:245], off
	global_load_dwordx2 v[198:199], v[244:245], off offset:32
	global_load_dwordx2 v[200:201], v[244:245], off offset:256
	global_load_dwordx2 v[202:203], v[244:245], off offset:288
	v_add_u32_e32 v244, 0x90, v140
	v_mad_i64_i32 v[244:245], s[2:3], v244, s78, v[142:143]
	v_lshl_add_u64 v[244:245], v[244:245], 0, s[24:25]
	v_lshl_add_u64 v[244:245], v[244:245], 0, v[2:3]
	global_load_dwordx2 v[204:205], v[244:245], off
	global_load_dwordx2 v[206:207], v[244:245], off offset:32
	global_load_dwordx2 v[208:209], v[244:245], off offset:256
	global_load_dwordx2 v[218:219], v[244:245], off offset:288
	v_add_u32_e32 v244, 0xa0, v140
	v_mad_i64_i32 v[244:245], s[2:3], v244, s78, v[142:143]
	v_lshl_add_u64 v[244:245], v[244:245], 0, s[24:25]
	v_lshl_add_u64 v[244:245], v[244:245], 0, v[2:3]
	global_load_dwordx2 v[220:221], v[244:245], off
	global_load_dwordx2 v[222:223], v[244:245], off offset:32
	global_load_dwordx2 v[224:225], v[244:245], off offset:256
	global_load_dwordx2 v[232:233], v[244:245], off offset:288
	v_add_u32_e32 v244, 0xb0, v140
	v_mad_i64_i32 v[244:245], s[2:3], v244, s78, v[142:143]
	v_lshl_add_u64 v[244:245], v[244:245], 0, s[24:25]
	v_lshl_add_u64 v[244:245], v[244:245], 0, v[2:3]
	global_load_dwordx2 v[234:235], v[244:245], off
	global_load_dwordx2 v[236:237], v[244:245], off offset:32
	global_load_dwordx2 v[238:239], v[244:245], off offset:256
	global_load_dwordx2 v[240:241], v[244:245], off offset:288
	s_waitcnt vmcnt(31)
	v_mov_b32_e32 v156, v162
	v_mov_b32_e32 v157, v163
	v_ashrrev_i32_e32 v141, 31, v140
	v_lshlrev_b64 v[148:149], 12, v[140:141]
	s_nop 0
	v_lshlrev_b32_e32 v0, 16, v156
	v_mul_f32_e32 v0, 0xbfb8aa3b, v0
	v_exp_f32_e32 v158, v0
	v_and_b32_e32 v0, 0xffff0000, v156
	v_mul_f32_e32 v0, 0xbfb8aa3b, v0
	v_exp_f32_e32 v159, v0
	v_lshlrev_b32_e32 v0, 16, v157
	v_mul_f32_e32 v0, 0xbfb8aa3b, v0
	v_exp_f32_e32 v156, v0
	v_and_b32_e32 v0, 0xffff0000, v157
	v_mul_f32_e32 v0, 0xbfb8aa3b, v0
	v_pk_add_f32 v[158:159], v[158:159], 1.0 op_sel_hi:[1,0]
	v_exp_f32_e32 v157, v0
	v_div_scale_f32 v0, s[2:3], v159, v159, 1.0
	v_rcp_f32_e32 v141, v0
	v_pk_add_f32 v[156:157], v[156:157], 1.0 op_sel_hi:[1,0]
	v_fma_f32 v147, -v0, v141, 1.0
	v_fmac_f32_e32 v141, v147, v141
	v_div_scale_f32 v147, vcc, 1.0, v159, 1.0
	v_mul_f32_e32 v160, v147, v141
	v_fma_f32 v161, -v0, v160, v147
	v_fmac_f32_e32 v160, v161, v141
	v_fma_f32 v0, -v0, v160, v147
	v_div_fmas_f32 v0, v0, v141, v160
	v_div_fixup_f32 v159, v0, v159, 1.0
	v_div_scale_f32 v0, s[2:3], v158, v158, 1.0
	v_rcp_f32_e32 v141, v0
	s_nop 0
	v_fma_f32 v147, -v0, v141, 1.0
	v_fmac_f32_e32 v141, v147, v141
	v_div_scale_f32 v147, vcc, 1.0, v158, 1.0
	v_mul_f32_e32 v160, v147, v141
	v_fma_f32 v161, -v0, v160, v147
	v_fmac_f32_e32 v160, v161, v141
	v_fma_f32 v0, -v0, v160, v147
	v_div_fmas_f32 v0, v0, v141, v160
	v_div_fixup_f32 v158, v0, v158, 1.0
	v_div_scale_f32 v0, s[2:3], v157, v157, 1.0
	v_rcp_f32_e32 v141, v0
	v_pk_mul_f32 v[128:129], v[128:129], v[158:159]
	v_fma_f32 v147, -v0, v141, 1.0
	v_fmac_f32_e32 v141, v147, v141
	v_div_scale_f32 v147, vcc, 1.0, v157, 1.0
	v_mul_f32_e32 v160, v147, v141
	v_fma_f32 v161, -v0, v160, v147
	v_fmac_f32_e32 v160, v161, v141
	v_fma_f32 v0, -v0, v160, v147
	v_div_fmas_f32 v0, v0, v141, v160
	v_div_fixup_f32 v157, v0, v157, 1.0
	v_div_scale_f32 v0, s[2:3], v156, v156, 1.0
	v_rcp_f32_e32 v141, v0
	v_cvt_pk_bf16_f32 v128, v128, v129
	s_nop 0
	v_fma_f32 v147, -v0, v141, 1.0
	v_fmac_f32_e32 v141, v147, v141
	v_div_scale_f32 v147, vcc, 1.0, v156, 1.0
	v_mul_f32_e32 v160, v147, v141
	v_fma_f32 v161, -v0, v160, v147
	v_fmac_f32_e32 v160, v161, v141
	v_fma_f32 v0, -v0, v160, v147
	v_div_fmas_f32 v0, v0, v141, v160
	v_div_fixup_f32 v156, v0, v156, 1.0
	v_pk_mul_f32 v[130:131], v[130:131], v[156:157]
	s_nop 0
	v_cvt_pk_bf16_f32 v129, v130, v131
	v_lshl_add_u64 v[130:131], s[48:49], 0, v[148:149]
	v_lshl_add_u64 v[130:131], v[130:131], 0, v[2:3]
	global_store_dwordx2 v[130:131], v[128:129], off
	v_or_b32_e32 v128, 16, v146
	v_ashrrev_i32_e32 v129, 31, v128
	v_lshlrev_b64 v[128:129], 1, v[128:129]
	v_lshl_add_u64 v[148:149], v[144:145], 0, v[128:129]
	s_waitcnt vmcnt(31)
	v_mov_b32_e32 v148, v164
	v_mov_b32_e32 v149, v165
	s_nop 0
	v_lshlrev_b32_e32 v0, 16, v148
	v_mul_f32_e32 v0, 0xbfb8aa3b, v0
	v_exp_f32_e32 v156, v0
	v_and_b32_e32 v0, 0xffff0000, v148
	v_mul_f32_e32 v0, 0xbfb8aa3b, v0
	v_exp_f32_e32 v157, v0
	v_lshlrev_b32_e32 v0, 16, v149
	v_mul_f32_e32 v0, 0xbfb8aa3b, v0
	v_exp_f32_e32 v148, v0
	v_and_b32_e32 v0, 0xffff0000, v149
	v_mul_f32_e32 v0, 0xbfb8aa3b, v0
	v_pk_add_f32 v[156:157], v[156:157], 1.0 op_sel_hi:[1,0]
	v_exp_f32_e32 v149, v0
	v_div_scale_f32 v0, s[2:3], v157, v157, 1.0
	v_rcp_f32_e32 v141, v0
	v_pk_add_f32 v[148:149], v[148:149], 1.0 op_sel_hi:[1,0]
	v_fma_f32 v147, -v0, v141, 1.0
	v_fmac_f32_e32 v141, v147, v141
	v_div_scale_f32 v147, vcc, 1.0, v157, 1.0
	v_mul_f32_e32 v158, v147, v141
	v_fma_f32 v159, -v0, v158, v147
	v_fmac_f32_e32 v158, v159, v141
	v_fma_f32 v0, -v0, v158, v147
	v_div_fmas_f32 v0, v0, v141, v158
	v_div_fixup_f32 v157, v0, v157, 1.0
	v_div_scale_f32 v0, s[2:3], v156, v156, 1.0
	v_rcp_f32_e32 v141, v0
	s_nop 0
	v_fma_f32 v147, -v0, v141, 1.0
	v_fmac_f32_e32 v141, v147, v141
	v_div_scale_f32 v147, vcc, 1.0, v156, 1.0
	v_mul_f32_e32 v158, v147, v141
	v_fma_f32 v159, -v0, v158, v147
	v_fmac_f32_e32 v158, v159, v141
	v_fma_f32 v0, -v0, v158, v147
	v_div_fmas_f32 v0, v0, v141, v158
	v_div_fixup_f32 v156, v0, v156, 1.0
	v_div_scale_f32 v0, s[2:3], v149, v149, 1.0
	v_rcp_f32_e32 v141, v0
	v_pk_mul_f32 v[124:125], v[124:125], v[156:157]
	v_fma_f32 v147, -v0, v141, 1.0
	v_fmac_f32_e32 v141, v147, v141
	v_div_scale_f32 v147, vcc, 1.0, v149, 1.0
	v_mul_f32_e32 v158, v147, v141
	v_fma_f32 v159, -v0, v158, v147
	v_fmac_f32_e32 v158, v159, v141
	v_fma_f32 v0, -v0, v158, v147
	v_div_fmas_f32 v0, v0, v141, v158
	v_div_fixup_f32 v149, v0, v149, 1.0
	v_div_scale_f32 v0, s[2:3], v148, v148, 1.0
	v_rcp_f32_e32 v141, v0
	v_cvt_pk_bf16_f32 v124, v124, v125
	s_nop 0
	v_fma_f32 v147, -v0, v141, 1.0
	v_fmac_f32_e32 v141, v147, v141
	v_div_scale_f32 v147, vcc, 1.0, v148, 1.0
	v_mul_f32_e32 v158, v147, v141
	v_fma_f32 v159, -v0, v158, v147
	v_fmac_f32_e32 v158, v159, v141
	v_fma_f32 v0, -v0, v158, v147
	v_div_fmas_f32 v0, v0, v141, v158
	v_div_fixup_f32 v148, v0, v148, 1.0
	v_pk_mul_f32 v[126:127], v[126:127], v[148:149]
	s_nop 0
	v_cvt_pk_bf16_f32 v125, v126, v127
	global_store_dwordx2 v[130:131], v[124:125], off offset:32
	v_or_b32_e32 v124, 0x80, v146
	v_ashrrev_i32_e32 v125, 31, v124
	v_lshlrev_b64 v[124:125], 1, v[124:125]
	v_lshl_add_u64 v[126:127], v[144:145], 0, v[124:125]
	s_waitcnt vmcnt(31)
	v_mov_b32_e32 v126, v166
	v_mov_b32_e32 v127, v167
	s_nop 0
	v_lshlrev_b32_e32 v0, 16, v126
	v_mul_f32_e32 v0, 0xbfb8aa3b, v0
	v_exp_f32_e32 v148, v0
	v_and_b32_e32 v0, 0xffff0000, v126
	v_mul_f32_e32 v0, 0xbfb8aa3b, v0
	v_exp_f32_e32 v149, v0
	v_lshlrev_b32_e32 v0, 16, v127
	v_mul_f32_e32 v0, 0xbfb8aa3b, v0
	v_exp_f32_e32 v126, v0
	v_and_b32_e32 v0, 0xffff0000, v127
	v_mul_f32_e32 v0, 0xbfb8aa3b, v0
	v_pk_add_f32 v[148:149], v[148:149], 1.0 op_sel_hi:[1,0]
	v_exp_f32_e32 v127, v0
	v_div_scale_f32 v0, s[2:3], v149, v149, 1.0
	v_rcp_f32_e32 v141, v0
	v_pk_add_f32 v[126:127], v[126:127], 1.0 op_sel_hi:[1,0]
	v_fma_f32 v147, -v0, v141, 1.0
	v_fmac_f32_e32 v141, v147, v141
	v_div_scale_f32 v147, vcc, 1.0, v149, 1.0
	v_mul_f32_e32 v156, v147, v141
	v_fma_f32 v157, -v0, v156, v147
	v_fmac_f32_e32 v156, v157, v141
	v_fma_f32 v0, -v0, v156, v147
	v_div_fmas_f32 v0, v0, v141, v156
	v_div_fixup_f32 v149, v0, v149, 1.0
	v_div_scale_f32 v0, s[2:3], v148, v148, 1.0
	v_rcp_f32_e32 v141, v0
	s_nop 0
	v_fma_f32 v147, -v0, v141, 1.0
	v_fmac_f32_e32 v141, v147, v141
	v_div_scale_f32 v147, vcc, 1.0, v148, 1.0
	v_mul_f32_e32 v156, v147, v141
	v_fma_f32 v157, -v0, v156, v147
	v_fmac_f32_e32 v156, v157, v141
	v_fma_f32 v0, -v0, v156, v147
	v_div_fmas_f32 v0, v0, v141, v156
	v_div_fixup_f32 v148, v0, v148, 1.0
	v_div_scale_f32 v0, s[2:3], v127, v127, 1.0
	v_rcp_f32_e32 v141, v0
	v_pk_mul_f32 v[120:121], v[120:121], v[148:149]
	v_fma_f32 v147, -v0, v141, 1.0
	v_fmac_f32_e32 v141, v147, v141
	v_div_scale_f32 v147, vcc, 1.0, v127, 1.0
	v_mul_f32_e32 v156, v147, v141
	v_fma_f32 v157, -v0, v156, v147
	v_fmac_f32_e32 v156, v157, v141
	v_fma_f32 v0, -v0, v156, v147
	v_div_fmas_f32 v0, v0, v141, v156
	v_div_fixup_f32 v127, v0, v127, 1.0
	v_div_scale_f32 v0, s[2:3], v126, v126, 1.0
	v_rcp_f32_e32 v141, v0
	v_cvt_pk_bf16_f32 v120, v120, v121
	s_nop 0
	v_fma_f32 v147, -v0, v141, 1.0
	v_fmac_f32_e32 v141, v147, v141
	v_div_scale_f32 v147, vcc, 1.0, v126, 1.0
	v_mul_f32_e32 v156, v147, v141
	v_fma_f32 v157, -v0, v156, v147
	v_fmac_f32_e32 v156, v157, v141
	v_fma_f32 v0, -v0, v156, v147
	v_div_fmas_f32 v0, v0, v141, v156
	v_div_fixup_f32 v126, v0, v126, 1.0
	v_pk_mul_f32 v[122:123], v[122:123], v[126:127]
	s_nop 0
	v_cvt_pk_bf16_f32 v121, v122, v123
	global_store_dwordx2 v[130:131], v[120:121], off offset:256
	v_or_b32_e32 v120, 0x90, v146
	v_ashrrev_i32_e32 v121, 31, v120
	v_lshlrev_b64 v[120:121], 1, v[120:121]
	v_lshl_add_u64 v[122:123], v[144:145], 0, v[120:121]
	s_waitcnt vmcnt(31)
	v_mov_b32_e32 v122, v168
	v_mov_b32_e32 v123, v169
	s_nop 0
	v_lshlrev_b32_e32 v0, 16, v122
	v_mul_f32_e32 v0, 0xbfb8aa3b, v0
	v_exp_f32_e32 v126, v0
	v_and_b32_e32 v0, 0xffff0000, v122
	v_mul_f32_e32 v0, 0xbfb8aa3b, v0
	v_exp_f32_e32 v127, v0
	v_lshlrev_b32_e32 v0, 16, v123
	v_mul_f32_e32 v0, 0xbfb8aa3b, v0
	v_exp_f32_e32 v122, v0
	v_and_b32_e32 v0, 0xffff0000, v123
	v_mul_f32_e32 v0, 0xbfb8aa3b, v0
	v_pk_add_f32 v[126:127], v[126:127], 1.0 op_sel_hi:[1,0]
	v_exp_f32_e32 v123, v0
	v_div_scale_f32 v0, s[2:3], v127, v127, 1.0
	v_rcp_f32_e32 v141, v0
	v_pk_add_f32 v[122:123], v[122:123], 1.0 op_sel_hi:[1,0]
	v_fma_f32 v144, -v0, v141, 1.0
	v_fmac_f32_e32 v141, v144, v141
	v_div_scale_f32 v144, vcc, 1.0, v127, 1.0
	v_mul_f32_e32 v145, v144, v141
	v_fma_f32 v146, -v0, v145, v144
	v_fmac_f32_e32 v145, v146, v141
	v_fma_f32 v0, -v0, v145, v144
	v_div_fmas_f32 v0, v0, v141, v145
	v_div_fixup_f32 v127, v0, v127, 1.0
	v_div_scale_f32 v0, s[2:3], v126, v126, 1.0
	v_rcp_f32_e32 v141, v0
	s_nop 0
	v_fma_f32 v144, -v0, v141, 1.0
	v_fmac_f32_e32 v141, v144, v141
	v_div_scale_f32 v144, vcc, 1.0, v126, 1.0
	v_mul_f32_e32 v145, v144, v141
	v_fma_f32 v146, -v0, v145, v144
	v_fmac_f32_e32 v145, v146, v141
	v_fma_f32 v0, -v0, v145, v144
	v_div_fmas_f32 v0, v0, v141, v145
	v_div_fixup_f32 v126, v0, v126, 1.0
	v_div_scale_f32 v0, s[2:3], v123, v123, 1.0
	v_rcp_f32_e32 v141, v0
	v_pk_mul_f32 v[116:117], v[116:117], v[126:127]
	v_fma_f32 v144, -v0, v141, 1.0
	v_fmac_f32_e32 v141, v144, v141
	v_div_scale_f32 v144, vcc, 1.0, v123, 1.0
	v_mul_f32_e32 v145, v144, v141
	v_fma_f32 v146, -v0, v145, v144
	v_fmac_f32_e32 v145, v146, v141
	v_fma_f32 v0, -v0, v145, v144
	v_div_fmas_f32 v0, v0, v141, v145
	v_div_fixup_f32 v123, v0, v123, 1.0
	v_div_scale_f32 v0, s[2:3], v122, v122, 1.0
	v_rcp_f32_e32 v141, v0
	v_cvt_pk_bf16_f32 v116, v116, v117
	s_nop 0
	v_fma_f32 v144, -v0, v141, 1.0
	v_fmac_f32_e32 v141, v144, v141
	v_div_scale_f32 v144, vcc, 1.0, v122, 1.0
	v_mul_f32_e32 v145, v144, v141
	v_fma_f32 v146, -v0, v145, v144
	v_fmac_f32_e32 v145, v146, v141
	v_fma_f32 v0, -v0, v145, v144
	v_div_fmas_f32 v0, v0, v141, v145
	v_div_fixup_f32 v122, v0, v122, 1.0
	v_pk_mul_f32 v[118:119], v[118:119], v[122:123]
	s_nop 0
	v_cvt_pk_bf16_f32 v117, v118, v119
	global_store_dwordx2 v[130:131], v[116:117], off offset:288
	v_or_b32_e32 v116, 16, v140
	v_ashrrev_i32_e32 v117, 31, v116
	v_lshlrev_b64 v[118:119], 12, v[116:117]
	v_mad_i64_i32 v[116:117], s[2:3], v116, s78, v[142:143]
	v_lshl_add_u64 v[116:117], v[116:117], 0, s[24:25]
	v_lshl_add_u64 v[122:123], v[116:117], 0, v[2:3]
	s_waitcnt vmcnt(31)
	v_mov_b32_e32 v122, v170
	v_mov_b32_e32 v123, v171
	s_nop 0
	v_lshlrev_b32_e32 v0, 16, v122
	v_mul_f32_e32 v0, 0xbfb8aa3b, v0
	v_exp_f32_e32 v126, v0
	v_and_b32_e32 v0, 0xffff0000, v122
	v_mul_f32_e32 v0, 0xbfb8aa3b, v0
	v_exp_f32_e32 v127, v0
	v_lshlrev_b32_e32 v0, 16, v123
	v_mul_f32_e32 v0, 0xbfb8aa3b, v0
	v_exp_f32_e32 v122, v0
	v_and_b32_e32 v0, 0xffff0000, v123
	v_mul_f32_e32 v0, 0xbfb8aa3b, v0
	v_pk_add_f32 v[126:127], v[126:127], 1.0 op_sel_hi:[1,0]
	v_exp_f32_e32 v123, v0
	v_div_scale_f32 v0, s[2:3], v127, v127, 1.0
	v_rcp_f32_e32 v130, v0
	v_pk_add_f32 v[122:123], v[122:123], 1.0 op_sel_hi:[1,0]
	v_fma_f32 v131, -v0, v130, 1.0
	v_fmac_f32_e32 v130, v131, v130
	v_div_scale_f32 v131, vcc, 1.0, v127, 1.0
	v_mul_f32_e32 v141, v131, v130
	v_fma_f32 v144, -v0, v141, v131
	v_fmac_f32_e32 v141, v144, v130
	v_fma_f32 v0, -v0, v141, v131
	v_div_fmas_f32 v0, v0, v130, v141
	v_div_fixup_f32 v127, v0, v127, 1.0
	v_div_scale_f32 v0, s[2:3], v126, v126, 1.0
	v_rcp_f32_e32 v130, v0
	s_nop 0
	v_fma_f32 v131, -v0, v130, 1.0
	v_fmac_f32_e32 v130, v131, v130
	v_div_scale_f32 v131, vcc, 1.0, v126, 1.0
	v_mul_f32_e32 v141, v131, v130
	v_fma_f32 v144, -v0, v141, v131
	v_fmac_f32_e32 v141, v144, v130
	v_fma_f32 v0, -v0, v141, v131
	v_div_fmas_f32 v0, v0, v130, v141
	v_div_fixup_f32 v126, v0, v126, 1.0
	v_div_scale_f32 v0, s[2:3], v123, v123, 1.0
	v_rcp_f32_e32 v130, v0
	v_pk_mul_f32 v[112:113], v[112:113], v[126:127]
	v_fma_f32 v131, -v0, v130, 1.0
	v_fmac_f32_e32 v130, v131, v130
	v_div_scale_f32 v131, vcc, 1.0, v123, 1.0
	v_mul_f32_e32 v141, v131, v130
	v_fma_f32 v144, -v0, v141, v131
	v_fmac_f32_e32 v141, v144, v130
	v_fma_f32 v0, -v0, v141, v131
	v_div_fmas_f32 v0, v0, v130, v141
	v_div_fixup_f32 v123, v0, v123, 1.0
	v_div_scale_f32 v0, s[2:3], v122, v122, 1.0
	v_rcp_f32_e32 v130, v0
	s_nop 0
	v_fma_f32 v131, -v0, v130, 1.0
	v_fmac_f32_e32 v130, v131, v130
	v_div_scale_f32 v131, vcc, 1.0, v122, 1.0
	v_mul_f32_e32 v141, v131, v130
	v_fma_f32 v144, -v0, v141, v131
	v_fmac_f32_e32 v141, v144, v130
	v_fma_f32 v0, -v0, v141, v131
	v_div_fmas_f32 v0, v0, v130, v141
	v_div_fixup_f32 v122, v0, v122, 1.0
	v_pk_mul_f32 v[114:115], v[114:115], v[122:123]
	v_cvt_pk_bf16_f32 v122, v112, v113
	v_lshl_add_u64 v[112:113], s[48:49], 0, v[118:119]
	v_cvt_pk_bf16_f32 v123, v114, v115
	v_lshl_add_u64 v[114:115], v[116:117], 0, v[128:129]
	s_waitcnt vmcnt(30)
	v_mov_b32_e32 v114, v172
	v_mov_b32_e32 v115, v173
	v_lshl_add_u64 v[112:113], v[112:113], 0, v[2:3]
	global_store_dwordx2 v[112:113], v[122:123], off
	s_nop 0
	v_lshlrev_b32_e32 v0, 16, v114
	v_mul_f32_e32 v0, 0xbfb8aa3b, v0
	v_exp_f32_e32 v118, v0
	v_and_b32_e32 v0, 0xffff0000, v114
	v_mul_f32_e32 v0, 0xbfb8aa3b, v0
	v_exp_f32_e32 v119, v0
	v_lshlrev_b32_e32 v0, 16, v115
	v_mul_f32_e32 v0, 0xbfb8aa3b, v0
	v_exp_f32_e32 v114, v0
	v_and_b32_e32 v0, 0xffff0000, v115
	v_mul_f32_e32 v0, 0xbfb8aa3b, v0
	v_pk_add_f32 v[118:119], v[118:119], 1.0 op_sel_hi:[1,0]
	v_exp_f32_e32 v115, v0
	v_div_scale_f32 v0, s[2:3], v119, v119, 1.0
	v_rcp_f32_e32 v122, v0
	v_pk_add_f32 v[114:115], v[114:115], 1.0 op_sel_hi:[1,0]
	v_fma_f32 v123, -v0, v122, 1.0
	v_fmac_f32_e32 v122, v123, v122
	v_div_scale_f32 v123, vcc, 1.0, v119, 1.0
	v_mul_f32_e32 v126, v123, v122
	v_fma_f32 v127, -v0, v126, v123
	v_fmac_f32_e32 v126, v127, v122
	v_fma_f32 v0, -v0, v126, v123
	v_div_fmas_f32 v0, v0, v122, v126
	v_div_fixup_f32 v119, v0, v119, 1.0
	v_div_scale_f32 v0, s[2:3], v118, v118, 1.0
	v_rcp_f32_e32 v122, v0
	s_nop 0
	v_fma_f32 v123, -v0, v122, 1.0
	v_fmac_f32_e32 v122, v123, v122
	v_div_scale_f32 v123, vcc, 1.0, v118, 1.0
	v_mul_f32_e32 v126, v123, v122
	v_fma_f32 v127, -v0, v126, v123
	v_fmac_f32_e32 v126, v127, v122
	v_fma_f32 v0, -v0, v126, v123
	v_div_fmas_f32 v0, v0, v122, v126
	v_div_fixup_f32 v118, v0, v118, 1.0
	v_div_scale_f32 v0, s[2:3], v115, v115, 1.0
	v_rcp_f32_e32 v122, v0
	v_pk_mul_f32 v[108:109], v[108:109], v[118:119]
	v_fma_f32 v123, -v0, v122, 1.0
	v_fmac_f32_e32 v122, v123, v122
	v_div_scale_f32 v123, vcc, 1.0, v115, 1.0
	v_mul_f32_e32 v126, v123, v122
	v_fma_f32 v127, -v0, v126, v123
	v_fmac_f32_e32 v126, v127, v122
	v_fma_f32 v0, -v0, v126, v123
	v_div_fmas_f32 v0, v0, v122, v126
	v_div_fixup_f32 v115, v0, v115, 1.0
	v_div_scale_f32 v0, s[2:3], v114, v114, 1.0
	v_rcp_f32_e32 v122, v0
	v_cvt_pk_bf16_f32 v108, v108, v109
	s_nop 0
	v_fma_f32 v123, -v0, v122, 1.0
	v_fmac_f32_e32 v122, v123, v122
	v_div_scale_f32 v123, vcc, 1.0, v114, 1.0
	v_mul_f32_e32 v126, v123, v122
	v_fma_f32 v127, -v0, v126, v123
	v_fmac_f32_e32 v126, v127, v122
	v_fma_f32 v0, -v0, v126, v123
	v_div_fmas_f32 v0, v0, v122, v126
	v_div_fixup_f32 v114, v0, v114, 1.0
	v_pk_mul_f32 v[110:111], v[110:111], v[114:115]
	s_nop 0
	v_cvt_pk_bf16_f32 v109, v110, v111
	global_store_dwordx2 v[112:113], v[108:109], off offset:32
	v_lshl_add_u64 v[108:109], v[116:117], 0, v[124:125]
	s_waitcnt vmcnt(31)
	v_mov_b32_e32 v108, v174
	v_mov_b32_e32 v109, v175
	s_nop 0
	v_lshlrev_b32_e32 v0, 16, v108
	v_mul_f32_e32 v0, 0xbfb8aa3b, v0
	v_exp_f32_e32 v110, v0
	v_and_b32_e32 v0, 0xffff0000, v108
	v_mul_f32_e32 v0, 0xbfb8aa3b, v0
	v_exp_f32_e32 v111, v0
	v_lshlrev_b32_e32 v0, 16, v109
	v_mul_f32_e32 v0, 0xbfb8aa3b, v0
	v_exp_f32_e32 v108, v0
	v_and_b32_e32 v0, 0xffff0000, v109
	v_mul_f32_e32 v0, 0xbfb8aa3b, v0
	v_pk_add_f32 v[110:111], v[110:111], 1.0 op_sel_hi:[1,0]
	v_exp_f32_e32 v109, v0
	v_div_scale_f32 v0, s[2:3], v111, v111, 1.0
	v_rcp_f32_e32 v114, v0
	v_pk_add_f32 v[108:109], v[108:109], 1.0 op_sel_hi:[1,0]
	v_fma_f32 v115, -v0, v114, 1.0
	v_fmac_f32_e32 v114, v115, v114
	v_div_scale_f32 v115, vcc, 1.0, v111, 1.0
	v_mul_f32_e32 v118, v115, v114
	v_fma_f32 v119, -v0, v118, v115
	v_fmac_f32_e32 v118, v119, v114
	v_fma_f32 v0, -v0, v118, v115
	v_div_fmas_f32 v0, v0, v114, v118
	v_div_fixup_f32 v111, v0, v111, 1.0
	v_div_scale_f32 v0, s[2:3], v110, v110, 1.0
	v_rcp_f32_e32 v114, v0
	s_nop 0
	v_fma_f32 v115, -v0, v114, 1.0
	v_fmac_f32_e32 v114, v115, v114
	v_div_scale_f32 v115, vcc, 1.0, v110, 1.0
	v_mul_f32_e32 v118, v115, v114
	v_fma_f32 v119, -v0, v118, v115
	v_fmac_f32_e32 v118, v119, v114
	v_fma_f32 v0, -v0, v118, v115
	v_div_fmas_f32 v0, v0, v114, v118
	v_div_fixup_f32 v110, v0, v110, 1.0
	v_div_scale_f32 v0, s[2:3], v109, v109, 1.0
	v_rcp_f32_e32 v114, v0
	v_pk_mul_f32 v[104:105], v[104:105], v[110:111]
	v_fma_f32 v115, -v0, v114, 1.0
	v_fmac_f32_e32 v114, v115, v114
	v_div_scale_f32 v115, vcc, 1.0, v109, 1.0
	v_mul_f32_e32 v118, v115, v114
	v_fma_f32 v119, -v0, v118, v115
	v_fmac_f32_e32 v118, v119, v114
	v_fma_f32 v0, -v0, v118, v115
	v_div_fmas_f32 v0, v0, v114, v118
	v_div_fixup_f32 v109, v0, v109, 1.0
	v_div_scale_f32 v0, s[2:3], v108, v108, 1.0
	v_rcp_f32_e32 v114, v0
	v_cvt_pk_bf16_f32 v104, v104, v105
	s_nop 0
	v_fma_f32 v115, -v0, v114, 1.0
	v_fmac_f32_e32 v114, v115, v114
	v_div_scale_f32 v115, vcc, 1.0, v108, 1.0
	v_mul_f32_e32 v118, v115, v114
	v_fma_f32 v119, -v0, v118, v115
	v_fmac_f32_e32 v118, v119, v114
	v_fma_f32 v0, -v0, v118, v115
	v_div_fmas_f32 v0, v0, v114, v118
	v_div_fixup_f32 v108, v0, v108, 1.0
	v_pk_mul_f32 v[106:107], v[106:107], v[108:109]
	s_nop 0
	v_cvt_pk_bf16_f32 v105, v106, v107
	global_store_dwordx2 v[112:113], v[104:105], off offset:256
	v_lshl_add_u64 v[104:105], v[116:117], 0, v[120:121]
	s_waitcnt vmcnt(31)
	v_mov_b32_e32 v104, v178
	v_mov_b32_e32 v105, v179
	s_nop 0
	v_lshlrev_b32_e32 v0, 16, v104
	v_mul_f32_e32 v0, 0xbfb8aa3b, v0
	v_exp_f32_e32 v106, v0
	v_and_b32_e32 v0, 0xffff0000, v104
	v_mul_f32_e32 v0, 0xbfb8aa3b, v0
	v_exp_f32_e32 v107, v0
	v_lshlrev_b32_e32 v0, 16, v105
	v_mul_f32_e32 v0, 0xbfb8aa3b, v0
	v_exp_f32_e32 v104, v0
	v_and_b32_e32 v0, 0xffff0000, v105
	v_mul_f32_e32 v0, 0xbfb8aa3b, v0
	v_pk_add_f32 v[106:107], v[106:107], 1.0 op_sel_hi:[1,0]
	v_exp_f32_e32 v105, v0
	v_div_scale_f32 v0, s[2:3], v107, v107, 1.0
	v_rcp_f32_e32 v108, v0
	v_pk_add_f32 v[104:105], v[104:105], 1.0 op_sel_hi:[1,0]
	v_fma_f32 v109, -v0, v108, 1.0
	v_fmac_f32_e32 v108, v109, v108
	v_div_scale_f32 v109, vcc, 1.0, v107, 1.0
	v_mul_f32_e32 v110, v109, v108
	v_fma_f32 v111, -v0, v110, v109
	v_fmac_f32_e32 v110, v111, v108
	v_fma_f32 v0, -v0, v110, v109
	v_div_fmas_f32 v0, v0, v108, v110
	v_div_fixup_f32 v107, v0, v107, 1.0
	v_div_scale_f32 v0, s[2:3], v106, v106, 1.0
	v_rcp_f32_e32 v108, v0
	s_nop 0
	v_fma_f32 v109, -v0, v108, 1.0
	v_fmac_f32_e32 v108, v109, v108
	v_div_scale_f32 v109, vcc, 1.0, v106, 1.0
	v_mul_f32_e32 v110, v109, v108
	v_fma_f32 v111, -v0, v110, v109
	v_fmac_f32_e32 v110, v111, v108
	v_fma_f32 v0, -v0, v110, v109
	v_div_fmas_f32 v0, v0, v108, v110
	v_div_fixup_f32 v106, v0, v106, 1.0
	v_div_scale_f32 v0, s[2:3], v105, v105, 1.0
	v_rcp_f32_e32 v108, v0
	v_pk_mul_f32 v[100:101], v[100:101], v[106:107]
	v_fma_f32 v109, -v0, v108, 1.0
	v_fmac_f32_e32 v108, v109, v108
	v_div_scale_f32 v109, vcc, 1.0, v105, 1.0
	v_mul_f32_e32 v110, v109, v108
	v_fma_f32 v111, -v0, v110, v109
	v_fmac_f32_e32 v110, v111, v108
	v_fma_f32 v0, -v0, v110, v109
	v_div_fmas_f32 v0, v0, v108, v110
	v_div_fixup_f32 v105, v0, v105, 1.0
	v_div_scale_f32 v0, s[2:3], v104, v104, 1.0
	v_rcp_f32_e32 v108, v0
	v_cvt_pk_bf16_f32 v100, v100, v101
	s_nop 0
	v_fma_f32 v109, -v0, v108, 1.0
	v_fmac_f32_e32 v108, v109, v108
	v_div_scale_f32 v109, vcc, 1.0, v104, 1.0
	v_mul_f32_e32 v110, v109, v108
	v_fma_f32 v111, -v0, v110, v109
	v_fmac_f32_e32 v110, v111, v108
	v_fma_f32 v0, -v0, v110, v109
	v_div_fmas_f32 v0, v0, v108, v110
	v_div_fixup_f32 v104, v0, v104, 1.0
	v_pk_mul_f32 v[102:103], v[102:103], v[104:105]
	s_nop 0
	v_cvt_pk_bf16_f32 v101, v102, v103
	global_store_dwordx2 v[112:113], v[100:101], off offset:288
	v_or_b32_e32 v100, 32, v140
	v_ashrrev_i32_e32 v101, 31, v100
	v_lshlrev_b64 v[102:103], 12, v[100:101]
	v_mad_i64_i32 v[100:101], s[2:3], v100, s78, v[142:143]
	v_lshl_add_u64 v[100:101], v[100:101], 0, s[24:25]
	v_lshl_add_u64 v[104:105], v[100:101], 0, v[2:3]
	s_waitcnt vmcnt(31)
	v_mov_b32_e32 v104, v180
	v_mov_b32_e32 v105, v181
	s_nop 0
	v_lshlrev_b32_e32 v0, 16, v104
	v_mul_f32_e32 v0, 0xbfb8aa3b, v0
	v_exp_f32_e32 v106, v0
	v_and_b32_e32 v0, 0xffff0000, v104
	v_mul_f32_e32 v0, 0xbfb8aa3b, v0
	v_exp_f32_e32 v107, v0
	v_lshlrev_b32_e32 v0, 16, v105
	v_mul_f32_e32 v0, 0xbfb8aa3b, v0
	v_exp_f32_e32 v104, v0
	v_and_b32_e32 v0, 0xffff0000, v105
	v_mul_f32_e32 v0, 0xbfb8aa3b, v0
	v_pk_add_f32 v[106:107], v[106:107], 1.0 op_sel_hi:[1,0]
	v_exp_f32_e32 v105, v0
	v_div_scale_f32 v0, s[2:3], v107, v107, 1.0
	v_rcp_f32_e32 v108, v0
	v_pk_add_f32 v[104:105], v[104:105], 1.0 op_sel_hi:[1,0]
	v_fma_f32 v109, -v0, v108, 1.0
	v_fmac_f32_e32 v108, v109, v108
	v_div_scale_f32 v109, vcc, 1.0, v107, 1.0
	v_mul_f32_e32 v110, v109, v108
	v_fma_f32 v111, -v0, v110, v109
	v_fmac_f32_e32 v110, v111, v108
	v_fma_f32 v0, -v0, v110, v109
	v_div_fmas_f32 v0, v0, v108, v110
	v_div_fixup_f32 v107, v0, v107, 1.0
	v_div_scale_f32 v0, s[2:3], v106, v106, 1.0
	v_rcp_f32_e32 v108, v0
	s_nop 0
	v_fma_f32 v109, -v0, v108, 1.0
	v_fmac_f32_e32 v108, v109, v108
	v_div_scale_f32 v109, vcc, 1.0, v106, 1.0
	v_mul_f32_e32 v110, v109, v108
	v_fma_f32 v111, -v0, v110, v109
	v_fmac_f32_e32 v110, v111, v108
	v_fma_f32 v0, -v0, v110, v109
	v_div_fmas_f32 v0, v0, v108, v110
	v_div_fixup_f32 v106, v0, v106, 1.0
	v_div_scale_f32 v0, s[2:3], v105, v105, 1.0
	v_rcp_f32_e32 v108, v0
	v_pk_mul_f32 v[96:97], v[96:97], v[106:107]
	v_fma_f32 v109, -v0, v108, 1.0
	v_fmac_f32_e32 v108, v109, v108
	v_div_scale_f32 v109, vcc, 1.0, v105, 1.0
	v_mul_f32_e32 v110, v109, v108
	v_fma_f32 v111, -v0, v110, v109
	v_fmac_f32_e32 v110, v111, v108
	v_fma_f32 v0, -v0, v110, v109
	v_div_fmas_f32 v0, v0, v108, v110
	v_div_fixup_f32 v105, v0, v105, 1.0
	v_div_scale_f32 v0, s[2:3], v104, v104, 1.0
	v_rcp_f32_e32 v108, v0
	s_nop 0
	v_fma_f32 v109, -v0, v108, 1.0
	v_fmac_f32_e32 v108, v109, v108
	v_div_scale_f32 v109, vcc, 1.0, v104, 1.0
	v_mul_f32_e32 v110, v109, v108
	v_fma_f32 v111, -v0, v110, v109
	v_fmac_f32_e32 v110, v111, v108
	v_fma_f32 v0, -v0, v110, v109
	v_div_fmas_f32 v0, v0, v108, v110
	v_div_fixup_f32 v104, v0, v104, 1.0
	v_pk_mul_f32 v[98:99], v[98:99], v[104:105]
	v_cvt_pk_bf16_f32 v104, v96, v97
	v_lshl_add_u64 v[96:97], s[48:49], 0, v[102:103]
	v_cvt_pk_bf16_f32 v105, v98, v99
	v_lshl_add_u64 v[98:99], v[100:101], 0, v[128:129]
	s_waitcnt vmcnt(30)
	v_mov_b32_e32 v98, v182
	v_mov_b32_e32 v99, v183
	v_lshl_add_u64 v[96:97], v[96:97], 0, v[2:3]
	global_store_dwordx2 v[96:97], v[104:105], off
	s_nop 0
	v_lshlrev_b32_e32 v0, 16, v98
	v_mul_f32_e32 v0, 0xbfb8aa3b, v0
	v_exp_f32_e32 v102, v0
	v_and_b32_e32 v0, 0xffff0000, v98
	v_mul_f32_e32 v0, 0xbfb8aa3b, v0
	v_exp_f32_e32 v103, v0
	v_lshlrev_b32_e32 v0, 16, v99
	v_mul_f32_e32 v0, 0xbfb8aa3b, v0
	v_exp_f32_e32 v98, v0
	v_and_b32_e32 v0, 0xffff0000, v99
	v_mul_f32_e32 v0, 0xbfb8aa3b, v0
	v_pk_add_f32 v[102:103], v[102:103], 1.0 op_sel_hi:[1,0]
	v_exp_f32_e32 v99, v0
	v_div_scale_f32 v0, s[2:3], v103, v103, 1.0
	v_rcp_f32_e32 v104, v0
	v_pk_add_f32 v[98:99], v[98:99], 1.0 op_sel_hi:[1,0]
	v_fma_f32 v105, -v0, v104, 1.0
	v_fmac_f32_e32 v104, v105, v104
	v_div_scale_f32 v105, vcc, 1.0, v103, 1.0
	v_mul_f32_e32 v106, v105, v104
	v_fma_f32 v107, -v0, v106, v105
	v_fmac_f32_e32 v106, v107, v104
	v_fma_f32 v0, -v0, v106, v105
	v_div_fmas_f32 v0, v0, v104, v106
	v_div_fixup_f32 v103, v0, v103, 1.0
	v_div_scale_f32 v0, s[2:3], v102, v102, 1.0
	v_rcp_f32_e32 v104, v0
	s_nop 0
	v_fma_f32 v105, -v0, v104, 1.0
	v_fmac_f32_e32 v104, v105, v104
	v_div_scale_f32 v105, vcc, 1.0, v102, 1.0
	v_mul_f32_e32 v106, v105, v104
	v_fma_f32 v107, -v0, v106, v105
	v_fmac_f32_e32 v106, v107, v104
	v_fma_f32 v0, -v0, v106, v105
	v_div_fmas_f32 v0, v0, v104, v106
	v_div_fixup_f32 v102, v0, v102, 1.0
	v_div_scale_f32 v0, s[2:3], v99, v99, 1.0
	v_rcp_f32_e32 v104, v0
	v_pk_mul_f32 v[92:93], v[92:93], v[102:103]
	v_fma_f32 v105, -v0, v104, 1.0
	v_fmac_f32_e32 v104, v105, v104
	v_div_scale_f32 v105, vcc, 1.0, v99, 1.0
	v_mul_f32_e32 v106, v105, v104
	v_fma_f32 v107, -v0, v106, v105
	v_fmac_f32_e32 v106, v107, v104
	v_fma_f32 v0, -v0, v106, v105
	v_div_fmas_f32 v0, v0, v104, v106
	v_div_fixup_f32 v99, v0, v99, 1.0
	v_div_scale_f32 v0, s[2:3], v98, v98, 1.0
	v_rcp_f32_e32 v104, v0
	v_cvt_pk_bf16_f32 v92, v92, v93
	s_nop 0
	v_fma_f32 v105, -v0, v104, 1.0
	v_fmac_f32_e32 v104, v105, v104
	v_div_scale_f32 v105, vcc, 1.0, v98, 1.0
	v_mul_f32_e32 v106, v105, v104
	v_fma_f32 v107, -v0, v106, v105
	v_fmac_f32_e32 v106, v107, v104
	v_fma_f32 v0, -v0, v106, v105
	v_div_fmas_f32 v0, v0, v104, v106
	v_div_fixup_f32 v98, v0, v98, 1.0
	v_pk_mul_f32 v[94:95], v[94:95], v[98:99]
	s_nop 0
	v_cvt_pk_bf16_f32 v93, v94, v95
	global_store_dwordx2 v[96:97], v[92:93], off offset:32
	v_lshl_add_u64 v[92:93], v[100:101], 0, v[124:125]
	s_waitcnt vmcnt(31)
	v_mov_b32_e32 v92, v184
	v_mov_b32_e32 v93, v185
	s_nop 0
	v_lshlrev_b32_e32 v0, 16, v92
	v_mul_f32_e32 v0, 0xbfb8aa3b, v0
	v_exp_f32_e32 v94, v0
	v_and_b32_e32 v0, 0xffff0000, v92
	v_mul_f32_e32 v0, 0xbfb8aa3b, v0
	v_exp_f32_e32 v95, v0
	v_lshlrev_b32_e32 v0, 16, v93
	v_mul_f32_e32 v0, 0xbfb8aa3b, v0
	v_exp_f32_e32 v92, v0
	v_and_b32_e32 v0, 0xffff0000, v93
	v_mul_f32_e32 v0, 0xbfb8aa3b, v0
	v_pk_add_f32 v[94:95], v[94:95], 1.0 op_sel_hi:[1,0]
	v_exp_f32_e32 v93, v0
	v_div_scale_f32 v0, s[2:3], v95, v95, 1.0
	v_rcp_f32_e32 v98, v0
	v_pk_add_f32 v[92:93], v[92:93], 1.0 op_sel_hi:[1,0]
	v_fma_f32 v99, -v0, v98, 1.0
	v_fmac_f32_e32 v98, v99, v98
	v_div_scale_f32 v99, vcc, 1.0, v95, 1.0
	v_mul_f32_e32 v102, v99, v98
	v_fma_f32 v103, -v0, v102, v99
	v_fmac_f32_e32 v102, v103, v98
	v_fma_f32 v0, -v0, v102, v99
	v_div_fmas_f32 v0, v0, v98, v102
	v_div_fixup_f32 v95, v0, v95, 1.0
	v_div_scale_f32 v0, s[2:3], v94, v94, 1.0
	v_rcp_f32_e32 v98, v0
	s_nop 0
	v_fma_f32 v99, -v0, v98, 1.0
	v_fmac_f32_e32 v98, v99, v98
	v_div_scale_f32 v99, vcc, 1.0, v94, 1.0
	v_mul_f32_e32 v102, v99, v98
	v_fma_f32 v103, -v0, v102, v99
	v_fmac_f32_e32 v102, v103, v98
	v_fma_f32 v0, -v0, v102, v99
	v_div_fmas_f32 v0, v0, v98, v102
	v_div_fixup_f32 v94, v0, v94, 1.0
	v_div_scale_f32 v0, s[2:3], v93, v93, 1.0
	v_rcp_f32_e32 v98, v0
	v_pk_mul_f32 v[88:89], v[88:89], v[94:95]
	v_fma_f32 v99, -v0, v98, 1.0
	v_fmac_f32_e32 v98, v99, v98
	v_div_scale_f32 v99, vcc, 1.0, v93, 1.0
	v_mul_f32_e32 v102, v99, v98
	v_fma_f32 v103, -v0, v102, v99
	v_fmac_f32_e32 v102, v103, v98
	v_fma_f32 v0, -v0, v102, v99
	v_div_fmas_f32 v0, v0, v98, v102
	v_div_fixup_f32 v93, v0, v93, 1.0
	v_div_scale_f32 v0, s[2:3], v92, v92, 1.0
	v_rcp_f32_e32 v98, v0
	v_cvt_pk_bf16_f32 v88, v88, v89
	s_nop 0
	v_fma_f32 v99, -v0, v98, 1.0
	v_fmac_f32_e32 v98, v99, v98
	v_div_scale_f32 v99, vcc, 1.0, v92, 1.0
	v_mul_f32_e32 v102, v99, v98
	v_fma_f32 v103, -v0, v102, v99
	v_fmac_f32_e32 v102, v103, v98
	v_fma_f32 v0, -v0, v102, v99
	v_div_fmas_f32 v0, v0, v98, v102
	v_div_fixup_f32 v92, v0, v92, 1.0
	v_pk_mul_f32 v[90:91], v[90:91], v[92:93]
	s_nop 0
	v_cvt_pk_bf16_f32 v89, v90, v91
	global_store_dwordx2 v[96:97], v[88:89], off offset:256
	v_lshl_add_u64 v[88:89], v[100:101], 0, v[120:121]
	s_waitcnt vmcnt(31)
	v_mov_b32_e32 v88, v186
	v_mov_b32_e32 v89, v187
	s_nop 0
	v_lshlrev_b32_e32 v0, 16, v88
	v_mul_f32_e32 v0, 0xbfb8aa3b, v0
	v_exp_f32_e32 v90, v0
	v_and_b32_e32 v0, 0xffff0000, v88
	v_mul_f32_e32 v0, 0xbfb8aa3b, v0
	v_exp_f32_e32 v91, v0
	v_lshlrev_b32_e32 v0, 16, v89
	v_mul_f32_e32 v0, 0xbfb8aa3b, v0
	v_exp_f32_e32 v88, v0
	v_and_b32_e32 v0, 0xffff0000, v89
	v_mul_f32_e32 v0, 0xbfb8aa3b, v0
	v_pk_add_f32 v[90:91], v[90:91], 1.0 op_sel_hi:[1,0]
	v_exp_f32_e32 v89, v0
	v_div_scale_f32 v0, s[2:3], v91, v91, 1.0
	v_rcp_f32_e32 v92, v0
	v_pk_add_f32 v[88:89], v[88:89], 1.0 op_sel_hi:[1,0]
	v_fma_f32 v93, -v0, v92, 1.0
	v_fmac_f32_e32 v92, v93, v92
	v_div_scale_f32 v93, vcc, 1.0, v91, 1.0
	v_mul_f32_e32 v94, v93, v92
	v_fma_f32 v95, -v0, v94, v93
	v_fmac_f32_e32 v94, v95, v92
	v_fma_f32 v0, -v0, v94, v93
	v_div_fmas_f32 v0, v0, v92, v94
	v_div_fixup_f32 v91, v0, v91, 1.0
	v_div_scale_f32 v0, s[2:3], v90, v90, 1.0
	v_rcp_f32_e32 v92, v0
	s_nop 0
	v_fma_f32 v93, -v0, v92, 1.0
	v_fmac_f32_e32 v92, v93, v92
	v_div_scale_f32 v93, vcc, 1.0, v90, 1.0
	v_mul_f32_e32 v94, v93, v92
	v_fma_f32 v95, -v0, v94, v93
	v_fmac_f32_e32 v94, v95, v92
	v_fma_f32 v0, -v0, v94, v93
	v_div_fmas_f32 v0, v0, v92, v94
	v_div_fixup_f32 v90, v0, v90, 1.0
	v_div_scale_f32 v0, s[2:3], v89, v89, 1.0
	v_rcp_f32_e32 v92, v0
	v_pk_mul_f32 v[84:85], v[84:85], v[90:91]
	v_fma_f32 v93, -v0, v92, 1.0
	v_fmac_f32_e32 v92, v93, v92
	v_div_scale_f32 v93, vcc, 1.0, v89, 1.0
	v_mul_f32_e32 v94, v93, v92
	v_fma_f32 v95, -v0, v94, v93
	v_fmac_f32_e32 v94, v95, v92
	v_fma_f32 v0, -v0, v94, v93
	v_div_fmas_f32 v0, v0, v92, v94
	v_div_fixup_f32 v89, v0, v89, 1.0
	v_div_scale_f32 v0, s[2:3], v88, v88, 1.0
	v_rcp_f32_e32 v92, v0
	v_cvt_pk_bf16_f32 v84, v84, v85
	s_nop 0
	v_fma_f32 v93, -v0, v92, 1.0
	v_fmac_f32_e32 v92, v93, v92
	v_div_scale_f32 v93, vcc, 1.0, v88, 1.0
	v_mul_f32_e32 v94, v93, v92
	v_fma_f32 v95, -v0, v94, v93
	v_fmac_f32_e32 v94, v95, v92
	v_fma_f32 v0, -v0, v94, v93
	v_div_fmas_f32 v0, v0, v92, v94
	v_div_fixup_f32 v88, v0, v88, 1.0
	v_pk_mul_f32 v[86:87], v[86:87], v[88:89]
	s_nop 0
	v_cvt_pk_bf16_f32 v85, v86, v87
	global_store_dwordx2 v[96:97], v[84:85], off offset:288
	v_or_b32_e32 v84, 48, v140
	v_ashrrev_i32_e32 v85, 31, v84
	v_lshlrev_b64 v[86:87], 12, v[84:85]
	v_mad_i64_i32 v[84:85], s[2:3], v84, s78, v[142:143]
	v_lshl_add_u64 v[84:85], v[84:85], 0, s[24:25]
	v_lshl_add_u64 v[88:89], v[84:85], 0, v[2:3]
	s_waitcnt vmcnt(31)
	v_mov_b32_e32 v88, v188
	v_mov_b32_e32 v89, v189
	s_nop 0
	v_lshlrev_b32_e32 v0, 16, v88
	v_mul_f32_e32 v0, 0xbfb8aa3b, v0
	v_exp_f32_e32 v90, v0
	v_and_b32_e32 v0, 0xffff0000, v88
	v_mul_f32_e32 v0, 0xbfb8aa3b, v0
	v_exp_f32_e32 v91, v0
	v_lshlrev_b32_e32 v0, 16, v89
	v_mul_f32_e32 v0, 0xbfb8aa3b, v0
	v_exp_f32_e32 v88, v0
	v_and_b32_e32 v0, 0xffff0000, v89
	v_mul_f32_e32 v0, 0xbfb8aa3b, v0
	v_pk_add_f32 v[90:91], v[90:91], 1.0 op_sel_hi:[1,0]
	v_exp_f32_e32 v89, v0
	v_div_scale_f32 v0, s[2:3], v91, v91, 1.0
	v_rcp_f32_e32 v92, v0
	v_pk_add_f32 v[88:89], v[88:89], 1.0 op_sel_hi:[1,0]
	v_fma_f32 v93, -v0, v92, 1.0
	v_fmac_f32_e32 v92, v93, v92
	v_div_scale_f32 v93, vcc, 1.0, v91, 1.0
	v_mul_f32_e32 v94, v93, v92
	v_fma_f32 v95, -v0, v94, v93
	v_fmac_f32_e32 v94, v95, v92
	v_fma_f32 v0, -v0, v94, v93
	v_div_fmas_f32 v0, v0, v92, v94
	v_div_fixup_f32 v91, v0, v91, 1.0
	v_div_scale_f32 v0, s[2:3], v90, v90, 1.0
	v_rcp_f32_e32 v92, v0
	s_nop 0
	v_fma_f32 v93, -v0, v92, 1.0
	v_fmac_f32_e32 v92, v93, v92
	v_div_scale_f32 v93, vcc, 1.0, v90, 1.0
	v_mul_f32_e32 v94, v93, v92
	v_fma_f32 v95, -v0, v94, v93
	v_fmac_f32_e32 v94, v95, v92
	v_fma_f32 v0, -v0, v94, v93
	v_div_fmas_f32 v0, v0, v92, v94
	v_div_fixup_f32 v90, v0, v90, 1.0
	v_div_scale_f32 v0, s[2:3], v89, v89, 1.0
	v_rcp_f32_e32 v92, v0
	v_pk_mul_f32 v[80:81], v[80:81], v[90:91]
	v_fma_f32 v93, -v0, v92, 1.0
	v_fmac_f32_e32 v92, v93, v92
	v_div_scale_f32 v93, vcc, 1.0, v89, 1.0
	v_mul_f32_e32 v94, v93, v92
	v_fma_f32 v95, -v0, v94, v93
	v_fmac_f32_e32 v94, v95, v92
	v_fma_f32 v0, -v0, v94, v93
	v_div_fmas_f32 v0, v0, v92, v94
	v_div_fixup_f32 v89, v0, v89, 1.0
	v_div_scale_f32 v0, s[2:3], v88, v88, 1.0
	v_rcp_f32_e32 v92, v0
	s_nop 0
	v_fma_f32 v93, -v0, v92, 1.0
	v_fmac_f32_e32 v92, v93, v92
	v_div_scale_f32 v93, vcc, 1.0, v88, 1.0
	v_mul_f32_e32 v94, v93, v92
	v_fma_f32 v95, -v0, v94, v93
	v_fmac_f32_e32 v94, v95, v92
	v_fma_f32 v0, -v0, v94, v93
	v_div_fmas_f32 v0, v0, v92, v94
	v_div_fixup_f32 v88, v0, v88, 1.0
	v_pk_mul_f32 v[82:83], v[82:83], v[88:89]
	v_cvt_pk_bf16_f32 v88, v80, v81
	v_lshl_add_u64 v[80:81], s[48:49], 0, v[86:87]
	v_cvt_pk_bf16_f32 v89, v82, v83
	v_lshl_add_u64 v[82:83], v[84:85], 0, v[128:129]
	s_waitcnt vmcnt(30)
	v_mov_b32_e32 v82, v190
	v_mov_b32_e32 v83, v191
	v_lshl_add_u64 v[80:81], v[80:81], 0, v[2:3]
	global_store_dwordx2 v[80:81], v[88:89], off
	s_nop 0
	v_lshlrev_b32_e32 v0, 16, v82
	v_mul_f32_e32 v0, 0xbfb8aa3b, v0
	v_exp_f32_e32 v86, v0
	v_and_b32_e32 v0, 0xffff0000, v82
	v_mul_f32_e32 v0, 0xbfb8aa3b, v0
	v_exp_f32_e32 v87, v0
	v_lshlrev_b32_e32 v0, 16, v83
	v_mul_f32_e32 v0, 0xbfb8aa3b, v0
	v_exp_f32_e32 v82, v0
	v_and_b32_e32 v0, 0xffff0000, v83
	v_mul_f32_e32 v0, 0xbfb8aa3b, v0
	v_pk_add_f32 v[86:87], v[86:87], 1.0 op_sel_hi:[1,0]
	v_exp_f32_e32 v83, v0
	v_div_scale_f32 v0, s[2:3], v87, v87, 1.0
	v_rcp_f32_e32 v88, v0
	v_pk_add_f32 v[82:83], v[82:83], 1.0 op_sel_hi:[1,0]
	v_fma_f32 v89, -v0, v88, 1.0
	v_fmac_f32_e32 v88, v89, v88
	v_div_scale_f32 v89, vcc, 1.0, v87, 1.0
	v_mul_f32_e32 v90, v89, v88
	v_fma_f32 v91, -v0, v90, v89
	v_fmac_f32_e32 v90, v91, v88
	v_fma_f32 v0, -v0, v90, v89
	v_div_fmas_f32 v0, v0, v88, v90
	v_div_fixup_f32 v87, v0, v87, 1.0
	v_div_scale_f32 v0, s[2:3], v86, v86, 1.0
	v_rcp_f32_e32 v88, v0
	s_nop 0
	v_fma_f32 v89, -v0, v88, 1.0
	v_fmac_f32_e32 v88, v89, v88
	v_div_scale_f32 v89, vcc, 1.0, v86, 1.0
	v_mul_f32_e32 v90, v89, v88
	v_fma_f32 v91, -v0, v90, v89
	v_fmac_f32_e32 v90, v91, v88
	v_fma_f32 v0, -v0, v90, v89
	v_div_fmas_f32 v0, v0, v88, v90
	v_div_fixup_f32 v86, v0, v86, 1.0
	v_div_scale_f32 v0, s[2:3], v83, v83, 1.0
	v_rcp_f32_e32 v88, v0
	v_pk_mul_f32 v[76:77], v[76:77], v[86:87]
	v_fma_f32 v89, -v0, v88, 1.0
	v_fmac_f32_e32 v88, v89, v88
	v_div_scale_f32 v89, vcc, 1.0, v83, 1.0
	v_mul_f32_e32 v90, v89, v88
	v_fma_f32 v91, -v0, v90, v89
	v_fmac_f32_e32 v90, v91, v88
	v_fma_f32 v0, -v0, v90, v89
	v_div_fmas_f32 v0, v0, v88, v90
	v_div_fixup_f32 v83, v0, v83, 1.0
	v_div_scale_f32 v0, s[2:3], v82, v82, 1.0
	v_rcp_f32_e32 v88, v0
	v_cvt_pk_bf16_f32 v76, v76, v77
	s_nop 0
	v_fma_f32 v89, -v0, v88, 1.0
	v_fmac_f32_e32 v88, v89, v88
	v_div_scale_f32 v89, vcc, 1.0, v82, 1.0
	v_mul_f32_e32 v90, v89, v88
	v_fma_f32 v91, -v0, v90, v89
	v_fmac_f32_e32 v90, v91, v88
	v_fma_f32 v0, -v0, v90, v89
	v_div_fmas_f32 v0, v0, v88, v90
	v_div_fixup_f32 v82, v0, v82, 1.0
	v_pk_mul_f32 v[78:79], v[78:79], v[82:83]
	s_nop 0
	v_cvt_pk_bf16_f32 v77, v78, v79
	global_store_dwordx2 v[80:81], v[76:77], off offset:32
	v_lshl_add_u64 v[76:77], v[84:85], 0, v[124:125]
	s_waitcnt vmcnt(31)
	v_mov_b32_e32 v76, v192
	v_mov_b32_e32 v77, v193
	s_nop 0
	v_lshlrev_b32_e32 v0, 16, v76
	v_mul_f32_e32 v0, 0xbfb8aa3b, v0
	v_exp_f32_e32 v78, v0
	v_and_b32_e32 v0, 0xffff0000, v76
	v_mul_f32_e32 v0, 0xbfb8aa3b, v0
	v_exp_f32_e32 v79, v0
	v_lshlrev_b32_e32 v0, 16, v77
	v_mul_f32_e32 v0, 0xbfb8aa3b, v0
	v_exp_f32_e32 v76, v0
	v_and_b32_e32 v0, 0xffff0000, v77
	v_mul_f32_e32 v0, 0xbfb8aa3b, v0
	v_pk_add_f32 v[78:79], v[78:79], 1.0 op_sel_hi:[1,0]
	v_exp_f32_e32 v77, v0
	v_div_scale_f32 v0, s[2:3], v79, v79, 1.0
	v_rcp_f32_e32 v82, v0
	v_pk_add_f32 v[76:77], v[76:77], 1.0 op_sel_hi:[1,0]
	v_fma_f32 v83, -v0, v82, 1.0
	v_fmac_f32_e32 v82, v83, v82
	v_div_scale_f32 v83, vcc, 1.0, v79, 1.0
	v_mul_f32_e32 v86, v83, v82
	v_fma_f32 v87, -v0, v86, v83
	v_fmac_f32_e32 v86, v87, v82
	v_fma_f32 v0, -v0, v86, v83
	v_div_fmas_f32 v0, v0, v82, v86
	v_div_fixup_f32 v79, v0, v79, 1.0
	v_div_scale_f32 v0, s[2:3], v78, v78, 1.0
	v_rcp_f32_e32 v82, v0
	s_nop 0
	v_fma_f32 v83, -v0, v82, 1.0
	v_fmac_f32_e32 v82, v83, v82
	v_div_scale_f32 v83, vcc, 1.0, v78, 1.0
	v_mul_f32_e32 v86, v83, v82
	v_fma_f32 v87, -v0, v86, v83
	v_fmac_f32_e32 v86, v87, v82
	v_fma_f32 v0, -v0, v86, v83
	v_div_fmas_f32 v0, v0, v82, v86
	v_div_fixup_f32 v78, v0, v78, 1.0
	v_div_scale_f32 v0, s[2:3], v77, v77, 1.0
	v_rcp_f32_e32 v82, v0
	v_pk_mul_f32 v[72:73], v[72:73], v[78:79]
	v_fma_f32 v83, -v0, v82, 1.0
	v_fmac_f32_e32 v82, v83, v82
	v_div_scale_f32 v83, vcc, 1.0, v77, 1.0
	v_mul_f32_e32 v86, v83, v82
	v_fma_f32 v87, -v0, v86, v83
	v_fmac_f32_e32 v86, v87, v82
	v_fma_f32 v0, -v0, v86, v83
	v_div_fmas_f32 v0, v0, v82, v86
	v_div_fixup_f32 v77, v0, v77, 1.0
	v_div_scale_f32 v0, s[2:3], v76, v76, 1.0
	v_rcp_f32_e32 v82, v0
	v_cvt_pk_bf16_f32 v72, v72, v73
	s_nop 0
	v_fma_f32 v83, -v0, v82, 1.0
	v_fmac_f32_e32 v82, v83, v82
	v_div_scale_f32 v83, vcc, 1.0, v76, 1.0
	v_mul_f32_e32 v86, v83, v82
	v_fma_f32 v87, -v0, v86, v83
	v_fmac_f32_e32 v86, v87, v82
	v_fma_f32 v0, -v0, v86, v83
	v_div_fmas_f32 v0, v0, v82, v86
	v_div_fixup_f32 v76, v0, v76, 1.0
	v_pk_mul_f32 v[74:75], v[74:75], v[76:77]
	s_nop 0
	v_cvt_pk_bf16_f32 v73, v74, v75
	global_store_dwordx2 v[80:81], v[72:73], off offset:256
	v_lshl_add_u64 v[72:73], v[84:85], 0, v[120:121]
	s_waitcnt vmcnt(31)
	v_mov_b32_e32 v72, v194
	v_mov_b32_e32 v73, v195
	s_nop 0
	v_lshlrev_b32_e32 v0, 16, v72
	v_mul_f32_e32 v0, 0xbfb8aa3b, v0
	v_exp_f32_e32 v74, v0
	v_and_b32_e32 v0, 0xffff0000, v72
	v_mul_f32_e32 v0, 0xbfb8aa3b, v0
	v_exp_f32_e32 v75, v0
	v_lshlrev_b32_e32 v0, 16, v73
	v_mul_f32_e32 v0, 0xbfb8aa3b, v0
	v_exp_f32_e32 v72, v0
	v_and_b32_e32 v0, 0xffff0000, v73
	v_mul_f32_e32 v0, 0xbfb8aa3b, v0
	v_pk_add_f32 v[74:75], v[74:75], 1.0 op_sel_hi:[1,0]
	v_exp_f32_e32 v73, v0
	v_div_scale_f32 v0, s[2:3], v75, v75, 1.0
	v_rcp_f32_e32 v76, v0
	v_pk_add_f32 v[72:73], v[72:73], 1.0 op_sel_hi:[1,0]
	v_fma_f32 v77, -v0, v76, 1.0
	v_fmac_f32_e32 v76, v77, v76
	v_div_scale_f32 v77, vcc, 1.0, v75, 1.0
	v_mul_f32_e32 v78, v77, v76
	v_fma_f32 v79, -v0, v78, v77
	v_fmac_f32_e32 v78, v79, v76
	v_fma_f32 v0, -v0, v78, v77
	v_div_fmas_f32 v0, v0, v76, v78
	v_div_fixup_f32 v75, v0, v75, 1.0
	v_div_scale_f32 v0, s[2:3], v74, v74, 1.0
	v_rcp_f32_e32 v76, v0
	s_nop 0
	v_fma_f32 v77, -v0, v76, 1.0
	v_fmac_f32_e32 v76, v77, v76
	v_div_scale_f32 v77, vcc, 1.0, v74, 1.0
	v_mul_f32_e32 v78, v77, v76
	v_fma_f32 v79, -v0, v78, v77
	v_fmac_f32_e32 v78, v79, v76
	v_fma_f32 v0, -v0, v78, v77
	v_div_fmas_f32 v0, v0, v76, v78
	v_div_fixup_f32 v74, v0, v74, 1.0
	v_div_scale_f32 v0, s[2:3], v73, v73, 1.0
	v_rcp_f32_e32 v76, v0
	v_pk_mul_f32 v[68:69], v[68:69], v[74:75]
	v_fma_f32 v77, -v0, v76, 1.0
	v_fmac_f32_e32 v76, v77, v76
	v_div_scale_f32 v77, vcc, 1.0, v73, 1.0
	v_mul_f32_e32 v78, v77, v76
	v_fma_f32 v79, -v0, v78, v77
	v_fmac_f32_e32 v78, v79, v76
	v_fma_f32 v0, -v0, v78, v77
	v_div_fmas_f32 v0, v0, v76, v78
	v_div_fixup_f32 v73, v0, v73, 1.0
	v_div_scale_f32 v0, s[2:3], v72, v72, 1.0
	v_rcp_f32_e32 v76, v0
	v_cvt_pk_bf16_f32 v68, v68, v69
	s_nop 0
	v_fma_f32 v77, -v0, v76, 1.0
	v_fmac_f32_e32 v76, v77, v76
	v_div_scale_f32 v77, vcc, 1.0, v72, 1.0
	v_mul_f32_e32 v78, v77, v76
	v_fma_f32 v79, -v0, v78, v77
	v_fmac_f32_e32 v78, v79, v76
	v_fma_f32 v0, -v0, v78, v77
	v_div_fmas_f32 v0, v0, v76, v78
	v_div_fixup_f32 v72, v0, v72, 1.0
	v_pk_mul_f32 v[70:71], v[70:71], v[72:73]
	s_nop 0
	v_cvt_pk_bf16_f32 v69, v70, v71
	global_store_dwordx2 v[80:81], v[68:69], off offset:288
	v_add_u32_e32 v68, 0x80, v140
	v_ashrrev_i32_e32 v69, 31, v68
	v_lshlrev_b64 v[70:71], 12, v[68:69]
	v_mad_i64_i32 v[68:69], s[2:3], v68, s78, v[142:143]
	v_lshl_add_u64 v[68:69], v[68:69], 0, s[24:25]
	v_lshl_add_u64 v[72:73], v[68:69], 0, v[2:3]
	s_waitcnt vmcnt(31)
	v_mov_b32_e32 v72, v196
	v_mov_b32_e32 v73, v197
	s_nop 0
	v_lshlrev_b32_e32 v0, 16, v72
	v_mul_f32_e32 v0, 0xbfb8aa3b, v0
	v_exp_f32_e32 v74, v0
	v_and_b32_e32 v0, 0xffff0000, v72
	v_mul_f32_e32 v0, 0xbfb8aa3b, v0
	v_exp_f32_e32 v75, v0
	v_lshlrev_b32_e32 v0, 16, v73
	v_mul_f32_e32 v0, 0xbfb8aa3b, v0
	v_exp_f32_e32 v72, v0
	v_and_b32_e32 v0, 0xffff0000, v73
	v_mul_f32_e32 v0, 0xbfb8aa3b, v0
	v_pk_add_f32 v[74:75], v[74:75], 1.0 op_sel_hi:[1,0]
	v_exp_f32_e32 v73, v0
	v_div_scale_f32 v0, s[2:3], v75, v75, 1.0
	v_rcp_f32_e32 v76, v0
	v_pk_add_f32 v[72:73], v[72:73], 1.0 op_sel_hi:[1,0]
	v_fma_f32 v77, -v0, v76, 1.0
	v_fmac_f32_e32 v76, v77, v76
	v_div_scale_f32 v77, vcc, 1.0, v75, 1.0
	v_mul_f32_e32 v78, v77, v76
	v_fma_f32 v79, -v0, v78, v77
	v_fmac_f32_e32 v78, v79, v76
	v_fma_f32 v0, -v0, v78, v77
	v_div_fmas_f32 v0, v0, v76, v78
	v_div_fixup_f32 v75, v0, v75, 1.0
	v_div_scale_f32 v0, s[2:3], v74, v74, 1.0
	v_rcp_f32_e32 v76, v0
	s_nop 0
	v_fma_f32 v77, -v0, v76, 1.0
	v_fmac_f32_e32 v76, v77, v76
	v_div_scale_f32 v77, vcc, 1.0, v74, 1.0
	v_mul_f32_e32 v78, v77, v76
	v_fma_f32 v79, -v0, v78, v77
	v_fmac_f32_e32 v78, v79, v76
	v_fma_f32 v0, -v0, v78, v77
	v_div_fmas_f32 v0, v0, v76, v78
	v_div_fixup_f32 v74, v0, v74, 1.0
	v_div_scale_f32 v0, s[2:3], v73, v73, 1.0
	v_rcp_f32_e32 v76, v0
	v_pk_mul_f32 v[64:65], v[64:65], v[74:75]
	v_fma_f32 v77, -v0, v76, 1.0
	v_fmac_f32_e32 v76, v77, v76
	v_div_scale_f32 v77, vcc, 1.0, v73, 1.0
	v_mul_f32_e32 v78, v77, v76
	v_fma_f32 v79, -v0, v78, v77
	v_fmac_f32_e32 v78, v79, v76
	v_fma_f32 v0, -v0, v78, v77
	v_div_fmas_f32 v0, v0, v76, v78
	v_div_fixup_f32 v73, v0, v73, 1.0
	v_div_scale_f32 v0, s[2:3], v72, v72, 1.0
	v_rcp_f32_e32 v76, v0
	s_nop 0
	v_fma_f32 v77, -v0, v76, 1.0
	v_fmac_f32_e32 v76, v77, v76
	v_div_scale_f32 v77, vcc, 1.0, v72, 1.0
	v_mul_f32_e32 v78, v77, v76
	v_fma_f32 v79, -v0, v78, v77
	v_fmac_f32_e32 v78, v79, v76
	v_fma_f32 v0, -v0, v78, v77
	v_div_fmas_f32 v0, v0, v76, v78
	v_div_fixup_f32 v72, v0, v72, 1.0
	v_pk_mul_f32 v[66:67], v[66:67], v[72:73]
	v_cvt_pk_bf16_f32 v72, v64, v65
	v_lshl_add_u64 v[64:65], s[48:49], 0, v[70:71]
	v_cvt_pk_bf16_f32 v73, v66, v67
	v_lshl_add_u64 v[66:67], v[68:69], 0, v[128:129]
	s_waitcnt vmcnt(30)
	v_mov_b32_e32 v66, v198
	v_mov_b32_e32 v67, v199
	v_lshl_add_u64 v[64:65], v[64:65], 0, v[2:3]
	global_store_dwordx2 v[64:65], v[72:73], off
	s_nop 0
	v_lshlrev_b32_e32 v0, 16, v66
	v_mul_f32_e32 v0, 0xbfb8aa3b, v0
	v_exp_f32_e32 v70, v0
	v_and_b32_e32 v0, 0xffff0000, v66
	v_mul_f32_e32 v0, 0xbfb8aa3b, v0
	v_exp_f32_e32 v71, v0
	v_lshlrev_b32_e32 v0, 16, v67
	v_mul_f32_e32 v0, 0xbfb8aa3b, v0
	v_exp_f32_e32 v66, v0
	v_and_b32_e32 v0, 0xffff0000, v67
	v_mul_f32_e32 v0, 0xbfb8aa3b, v0
	v_pk_add_f32 v[70:71], v[70:71], 1.0 op_sel_hi:[1,0]
	v_exp_f32_e32 v67, v0
	v_div_scale_f32 v0, s[2:3], v71, v71, 1.0
	v_rcp_f32_e32 v72, v0
	v_pk_add_f32 v[66:67], v[66:67], 1.0 op_sel_hi:[1,0]
	v_fma_f32 v73, -v0, v72, 1.0
	v_fmac_f32_e32 v72, v73, v72
	v_div_scale_f32 v73, vcc, 1.0, v71, 1.0
	v_mul_f32_e32 v74, v73, v72
	v_fma_f32 v75, -v0, v74, v73
	v_fmac_f32_e32 v74, v75, v72
	v_fma_f32 v0, -v0, v74, v73
	v_div_fmas_f32 v0, v0, v72, v74
	v_div_fixup_f32 v71, v0, v71, 1.0
	v_div_scale_f32 v0, s[2:3], v70, v70, 1.0
	v_rcp_f32_e32 v72, v0
	s_nop 0
	v_fma_f32 v73, -v0, v72, 1.0
	v_fmac_f32_e32 v72, v73, v72
	v_div_scale_f32 v73, vcc, 1.0, v70, 1.0
	v_mul_f32_e32 v74, v73, v72
	v_fma_f32 v75, -v0, v74, v73
	v_fmac_f32_e32 v74, v75, v72
	v_fma_f32 v0, -v0, v74, v73
	v_div_fmas_f32 v0, v0, v72, v74
	v_div_fixup_f32 v70, v0, v70, 1.0
	v_div_scale_f32 v0, s[2:3], v67, v67, 1.0
	v_rcp_f32_e32 v72, v0
	v_pk_mul_f32 v[60:61], v[60:61], v[70:71]
	v_fma_f32 v73, -v0, v72, 1.0
	v_fmac_f32_e32 v72, v73, v72
	v_div_scale_f32 v73, vcc, 1.0, v67, 1.0
	v_mul_f32_e32 v74, v73, v72
	v_fma_f32 v75, -v0, v74, v73
	v_fmac_f32_e32 v74, v75, v72
	v_fma_f32 v0, -v0, v74, v73
	v_div_fmas_f32 v0, v0, v72, v74
	v_div_fixup_f32 v67, v0, v67, 1.0
	v_div_scale_f32 v0, s[2:3], v66, v66, 1.0
	v_rcp_f32_e32 v72, v0
	v_cvt_pk_bf16_f32 v60, v60, v61
	s_nop 0
	v_fma_f32 v73, -v0, v72, 1.0
	v_fmac_f32_e32 v72, v73, v72
	v_div_scale_f32 v73, vcc, 1.0, v66, 1.0
	v_mul_f32_e32 v74, v73, v72
	v_fma_f32 v75, -v0, v74, v73
	v_fmac_f32_e32 v74, v75, v72
	v_fma_f32 v0, -v0, v74, v73
	v_div_fmas_f32 v0, v0, v72, v74
	v_div_fixup_f32 v66, v0, v66, 1.0
	v_pk_mul_f32 v[62:63], v[62:63], v[66:67]
	s_nop 0
	v_cvt_pk_bf16_f32 v61, v62, v63
	global_store_dwordx2 v[64:65], v[60:61], off offset:32
	v_lshl_add_u64 v[60:61], v[68:69], 0, v[124:125]
	s_waitcnt vmcnt(31)
	v_mov_b32_e32 v60, v200
	v_mov_b32_e32 v61, v201
	s_nop 0
	v_lshlrev_b32_e32 v0, 16, v60
	v_mul_f32_e32 v0, 0xbfb8aa3b, v0
	v_exp_f32_e32 v62, v0
	v_and_b32_e32 v0, 0xffff0000, v60
	v_mul_f32_e32 v0, 0xbfb8aa3b, v0
	v_exp_f32_e32 v63, v0
	v_lshlrev_b32_e32 v0, 16, v61
	v_mul_f32_e32 v0, 0xbfb8aa3b, v0
	v_exp_f32_e32 v60, v0
	v_and_b32_e32 v0, 0xffff0000, v61
	v_mul_f32_e32 v0, 0xbfb8aa3b, v0
	v_pk_add_f32 v[62:63], v[62:63], 1.0 op_sel_hi:[1,0]
	v_exp_f32_e32 v61, v0
	v_div_scale_f32 v0, s[2:3], v63, v63, 1.0
	v_rcp_f32_e32 v66, v0
	v_pk_add_f32 v[60:61], v[60:61], 1.0 op_sel_hi:[1,0]
	v_fma_f32 v67, -v0, v66, 1.0
	v_fmac_f32_e32 v66, v67, v66
	v_div_scale_f32 v67, vcc, 1.0, v63, 1.0
	v_mul_f32_e32 v70, v67, v66
	v_fma_f32 v71, -v0, v70, v67
	v_fmac_f32_e32 v70, v71, v66
	v_fma_f32 v0, -v0, v70, v67
	v_div_fmas_f32 v0, v0, v66, v70
	v_div_fixup_f32 v63, v0, v63, 1.0
	v_div_scale_f32 v0, s[2:3], v62, v62, 1.0
	v_rcp_f32_e32 v66, v0
	s_nop 0
	v_fma_f32 v67, -v0, v66, 1.0
	v_fmac_f32_e32 v66, v67, v66
	v_div_scale_f32 v67, vcc, 1.0, v62, 1.0
	v_mul_f32_e32 v70, v67, v66
	v_fma_f32 v71, -v0, v70, v67
	v_fmac_f32_e32 v70, v71, v66
	v_fma_f32 v0, -v0, v70, v67
	v_div_fmas_f32 v0, v0, v66, v70
	v_div_fixup_f32 v62, v0, v62, 1.0
	v_div_scale_f32 v0, s[2:3], v61, v61, 1.0
	v_rcp_f32_e32 v66, v0
	v_pk_mul_f32 v[56:57], v[56:57], v[62:63]
	v_fma_f32 v67, -v0, v66, 1.0
	v_fmac_f32_e32 v66, v67, v66
	v_div_scale_f32 v67, vcc, 1.0, v61, 1.0
	v_mul_f32_e32 v70, v67, v66
	v_fma_f32 v71, -v0, v70, v67
	v_fmac_f32_e32 v70, v71, v66
	v_fma_f32 v0, -v0, v70, v67
	v_div_fmas_f32 v0, v0, v66, v70
	v_div_fixup_f32 v61, v0, v61, 1.0
	v_div_scale_f32 v0, s[2:3], v60, v60, 1.0
	v_rcp_f32_e32 v66, v0
	v_cvt_pk_bf16_f32 v56, v56, v57
	s_nop 0
	v_fma_f32 v67, -v0, v66, 1.0
	v_fmac_f32_e32 v66, v67, v66
	v_div_scale_f32 v67, vcc, 1.0, v60, 1.0
	v_mul_f32_e32 v70, v67, v66
	v_fma_f32 v71, -v0, v70, v67
	v_fmac_f32_e32 v70, v71, v66
	v_fma_f32 v0, -v0, v70, v67
	v_div_fmas_f32 v0, v0, v66, v70
	v_div_fixup_f32 v60, v0, v60, 1.0
	v_pk_mul_f32 v[58:59], v[58:59], v[60:61]
	s_nop 0
	v_cvt_pk_bf16_f32 v57, v58, v59
	global_store_dwordx2 v[64:65], v[56:57], off offset:256
	v_lshl_add_u64 v[56:57], v[68:69], 0, v[120:121]
	s_waitcnt vmcnt(31)
	v_mov_b32_e32 v56, v202
	v_mov_b32_e32 v57, v203
	s_nop 0
	v_lshlrev_b32_e32 v0, 16, v56
	v_mul_f32_e32 v0, 0xbfb8aa3b, v0
	v_exp_f32_e32 v58, v0
	v_and_b32_e32 v0, 0xffff0000, v56
	v_mul_f32_e32 v0, 0xbfb8aa3b, v0
	v_exp_f32_e32 v59, v0
	v_lshlrev_b32_e32 v0, 16, v57
	v_mul_f32_e32 v0, 0xbfb8aa3b, v0
	v_exp_f32_e32 v56, v0
	v_and_b32_e32 v0, 0xffff0000, v57
	v_mul_f32_e32 v0, 0xbfb8aa3b, v0
	v_pk_add_f32 v[58:59], v[58:59], 1.0 op_sel_hi:[1,0]
	v_exp_f32_e32 v57, v0
	v_div_scale_f32 v0, s[2:3], v59, v59, 1.0
	v_rcp_f32_e32 v60, v0
	v_pk_add_f32 v[56:57], v[56:57], 1.0 op_sel_hi:[1,0]
	v_fma_f32 v61, -v0, v60, 1.0
	v_fmac_f32_e32 v60, v61, v60
	v_div_scale_f32 v61, vcc, 1.0, v59, 1.0
	v_mul_f32_e32 v62, v61, v60
	v_fma_f32 v63, -v0, v62, v61
	v_fmac_f32_e32 v62, v63, v60
	v_fma_f32 v0, -v0, v62, v61
	v_div_fmas_f32 v0, v0, v60, v62
	v_div_fixup_f32 v59, v0, v59, 1.0
	v_div_scale_f32 v0, s[2:3], v58, v58, 1.0
	v_rcp_f32_e32 v60, v0
	s_nop 0
	v_fma_f32 v61, -v0, v60, 1.0
	v_fmac_f32_e32 v60, v61, v60
	v_div_scale_f32 v61, vcc, 1.0, v58, 1.0
	v_mul_f32_e32 v62, v61, v60
	v_fma_f32 v63, -v0, v62, v61
	v_fmac_f32_e32 v62, v63, v60
	v_fma_f32 v0, -v0, v62, v61
	v_div_fmas_f32 v0, v0, v60, v62
	v_div_fixup_f32 v58, v0, v58, 1.0
	v_div_scale_f32 v0, s[2:3], v57, v57, 1.0
	v_rcp_f32_e32 v60, v0
	v_pk_mul_f32 v[52:53], v[52:53], v[58:59]
	v_fma_f32 v61, -v0, v60, 1.0
	v_fmac_f32_e32 v60, v61, v60
	v_div_scale_f32 v61, vcc, 1.0, v57, 1.0
	v_mul_f32_e32 v62, v61, v60
	v_fma_f32 v63, -v0, v62, v61
	v_fmac_f32_e32 v62, v63, v60
	v_fma_f32 v0, -v0, v62, v61
	v_div_fmas_f32 v0, v0, v60, v62
	v_div_fixup_f32 v57, v0, v57, 1.0
	v_div_scale_f32 v0, s[2:3], v56, v56, 1.0
	v_rcp_f32_e32 v60, v0
	v_cvt_pk_bf16_f32 v52, v52, v53
	s_nop 0
	v_fma_f32 v61, -v0, v60, 1.0
	v_fmac_f32_e32 v60, v61, v60
	v_div_scale_f32 v61, vcc, 1.0, v56, 1.0
	v_mul_f32_e32 v62, v61, v60
	v_fma_f32 v63, -v0, v62, v61
	v_fmac_f32_e32 v62, v63, v60
	v_fma_f32 v0, -v0, v62, v61
	v_div_fmas_f32 v0, v0, v60, v62
	v_div_fixup_f32 v56, v0, v56, 1.0
	v_pk_mul_f32 v[54:55], v[54:55], v[56:57]
	s_nop 0
	v_cvt_pk_bf16_f32 v53, v54, v55
	global_store_dwordx2 v[64:65], v[52:53], off offset:288
	v_add_u32_e32 v52, 0x90, v140
	v_ashrrev_i32_e32 v53, 31, v52
	v_lshlrev_b64 v[54:55], 12, v[52:53]
	v_mad_i64_i32 v[52:53], s[2:3], v52, s78, v[142:143]
	v_lshl_add_u64 v[52:53], v[52:53], 0, s[24:25]
	v_lshl_add_u64 v[56:57], v[52:53], 0, v[2:3]
	s_waitcnt vmcnt(31)
	v_mov_b32_e32 v56, v204
	v_mov_b32_e32 v57, v205
	s_nop 0
	v_lshlrev_b32_e32 v0, 16, v56
	v_mul_f32_e32 v0, 0xbfb8aa3b, v0
	v_exp_f32_e32 v58, v0
	v_and_b32_e32 v0, 0xffff0000, v56
	v_mul_f32_e32 v0, 0xbfb8aa3b, v0
	v_exp_f32_e32 v59, v0
	v_lshlrev_b32_e32 v0, 16, v57
	v_mul_f32_e32 v0, 0xbfb8aa3b, v0
	v_exp_f32_e32 v56, v0
	v_and_b32_e32 v0, 0xffff0000, v57
	v_mul_f32_e32 v0, 0xbfb8aa3b, v0
	v_pk_add_f32 v[58:59], v[58:59], 1.0 op_sel_hi:[1,0]
	v_exp_f32_e32 v57, v0
	v_div_scale_f32 v0, s[2:3], v59, v59, 1.0
	v_rcp_f32_e32 v60, v0
	v_pk_add_f32 v[56:57], v[56:57], 1.0 op_sel_hi:[1,0]
	v_fma_f32 v61, -v0, v60, 1.0
	v_fmac_f32_e32 v60, v61, v60
	v_div_scale_f32 v61, vcc, 1.0, v59, 1.0
	v_mul_f32_e32 v62, v61, v60
	v_fma_f32 v63, -v0, v62, v61
	v_fmac_f32_e32 v62, v63, v60
	v_fma_f32 v0, -v0, v62, v61
	v_div_fmas_f32 v0, v0, v60, v62
	v_div_fixup_f32 v59, v0, v59, 1.0
	v_div_scale_f32 v0, s[2:3], v58, v58, 1.0
	v_rcp_f32_e32 v60, v0
	s_nop 0
	v_fma_f32 v61, -v0, v60, 1.0
	v_fmac_f32_e32 v60, v61, v60
	v_div_scale_f32 v61, vcc, 1.0, v58, 1.0
	v_mul_f32_e32 v62, v61, v60
	v_fma_f32 v63, -v0, v62, v61
	v_fmac_f32_e32 v62, v63, v60
	v_fma_f32 v0, -v0, v62, v61
	v_div_fmas_f32 v0, v0, v60, v62
	v_div_fixup_f32 v58, v0, v58, 1.0
	v_div_scale_f32 v0, s[2:3], v57, v57, 1.0
	v_rcp_f32_e32 v60, v0
	v_pk_mul_f32 v[48:49], v[48:49], v[58:59]
	v_fma_f32 v61, -v0, v60, 1.0
	v_fmac_f32_e32 v60, v61, v60
	v_div_scale_f32 v61, vcc, 1.0, v57, 1.0
	v_mul_f32_e32 v62, v61, v60
	v_fma_f32 v63, -v0, v62, v61
	v_fmac_f32_e32 v62, v63, v60
	v_fma_f32 v0, -v0, v62, v61
	v_div_fmas_f32 v0, v0, v60, v62
	v_div_fixup_f32 v57, v0, v57, 1.0
	v_div_scale_f32 v0, s[2:3], v56, v56, 1.0
	v_rcp_f32_e32 v60, v0
	s_nop 0
	v_fma_f32 v61, -v0, v60, 1.0
	v_fmac_f32_e32 v60, v61, v60
	v_div_scale_f32 v61, vcc, 1.0, v56, 1.0
	v_mul_f32_e32 v62, v61, v60
	v_fma_f32 v63, -v0, v62, v61
	v_fmac_f32_e32 v62, v63, v60
	v_fma_f32 v0, -v0, v62, v61
	v_div_fmas_f32 v0, v0, v60, v62
	v_div_fixup_f32 v56, v0, v56, 1.0
	v_pk_mul_f32 v[50:51], v[50:51], v[56:57]
	v_cvt_pk_bf16_f32 v56, v48, v49
	v_lshl_add_u64 v[48:49], s[48:49], 0, v[54:55]
	v_cvt_pk_bf16_f32 v57, v50, v51
	v_lshl_add_u64 v[50:51], v[52:53], 0, v[128:129]
	s_waitcnt vmcnt(30)
	v_mov_b32_e32 v50, v206
	v_mov_b32_e32 v51, v207
	v_lshl_add_u64 v[48:49], v[48:49], 0, v[2:3]
	global_store_dwordx2 v[48:49], v[56:57], off
	s_nop 0
	v_lshlrev_b32_e32 v0, 16, v50
	v_mul_f32_e32 v0, 0xbfb8aa3b, v0
	v_exp_f32_e32 v54, v0
	v_and_b32_e32 v0, 0xffff0000, v50
	v_mul_f32_e32 v0, 0xbfb8aa3b, v0
	v_exp_f32_e32 v55, v0
	v_lshlrev_b32_e32 v0, 16, v51
	v_mul_f32_e32 v0, 0xbfb8aa3b, v0
	v_exp_f32_e32 v50, v0
	v_and_b32_e32 v0, 0xffff0000, v51
	v_mul_f32_e32 v0, 0xbfb8aa3b, v0
	v_pk_add_f32 v[54:55], v[54:55], 1.0 op_sel_hi:[1,0]
	v_exp_f32_e32 v51, v0
	v_div_scale_f32 v0, s[2:3], v55, v55, 1.0
	v_rcp_f32_e32 v56, v0
	v_pk_add_f32 v[50:51], v[50:51], 1.0 op_sel_hi:[1,0]
	v_fma_f32 v57, -v0, v56, 1.0
	v_fmac_f32_e32 v56, v57, v56
	v_div_scale_f32 v57, vcc, 1.0, v55, 1.0
	v_mul_f32_e32 v58, v57, v56
	v_fma_f32 v59, -v0, v58, v57
	v_fmac_f32_e32 v58, v59, v56
	v_fma_f32 v0, -v0, v58, v57
	v_div_fmas_f32 v0, v0, v56, v58
	v_div_fixup_f32 v55, v0, v55, 1.0
	v_div_scale_f32 v0, s[2:3], v54, v54, 1.0
	v_rcp_f32_e32 v56, v0
	s_nop 0
	v_fma_f32 v57, -v0, v56, 1.0
	v_fmac_f32_e32 v56, v57, v56
	v_div_scale_f32 v57, vcc, 1.0, v54, 1.0
	v_mul_f32_e32 v58, v57, v56
	v_fma_f32 v59, -v0, v58, v57
	v_fmac_f32_e32 v58, v59, v56
	v_fma_f32 v0, -v0, v58, v57
	v_div_fmas_f32 v0, v0, v56, v58
	v_div_fixup_f32 v54, v0, v54, 1.0
	v_div_scale_f32 v0, s[2:3], v51, v51, 1.0
	v_rcp_f32_e32 v56, v0
	v_pk_mul_f32 v[44:45], v[44:45], v[54:55]
	v_fma_f32 v57, -v0, v56, 1.0
	v_fmac_f32_e32 v56, v57, v56
	v_div_scale_f32 v57, vcc, 1.0, v51, 1.0
	v_mul_f32_e32 v58, v57, v56
	v_fma_f32 v59, -v0, v58, v57
	v_fmac_f32_e32 v58, v59, v56
	v_fma_f32 v0, -v0, v58, v57
	v_div_fmas_f32 v0, v0, v56, v58
	v_div_fixup_f32 v51, v0, v51, 1.0
	v_div_scale_f32 v0, s[2:3], v50, v50, 1.0
	v_rcp_f32_e32 v56, v0
	v_cvt_pk_bf16_f32 v44, v44, v45
	s_nop 0
	v_fma_f32 v57, -v0, v56, 1.0
	v_fmac_f32_e32 v56, v57, v56
	v_div_scale_f32 v57, vcc, 1.0, v50, 1.0
	v_mul_f32_e32 v58, v57, v56
	v_fma_f32 v59, -v0, v58, v57
	v_fmac_f32_e32 v58, v59, v56
	v_fma_f32 v0, -v0, v58, v57
	v_div_fmas_f32 v0, v0, v56, v58
	v_div_fixup_f32 v50, v0, v50, 1.0
	v_pk_mul_f32 v[46:47], v[46:47], v[50:51]
	s_nop 0
	v_cvt_pk_bf16_f32 v45, v46, v47
	global_store_dwordx2 v[48:49], v[44:45], off offset:32
	v_lshl_add_u64 v[44:45], v[52:53], 0, v[124:125]
	s_waitcnt vmcnt(31)
	v_mov_b32_e32 v44, v208
	v_mov_b32_e32 v45, v209
	s_nop 0
	v_lshlrev_b32_e32 v0, 16, v44
	v_mul_f32_e32 v0, 0xbfb8aa3b, v0
	v_exp_f32_e32 v46, v0
	v_and_b32_e32 v0, 0xffff0000, v44
	v_mul_f32_e32 v0, 0xbfb8aa3b, v0
	v_exp_f32_e32 v47, v0
	v_lshlrev_b32_e32 v0, 16, v45
	v_mul_f32_e32 v0, 0xbfb8aa3b, v0
	v_exp_f32_e32 v44, v0
	v_and_b32_e32 v0, 0xffff0000, v45
	v_mul_f32_e32 v0, 0xbfb8aa3b, v0
	v_pk_add_f32 v[46:47], v[46:47], 1.0 op_sel_hi:[1,0]
	v_exp_f32_e32 v45, v0
	v_div_scale_f32 v0, s[2:3], v47, v47, 1.0
	v_rcp_f32_e32 v50, v0
	v_pk_add_f32 v[44:45], v[44:45], 1.0 op_sel_hi:[1,0]
	v_fma_f32 v51, -v0, v50, 1.0
	v_fmac_f32_e32 v50, v51, v50
	v_div_scale_f32 v51, vcc, 1.0, v47, 1.0
	v_mul_f32_e32 v54, v51, v50
	v_fma_f32 v55, -v0, v54, v51
	v_fmac_f32_e32 v54, v55, v50
	v_fma_f32 v0, -v0, v54, v51
	v_div_fmas_f32 v0, v0, v50, v54
	v_div_fixup_f32 v47, v0, v47, 1.0
	v_div_scale_f32 v0, s[2:3], v46, v46, 1.0
	v_rcp_f32_e32 v50, v0
	s_nop 0
	v_fma_f32 v51, -v0, v50, 1.0
	v_fmac_f32_e32 v50, v51, v50
	v_div_scale_f32 v51, vcc, 1.0, v46, 1.0
	v_mul_f32_e32 v54, v51, v50
	v_fma_f32 v55, -v0, v54, v51
	v_fmac_f32_e32 v54, v55, v50
	v_fma_f32 v0, -v0, v54, v51
	v_div_fmas_f32 v0, v0, v50, v54
	v_div_fixup_f32 v46, v0, v46, 1.0
	v_div_scale_f32 v0, s[2:3], v45, v45, 1.0
	v_rcp_f32_e32 v50, v0
	v_pk_mul_f32 v[40:41], v[40:41], v[46:47]
	v_fma_f32 v51, -v0, v50, 1.0
	v_fmac_f32_e32 v50, v51, v50
	v_div_scale_f32 v51, vcc, 1.0, v45, 1.0
	v_mul_f32_e32 v54, v51, v50
	v_fma_f32 v55, -v0, v54, v51
	v_fmac_f32_e32 v54, v55, v50
	v_fma_f32 v0, -v0, v54, v51
	v_div_fmas_f32 v0, v0, v50, v54
	v_div_fixup_f32 v45, v0, v45, 1.0
	v_div_scale_f32 v0, s[2:3], v44, v44, 1.0
	v_rcp_f32_e32 v50, v0
	v_cvt_pk_bf16_f32 v40, v40, v41
	s_nop 0
	v_fma_f32 v51, -v0, v50, 1.0
	v_fmac_f32_e32 v50, v51, v50
	v_div_scale_f32 v51, vcc, 1.0, v44, 1.0
	v_mul_f32_e32 v54, v51, v50
	v_fma_f32 v55, -v0, v54, v51
	v_fmac_f32_e32 v54, v55, v50
	v_fma_f32 v0, -v0, v54, v51
	v_div_fmas_f32 v0, v0, v50, v54
	v_div_fixup_f32 v44, v0, v44, 1.0
	v_pk_mul_f32 v[42:43], v[42:43], v[44:45]
	s_nop 0
	v_cvt_pk_bf16_f32 v41, v42, v43
	global_store_dwordx2 v[48:49], v[40:41], off offset:256
	v_lshl_add_u64 v[40:41], v[52:53], 0, v[120:121]
	s_waitcnt vmcnt(31)
	v_mov_b32_e32 v40, v218
	v_mov_b32_e32 v41, v219
	s_nop 0
	v_lshlrev_b32_e32 v0, 16, v40
	v_mul_f32_e32 v0, 0xbfb8aa3b, v0
	v_exp_f32_e32 v42, v0
	v_and_b32_e32 v0, 0xffff0000, v40
	v_mul_f32_e32 v0, 0xbfb8aa3b, v0
	v_exp_f32_e32 v43, v0
	v_lshlrev_b32_e32 v0, 16, v41
	v_mul_f32_e32 v0, 0xbfb8aa3b, v0
	v_exp_f32_e32 v40, v0
	v_and_b32_e32 v0, 0xffff0000, v41
	v_mul_f32_e32 v0, 0xbfb8aa3b, v0
	v_pk_add_f32 v[42:43], v[42:43], 1.0 op_sel_hi:[1,0]
	v_exp_f32_e32 v41, v0
	v_div_scale_f32 v0, s[2:3], v43, v43, 1.0
	v_rcp_f32_e32 v44, v0
	v_pk_add_f32 v[40:41], v[40:41], 1.0 op_sel_hi:[1,0]
	v_fma_f32 v45, -v0, v44, 1.0
	v_fmac_f32_e32 v44, v45, v44
	v_div_scale_f32 v45, vcc, 1.0, v43, 1.0
	v_mul_f32_e32 v46, v45, v44
	v_fma_f32 v47, -v0, v46, v45
	v_fmac_f32_e32 v46, v47, v44
	v_fma_f32 v0, -v0, v46, v45
	v_div_fmas_f32 v0, v0, v44, v46
	v_div_fixup_f32 v43, v0, v43, 1.0
	v_div_scale_f32 v0, s[2:3], v42, v42, 1.0
	v_rcp_f32_e32 v44, v0
	s_nop 0
	v_fma_f32 v45, -v0, v44, 1.0
	v_fmac_f32_e32 v44, v45, v44
	v_div_scale_f32 v45, vcc, 1.0, v42, 1.0
	v_mul_f32_e32 v46, v45, v44
	v_fma_f32 v47, -v0, v46, v45
	v_fmac_f32_e32 v46, v47, v44
	v_fma_f32 v0, -v0, v46, v45
	v_div_fmas_f32 v0, v0, v44, v46
	v_div_fixup_f32 v42, v0, v42, 1.0
	v_div_scale_f32 v0, s[2:3], v41, v41, 1.0
	v_rcp_f32_e32 v44, v0
	v_pk_mul_f32 v[36:37], v[36:37], v[42:43]
	v_fma_f32 v45, -v0, v44, 1.0
	v_fmac_f32_e32 v44, v45, v44
	v_div_scale_f32 v45, vcc, 1.0, v41, 1.0
	v_mul_f32_e32 v46, v45, v44
	v_fma_f32 v47, -v0, v46, v45
	v_fmac_f32_e32 v46, v47, v44
	v_fma_f32 v0, -v0, v46, v45
	v_div_fmas_f32 v0, v0, v44, v46
	v_div_fixup_f32 v41, v0, v41, 1.0
	v_div_scale_f32 v0, s[2:3], v40, v40, 1.0
	v_rcp_f32_e32 v44, v0
	v_cvt_pk_bf16_f32 v36, v36, v37
	s_nop 0
	v_fma_f32 v45, -v0, v44, 1.0
	v_fmac_f32_e32 v44, v45, v44
	v_div_scale_f32 v45, vcc, 1.0, v40, 1.0
	v_mul_f32_e32 v46, v45, v44
	v_fma_f32 v47, -v0, v46, v45
	v_fmac_f32_e32 v46, v47, v44
	v_fma_f32 v0, -v0, v46, v45
	v_div_fmas_f32 v0, v0, v44, v46
	v_div_fixup_f32 v40, v0, v40, 1.0
	v_pk_mul_f32 v[38:39], v[38:39], v[40:41]
	s_nop 0
	v_cvt_pk_bf16_f32 v37, v38, v39
	global_store_dwordx2 v[48:49], v[36:37], off offset:288
	v_add_u32_e32 v36, 0xa0, v140
	v_ashrrev_i32_e32 v37, 31, v36
	v_lshlrev_b64 v[38:39], 12, v[36:37]
	v_mad_i64_i32 v[36:37], s[2:3], v36, s78, v[142:143]
	v_lshl_add_u64 v[36:37], v[36:37], 0, s[24:25]
	v_lshl_add_u64 v[40:41], v[36:37], 0, v[2:3]
	s_waitcnt vmcnt(31)
	v_mov_b32_e32 v40, v220
	v_mov_b32_e32 v41, v221
	s_nop 0
	v_lshlrev_b32_e32 v0, 16, v40
	v_mul_f32_e32 v0, 0xbfb8aa3b, v0
	v_exp_f32_e32 v42, v0
	v_and_b32_e32 v0, 0xffff0000, v40
	v_mul_f32_e32 v0, 0xbfb8aa3b, v0
	v_exp_f32_e32 v43, v0
	v_lshlrev_b32_e32 v0, 16, v41
	v_mul_f32_e32 v0, 0xbfb8aa3b, v0
	v_exp_f32_e32 v40, v0
	v_and_b32_e32 v0, 0xffff0000, v41
	v_mul_f32_e32 v0, 0xbfb8aa3b, v0
	v_pk_add_f32 v[42:43], v[42:43], 1.0 op_sel_hi:[1,0]
	v_exp_f32_e32 v41, v0
	v_div_scale_f32 v0, s[2:3], v43, v43, 1.0
	v_rcp_f32_e32 v44, v0
	v_pk_add_f32 v[40:41], v[40:41], 1.0 op_sel_hi:[1,0]
	v_fma_f32 v45, -v0, v44, 1.0
	v_fmac_f32_e32 v44, v45, v44
	v_div_scale_f32 v45, vcc, 1.0, v43, 1.0
	v_mul_f32_e32 v46, v45, v44
	v_fma_f32 v47, -v0, v46, v45
	v_fmac_f32_e32 v46, v47, v44
	v_fma_f32 v0, -v0, v46, v45
	v_div_fmas_f32 v0, v0, v44, v46
	v_div_fixup_f32 v43, v0, v43, 1.0
	v_div_scale_f32 v0, s[2:3], v42, v42, 1.0
	v_rcp_f32_e32 v44, v0
	s_nop 0
	v_fma_f32 v45, -v0, v44, 1.0
	v_fmac_f32_e32 v44, v45, v44
	v_div_scale_f32 v45, vcc, 1.0, v42, 1.0
	v_mul_f32_e32 v46, v45, v44
	v_fma_f32 v47, -v0, v46, v45
	v_fmac_f32_e32 v46, v47, v44
	v_fma_f32 v0, -v0, v46, v45
	v_div_fmas_f32 v0, v0, v44, v46
	v_div_fixup_f32 v42, v0, v42, 1.0
	v_div_scale_f32 v0, s[2:3], v41, v41, 1.0
	v_rcp_f32_e32 v44, v0
	v_pk_mul_f32 v[32:33], v[32:33], v[42:43]
	v_fma_f32 v45, -v0, v44, 1.0
	v_fmac_f32_e32 v44, v45, v44
	v_div_scale_f32 v45, vcc, 1.0, v41, 1.0
	v_mul_f32_e32 v46, v45, v44
	v_fma_f32 v47, -v0, v46, v45
	v_fmac_f32_e32 v46, v47, v44
	v_fma_f32 v0, -v0, v46, v45
	v_div_fmas_f32 v0, v0, v44, v46
	v_div_fixup_f32 v41, v0, v41, 1.0
	v_div_scale_f32 v0, s[2:3], v40, v40, 1.0
	v_rcp_f32_e32 v44, v0
	s_nop 0
	v_fma_f32 v45, -v0, v44, 1.0
	v_fmac_f32_e32 v44, v45, v44
	v_div_scale_f32 v45, vcc, 1.0, v40, 1.0
	v_mul_f32_e32 v46, v45, v44
	v_fma_f32 v47, -v0, v46, v45
	v_fmac_f32_e32 v46, v47, v44
	v_fma_f32 v0, -v0, v46, v45
	v_div_fmas_f32 v0, v0, v44, v46
	v_div_fixup_f32 v40, v0, v40, 1.0
	v_pk_mul_f32 v[34:35], v[34:35], v[40:41]
	v_cvt_pk_bf16_f32 v40, v32, v33
	v_lshl_add_u64 v[32:33], s[48:49], 0, v[38:39]
	v_cvt_pk_bf16_f32 v41, v34, v35
	v_lshl_add_u64 v[34:35], v[36:37], 0, v[128:129]
	s_waitcnt vmcnt(30)
	v_mov_b32_e32 v34, v222
	v_mov_b32_e32 v35, v223
	v_lshl_add_u64 v[32:33], v[32:33], 0, v[2:3]
	global_store_dwordx2 v[32:33], v[40:41], off
	s_nop 0
	v_lshlrev_b32_e32 v0, 16, v34
	v_mul_f32_e32 v0, 0xbfb8aa3b, v0
	v_exp_f32_e32 v38, v0
	v_and_b32_e32 v0, 0xffff0000, v34
	v_mul_f32_e32 v0, 0xbfb8aa3b, v0
	v_exp_f32_e32 v39, v0
	v_lshlrev_b32_e32 v0, 16, v35
	v_mul_f32_e32 v0, 0xbfb8aa3b, v0
	v_exp_f32_e32 v34, v0
	v_and_b32_e32 v0, 0xffff0000, v35
	v_mul_f32_e32 v0, 0xbfb8aa3b, v0
	v_pk_add_f32 v[38:39], v[38:39], 1.0 op_sel_hi:[1,0]
	v_exp_f32_e32 v35, v0
	v_div_scale_f32 v0, s[2:3], v39, v39, 1.0
	v_rcp_f32_e32 v40, v0
	v_pk_add_f32 v[34:35], v[34:35], 1.0 op_sel_hi:[1,0]
	v_fma_f32 v41, -v0, v40, 1.0
	v_fmac_f32_e32 v40, v41, v40
	v_div_scale_f32 v41, vcc, 1.0, v39, 1.0
	v_mul_f32_e32 v42, v41, v40
	v_fma_f32 v43, -v0, v42, v41
	v_fmac_f32_e32 v42, v43, v40
	v_fma_f32 v0, -v0, v42, v41
	v_div_fmas_f32 v0, v0, v40, v42
	v_div_fixup_f32 v39, v0, v39, 1.0
	v_div_scale_f32 v0, s[2:3], v38, v38, 1.0
	v_rcp_f32_e32 v40, v0
	s_nop 0
	v_fma_f32 v41, -v0, v40, 1.0
	v_fmac_f32_e32 v40, v41, v40
	v_div_scale_f32 v41, vcc, 1.0, v38, 1.0
	v_mul_f32_e32 v42, v41, v40
	v_fma_f32 v43, -v0, v42, v41
	v_fmac_f32_e32 v42, v43, v40
	v_fma_f32 v0, -v0, v42, v41
	v_div_fmas_f32 v0, v0, v40, v42
	v_div_fixup_f32 v38, v0, v38, 1.0
	v_div_scale_f32 v0, s[2:3], v35, v35, 1.0
	v_rcp_f32_e32 v40, v0
	v_pk_mul_f32 v[28:29], v[28:29], v[38:39]
	v_fma_f32 v41, -v0, v40, 1.0
	v_fmac_f32_e32 v40, v41, v40
	v_div_scale_f32 v41, vcc, 1.0, v35, 1.0
	v_mul_f32_e32 v42, v41, v40
	v_fma_f32 v43, -v0, v42, v41
	v_fmac_f32_e32 v42, v43, v40
	v_fma_f32 v0, -v0, v42, v41
	v_div_fmas_f32 v0, v0, v40, v42
	v_div_fixup_f32 v35, v0, v35, 1.0
	v_div_scale_f32 v0, s[2:3], v34, v34, 1.0
	v_rcp_f32_e32 v40, v0
	v_cvt_pk_bf16_f32 v28, v28, v29
	s_nop 0
	v_fma_f32 v41, -v0, v40, 1.0
	v_fmac_f32_e32 v40, v41, v40
	v_div_scale_f32 v41, vcc, 1.0, v34, 1.0
	v_mul_f32_e32 v42, v41, v40
	v_fma_f32 v43, -v0, v42, v41
	v_fmac_f32_e32 v42, v43, v40
	v_fma_f32 v0, -v0, v42, v41
	v_div_fmas_f32 v0, v0, v40, v42
	v_div_fixup_f32 v34, v0, v34, 1.0
	v_pk_mul_f32 v[30:31], v[30:31], v[34:35]
	s_nop 0
	v_cvt_pk_bf16_f32 v29, v30, v31
	global_store_dwordx2 v[32:33], v[28:29], off offset:32
	v_lshl_add_u64 v[28:29], v[36:37], 0, v[124:125]
	s_waitcnt vmcnt(31)
	v_mov_b32_e32 v28, v224
	v_mov_b32_e32 v29, v225
	s_nop 0
	v_lshlrev_b32_e32 v0, 16, v28
	v_mul_f32_e32 v0, 0xbfb8aa3b, v0
	v_exp_f32_e32 v30, v0
	v_and_b32_e32 v0, 0xffff0000, v28
	v_mul_f32_e32 v0, 0xbfb8aa3b, v0
	v_exp_f32_e32 v31, v0
	v_lshlrev_b32_e32 v0, 16, v29
	v_mul_f32_e32 v0, 0xbfb8aa3b, v0
	v_exp_f32_e32 v28, v0
	v_and_b32_e32 v0, 0xffff0000, v29
	v_mul_f32_e32 v0, 0xbfb8aa3b, v0
	v_pk_add_f32 v[30:31], v[30:31], 1.0 op_sel_hi:[1,0]
	v_exp_f32_e32 v29, v0
	v_div_scale_f32 v0, s[2:3], v31, v31, 1.0
	v_rcp_f32_e32 v34, v0
	v_pk_add_f32 v[28:29], v[28:29], 1.0 op_sel_hi:[1,0]
	v_fma_f32 v35, -v0, v34, 1.0
	v_fmac_f32_e32 v34, v35, v34
	v_div_scale_f32 v35, vcc, 1.0, v31, 1.0
	v_mul_f32_e32 v38, v35, v34
	v_fma_f32 v39, -v0, v38, v35
	v_fmac_f32_e32 v38, v39, v34
	v_fma_f32 v0, -v0, v38, v35
	v_div_fmas_f32 v0, v0, v34, v38
	v_div_fixup_f32 v31, v0, v31, 1.0
	v_div_scale_f32 v0, s[2:3], v30, v30, 1.0
	v_rcp_f32_e32 v34, v0
	s_nop 0
	v_fma_f32 v35, -v0, v34, 1.0
	v_fmac_f32_e32 v34, v35, v34
	v_div_scale_f32 v35, vcc, 1.0, v30, 1.0
	v_mul_f32_e32 v38, v35, v34
	v_fma_f32 v39, -v0, v38, v35
	v_fmac_f32_e32 v38, v39, v34
	v_fma_f32 v0, -v0, v38, v35
	v_div_fmas_f32 v0, v0, v34, v38
	v_div_fixup_f32 v30, v0, v30, 1.0
	v_div_scale_f32 v0, s[2:3], v29, v29, 1.0
	v_rcp_f32_e32 v34, v0
	v_pk_mul_f32 v[24:25], v[24:25], v[30:31]
	v_fma_f32 v35, -v0, v34, 1.0
	v_fmac_f32_e32 v34, v35, v34
	v_div_scale_f32 v35, vcc, 1.0, v29, 1.0
	v_mul_f32_e32 v38, v35, v34
	v_fma_f32 v39, -v0, v38, v35
	v_fmac_f32_e32 v38, v39, v34
	v_fma_f32 v0, -v0, v38, v35
	v_div_fmas_f32 v0, v0, v34, v38
	v_div_fixup_f32 v29, v0, v29, 1.0
	v_div_scale_f32 v0, s[2:3], v28, v28, 1.0
	v_rcp_f32_e32 v34, v0
	v_cvt_pk_bf16_f32 v24, v24, v25
	s_nop 0
	v_fma_f32 v35, -v0, v34, 1.0
	v_fmac_f32_e32 v34, v35, v34
	v_div_scale_f32 v35, vcc, 1.0, v28, 1.0
	v_mul_f32_e32 v38, v35, v34
	v_fma_f32 v39, -v0, v38, v35
	v_fmac_f32_e32 v38, v39, v34
	v_fma_f32 v0, -v0, v38, v35
	v_div_fmas_f32 v0, v0, v34, v38
	v_div_fixup_f32 v28, v0, v28, 1.0
	v_pk_mul_f32 v[26:27], v[26:27], v[28:29]
	s_nop 0
	v_cvt_pk_bf16_f32 v25, v26, v27
	global_store_dwordx2 v[32:33], v[24:25], off offset:256
	v_lshl_add_u64 v[24:25], v[36:37], 0, v[120:121]
	s_waitcnt vmcnt(31)
	v_mov_b32_e32 v24, v232
	v_mov_b32_e32 v25, v233
	s_nop 0
	v_lshlrev_b32_e32 v0, 16, v24
	v_mul_f32_e32 v0, 0xbfb8aa3b, v0
	v_exp_f32_e32 v26, v0
	v_and_b32_e32 v0, 0xffff0000, v24
	v_mul_f32_e32 v0, 0xbfb8aa3b, v0
	v_exp_f32_e32 v27, v0
	v_lshlrev_b32_e32 v0, 16, v25
	v_mul_f32_e32 v0, 0xbfb8aa3b, v0
	v_exp_f32_e32 v24, v0
	v_and_b32_e32 v0, 0xffff0000, v25
	v_mul_f32_e32 v0, 0xbfb8aa3b, v0
	v_pk_add_f32 v[26:27], v[26:27], 1.0 op_sel_hi:[1,0]
	v_exp_f32_e32 v25, v0
	v_div_scale_f32 v0, s[2:3], v27, v27, 1.0
	v_rcp_f32_e32 v28, v0
	v_pk_add_f32 v[24:25], v[24:25], 1.0 op_sel_hi:[1,0]
	v_fma_f32 v29, -v0, v28, 1.0
	v_fmac_f32_e32 v28, v29, v28
	v_div_scale_f32 v29, vcc, 1.0, v27, 1.0
	v_mul_f32_e32 v30, v29, v28
	v_fma_f32 v31, -v0, v30, v29
	v_fmac_f32_e32 v30, v31, v28
	v_fma_f32 v0, -v0, v30, v29
	v_div_fmas_f32 v0, v0, v28, v30
	v_div_fixup_f32 v27, v0, v27, 1.0
	v_div_scale_f32 v0, s[2:3], v26, v26, 1.0
	v_rcp_f32_e32 v28, v0
	s_nop 0
	v_fma_f32 v29, -v0, v28, 1.0
	v_fmac_f32_e32 v28, v29, v28
	v_div_scale_f32 v29, vcc, 1.0, v26, 1.0
	v_mul_f32_e32 v30, v29, v28
	v_fma_f32 v31, -v0, v30, v29
	v_fmac_f32_e32 v30, v31, v28
	v_fma_f32 v0, -v0, v30, v29
	v_div_fmas_f32 v0, v0, v28, v30
	v_div_fixup_f32 v26, v0, v26, 1.0
	v_div_scale_f32 v0, s[2:3], v25, v25, 1.0
	v_rcp_f32_e32 v28, v0
	v_pk_mul_f32 v[20:21], v[20:21], v[26:27]
	v_fma_f32 v29, -v0, v28, 1.0
	v_fmac_f32_e32 v28, v29, v28
	v_div_scale_f32 v29, vcc, 1.0, v25, 1.0
	v_mul_f32_e32 v30, v29, v28
	v_fma_f32 v31, -v0, v30, v29
	v_fmac_f32_e32 v30, v31, v28
	v_fma_f32 v0, -v0, v30, v29
	v_div_fmas_f32 v0, v0, v28, v30
	v_div_fixup_f32 v25, v0, v25, 1.0
	v_div_scale_f32 v0, s[2:3], v24, v24, 1.0
	v_rcp_f32_e32 v28, v0
	v_cvt_pk_bf16_f32 v20, v20, v21
	s_nop 0
	v_fma_f32 v29, -v0, v28, 1.0
	v_fmac_f32_e32 v28, v29, v28
	v_div_scale_f32 v29, vcc, 1.0, v24, 1.0
	v_mul_f32_e32 v30, v29, v28
	v_fma_f32 v31, -v0, v30, v29
	v_fmac_f32_e32 v30, v31, v28
	v_fma_f32 v0, -v0, v30, v29
	v_div_fmas_f32 v0, v0, v28, v30
	v_div_fixup_f32 v24, v0, v24, 1.0
	v_pk_mul_f32 v[22:23], v[22:23], v[24:25]
	s_nop 0
	v_cvt_pk_bf16_f32 v21, v22, v23
	global_store_dwordx2 v[32:33], v[20:21], off offset:288
	v_add_u32_e32 v20, 0xb0, v140
	v_ashrrev_i32_e32 v21, 31, v20
	v_lshlrev_b64 v[22:23], 12, v[20:21]
	v_mad_i64_i32 v[20:21], s[2:3], v20, s78, v[142:143]
	v_lshl_add_u64 v[20:21], v[20:21], 0, s[24:25]
	v_lshl_add_u64 v[24:25], v[20:21], 0, v[2:3]
	s_waitcnt vmcnt(31)
	v_mov_b32_e32 v24, v234
	v_mov_b32_e32 v25, v235
	s_nop 0
	v_lshlrev_b32_e32 v0, 16, v24
	v_mul_f32_e32 v0, 0xbfb8aa3b, v0
	v_exp_f32_e32 v26, v0
	v_and_b32_e32 v0, 0xffff0000, v24
	v_mul_f32_e32 v0, 0xbfb8aa3b, v0
	v_exp_f32_e32 v27, v0
	v_lshlrev_b32_e32 v0, 16, v25
	v_mul_f32_e32 v0, 0xbfb8aa3b, v0
	v_exp_f32_e32 v24, v0
	v_and_b32_e32 v0, 0xffff0000, v25
	v_mul_f32_e32 v0, 0xbfb8aa3b, v0
	v_pk_add_f32 v[26:27], v[26:27], 1.0 op_sel_hi:[1,0]
	v_exp_f32_e32 v25, v0
	v_div_scale_f32 v0, s[2:3], v27, v27, 1.0
	v_rcp_f32_e32 v28, v0
	v_pk_add_f32 v[24:25], v[24:25], 1.0 op_sel_hi:[1,0]
	v_fma_f32 v29, -v0, v28, 1.0
	v_fmac_f32_e32 v28, v29, v28
	v_div_scale_f32 v29, vcc, 1.0, v27, 1.0
	v_mul_f32_e32 v30, v29, v28
	v_fma_f32 v31, -v0, v30, v29
	v_fmac_f32_e32 v30, v31, v28
	v_fma_f32 v0, -v0, v30, v29
	v_div_fmas_f32 v0, v0, v28, v30
	v_div_fixup_f32 v27, v0, v27, 1.0
	v_div_scale_f32 v0, s[2:3], v26, v26, 1.0
	v_rcp_f32_e32 v28, v0
	s_nop 0
	v_fma_f32 v29, -v0, v28, 1.0
	v_fmac_f32_e32 v28, v29, v28
	v_div_scale_f32 v29, vcc, 1.0, v26, 1.0
	v_mul_f32_e32 v30, v29, v28
	v_fma_f32 v31, -v0, v30, v29
	v_fmac_f32_e32 v30, v31, v28
	v_fma_f32 v0, -v0, v30, v29
	v_div_fmas_f32 v0, v0, v28, v30
	v_div_fixup_f32 v26, v0, v26, 1.0
	v_div_scale_f32 v0, s[2:3], v25, v25, 1.0
	v_rcp_f32_e32 v28, v0
	v_pk_mul_f32 v[16:17], v[16:17], v[26:27]
	v_fma_f32 v29, -v0, v28, 1.0
	v_fmac_f32_e32 v28, v29, v28
	v_div_scale_f32 v29, vcc, 1.0, v25, 1.0
	v_mul_f32_e32 v30, v29, v28
	v_fma_f32 v31, -v0, v30, v29
	v_fmac_f32_e32 v30, v31, v28
	v_fma_f32 v0, -v0, v30, v29
	v_div_fmas_f32 v0, v0, v28, v30
	v_div_fixup_f32 v25, v0, v25, 1.0
	v_div_scale_f32 v0, s[2:3], v24, v24, 1.0
	v_rcp_f32_e32 v28, v0
	v_cvt_pk_bf16_f32 v16, v16, v17
	s_nop 0
	v_fma_f32 v29, -v0, v28, 1.0
	v_fmac_f32_e32 v28, v29, v28
	v_div_scale_f32 v29, vcc, 1.0, v24, 1.0
	v_mul_f32_e32 v30, v29, v28
	v_fma_f32 v31, -v0, v30, v29
	v_fmac_f32_e32 v30, v31, v28
	v_fma_f32 v0, -v0, v30, v29
	v_div_fmas_f32 v0, v0, v28, v30
	v_div_fixup_f32 v24, v0, v24, 1.0
	v_pk_mul_f32 v[18:19], v[18:19], v[24:25]
	s_nop 0
	v_cvt_pk_bf16_f32 v17, v18, v19
	v_lshl_add_u64 v[18:19], s[48:49], 0, v[22:23]
	v_lshl_add_u64 v[2:3], v[18:19], 0, v[2:3]
	global_store_dwordx2 v[2:3], v[16:17], off
	v_lshl_add_u64 v[16:17], v[20:21], 0, v[128:129]
	s_waitcnt vmcnt(31)
	v_mov_b32_e32 v16, v236
	v_mov_b32_e32 v17, v237
	s_nop 0
	v_lshlrev_b32_e32 v0, 16, v16
	v_mul_f32_e32 v0, 0xbfb8aa3b, v0
	v_exp_f32_e32 v18, v0
	v_and_b32_e32 v0, 0xffff0000, v16
	v_mul_f32_e32 v0, 0xbfb8aa3b, v0
	v_exp_f32_e32 v19, v0
	v_lshlrev_b32_e32 v0, 16, v17
	v_mul_f32_e32 v0, 0xbfb8aa3b, v0
	v_exp_f32_e32 v16, v0
	v_and_b32_e32 v0, 0xffff0000, v17
	v_mul_f32_e32 v0, 0xbfb8aa3b, v0
	v_pk_add_f32 v[18:19], v[18:19], 1.0 op_sel_hi:[1,0]
	v_exp_f32_e32 v17, v0
	v_div_scale_f32 v0, s[2:3], v19, v19, 1.0
	v_rcp_f32_e32 v22, v0
	v_pk_add_f32 v[16:17], v[16:17], 1.0 op_sel_hi:[1,0]
	v_fma_f32 v23, -v0, v22, 1.0
	v_fmac_f32_e32 v22, v23, v22
	v_div_scale_f32 v23, vcc, 1.0, v19, 1.0
	v_mul_f32_e32 v24, v23, v22
	v_fma_f32 v25, -v0, v24, v23
	v_fmac_f32_e32 v24, v25, v22
	v_fma_f32 v0, -v0, v24, v23
	v_div_fmas_f32 v0, v0, v22, v24
	v_div_fixup_f32 v19, v0, v19, 1.0
	v_div_scale_f32 v0, s[2:3], v18, v18, 1.0
	v_rcp_f32_e32 v22, v0
	s_nop 0
	v_fma_f32 v23, -v0, v22, 1.0
	v_fmac_f32_e32 v22, v23, v22
	v_div_scale_f32 v23, vcc, 1.0, v18, 1.0
	v_mul_f32_e32 v24, v23, v22
	v_fma_f32 v25, -v0, v24, v23
	v_fmac_f32_e32 v24, v25, v22
	v_fma_f32 v0, -v0, v24, v23
	v_div_fmas_f32 v0, v0, v22, v24
	v_div_fixup_f32 v18, v0, v18, 1.0
	v_div_scale_f32 v0, s[2:3], v17, v17, 1.0
	v_rcp_f32_e32 v22, v0
	v_pk_mul_f32 v[12:13], v[12:13], v[18:19]
	v_fma_f32 v23, -v0, v22, 1.0
	v_fmac_f32_e32 v22, v23, v22
	v_div_scale_f32 v23, vcc, 1.0, v17, 1.0
	v_mul_f32_e32 v24, v23, v22
	v_fma_f32 v25, -v0, v24, v23
	v_fmac_f32_e32 v24, v25, v22
	v_fma_f32 v0, -v0, v24, v23
	v_div_fmas_f32 v0, v0, v22, v24
	v_div_fixup_f32 v17, v0, v17, 1.0
	v_div_scale_f32 v0, s[2:3], v16, v16, 1.0
	v_rcp_f32_e32 v22, v0
	v_cvt_pk_bf16_f32 v12, v12, v13
	s_nop 0
	v_fma_f32 v23, -v0, v22, 1.0
	v_fmac_f32_e32 v22, v23, v22
	v_div_scale_f32 v23, vcc, 1.0, v16, 1.0
	v_mul_f32_e32 v24, v23, v22
	v_fma_f32 v25, -v0, v24, v23
	v_fmac_f32_e32 v24, v25, v22
	v_fma_f32 v0, -v0, v24, v23
	v_div_fmas_f32 v0, v0, v22, v24
	v_div_fixup_f32 v16, v0, v16, 1.0
	v_pk_mul_f32 v[14:15], v[14:15], v[16:17]
	s_nop 0
	v_cvt_pk_bf16_f32 v13, v14, v15
	global_store_dwordx2 v[2:3], v[12:13], off offset:32
	v_lshl_add_u64 v[12:13], v[20:21], 0, v[124:125]
	s_waitcnt vmcnt(31)
	v_mov_b32_e32 v12, v238
	v_mov_b32_e32 v13, v239
	s_nop 0
	v_lshlrev_b32_e32 v0, 16, v12
	v_mul_f32_e32 v0, 0xbfb8aa3b, v0
	v_exp_f32_e32 v14, v0
	v_and_b32_e32 v0, 0xffff0000, v12
	v_mul_f32_e32 v0, 0xbfb8aa3b, v0
	v_exp_f32_e32 v15, v0
	v_lshlrev_b32_e32 v0, 16, v13
	v_mul_f32_e32 v0, 0xbfb8aa3b, v0
	v_exp_f32_e32 v12, v0
	v_and_b32_e32 v0, 0xffff0000, v13
	v_mul_f32_e32 v0, 0xbfb8aa3b, v0
	v_pk_add_f32 v[14:15], v[14:15], 1.0 op_sel_hi:[1,0]
	v_exp_f32_e32 v13, v0
	v_div_scale_f32 v0, s[2:3], v15, v15, 1.0
	v_rcp_f32_e32 v16, v0
	v_pk_add_f32 v[12:13], v[12:13], 1.0 op_sel_hi:[1,0]
	v_fma_f32 v17, -v0, v16, 1.0
	v_fmac_f32_e32 v16, v17, v16
	v_div_scale_f32 v17, vcc, 1.0, v15, 1.0
	v_mul_f32_e32 v18, v17, v16
	v_fma_f32 v19, -v0, v18, v17
	v_fmac_f32_e32 v18, v19, v16
	v_fma_f32 v0, -v0, v18, v17
	v_div_fmas_f32 v0, v0, v16, v18
	v_div_fixup_f32 v15, v0, v15, 1.0
	v_div_scale_f32 v0, s[2:3], v14, v14, 1.0
	v_rcp_f32_e32 v16, v0
	s_nop 0
	v_fma_f32 v17, -v0, v16, 1.0
	v_fmac_f32_e32 v16, v17, v16
	v_div_scale_f32 v17, vcc, 1.0, v14, 1.0
	v_mul_f32_e32 v18, v17, v16
	v_fma_f32 v19, -v0, v18, v17
	v_fmac_f32_e32 v18, v19, v16
	v_fma_f32 v0, -v0, v18, v17
	v_div_fmas_f32 v0, v0, v16, v18
	v_div_fixup_f32 v14, v0, v14, 1.0
	v_div_scale_f32 v0, s[2:3], v13, v13, 1.0
	v_rcp_f32_e32 v16, v0
	v_pk_mul_f32 v[8:9], v[8:9], v[14:15]
	v_fma_f32 v17, -v0, v16, 1.0
	v_fmac_f32_e32 v16, v17, v16
	v_div_scale_f32 v17, vcc, 1.0, v13, 1.0
	v_mul_f32_e32 v18, v17, v16
	v_fma_f32 v19, -v0, v18, v17
	v_fmac_f32_e32 v18, v19, v16
	v_fma_f32 v0, -v0, v18, v17
	v_div_fmas_f32 v0, v0, v16, v18
	v_div_fixup_f32 v13, v0, v13, 1.0
	v_div_scale_f32 v0, s[2:3], v12, v12, 1.0
	v_rcp_f32_e32 v16, v0
	v_cvt_pk_bf16_f32 v8, v8, v9
	s_nop 0
	v_fma_f32 v17, -v0, v16, 1.0
	v_fmac_f32_e32 v16, v17, v16
	v_div_scale_f32 v17, vcc, 1.0, v12, 1.0
	v_mul_f32_e32 v18, v17, v16
	v_fma_f32 v19, -v0, v18, v17
	v_fmac_f32_e32 v18, v19, v16
	v_fma_f32 v0, -v0, v18, v17
	v_div_fmas_f32 v0, v0, v16, v18
	v_div_fixup_f32 v12, v0, v12, 1.0
	v_pk_mul_f32 v[10:11], v[10:11], v[12:13]
	s_nop 0
	v_cvt_pk_bf16_f32 v9, v10, v11
	global_store_dwordx2 v[2:3], v[8:9], off offset:256
	v_lshl_add_u64 v[8:9], v[20:21], 0, v[120:121]
	s_waitcnt vmcnt(31)
	v_mov_b32_e32 v8, v240
	v_mov_b32_e32 v9, v241
	s_nop 0
	v_lshlrev_b32_e32 v0, 16, v8
	v_mul_f32_e32 v0, 0xbfb8aa3b, v0
	v_exp_f32_e32 v10, v0
	v_and_b32_e32 v0, 0xffff0000, v8
	v_mul_f32_e32 v0, 0xbfb8aa3b, v0
	v_exp_f32_e32 v11, v0
	v_lshlrev_b32_e32 v0, 16, v9
	v_mul_f32_e32 v0, 0xbfb8aa3b, v0
	v_exp_f32_e32 v8, v0
	v_and_b32_e32 v0, 0xffff0000, v9
	v_mul_f32_e32 v0, 0xbfb8aa3b, v0
	v_pk_add_f32 v[10:11], v[10:11], 1.0 op_sel_hi:[1,0]
	v_exp_f32_e32 v9, v0
	v_div_scale_f32 v0, s[2:3], v11, v11, 1.0
	v_rcp_f32_e32 v12, v0
	v_pk_add_f32 v[8:9], v[8:9], 1.0 op_sel_hi:[1,0]
	v_fma_f32 v13, -v0, v12, 1.0
	v_fmac_f32_e32 v12, v13, v12
	v_div_scale_f32 v13, vcc, 1.0, v11, 1.0
	v_mul_f32_e32 v14, v13, v12
	v_fma_f32 v15, -v0, v14, v13
	v_fmac_f32_e32 v14, v15, v12
	v_fma_f32 v0, -v0, v14, v13
	v_div_fmas_f32 v0, v0, v12, v14
	v_div_fixup_f32 v11, v0, v11, 1.0
	v_div_scale_f32 v0, s[2:3], v10, v10, 1.0
	v_rcp_f32_e32 v12, v0
	s_nop 0
	v_fma_f32 v13, -v0, v12, 1.0
	v_fmac_f32_e32 v12, v13, v12
	v_div_scale_f32 v13, vcc, 1.0, v10, 1.0
	v_mul_f32_e32 v14, v13, v12
	v_fma_f32 v15, -v0, v14, v13
	v_fmac_f32_e32 v14, v15, v12
	v_fma_f32 v0, -v0, v14, v13
	v_div_fmas_f32 v0, v0, v12, v14
	v_div_fixup_f32 v10, v0, v10, 1.0
	v_div_scale_f32 v0, s[2:3], v9, v9, 1.0
	v_rcp_f32_e32 v12, v0
	v_pk_mul_f32 v[4:5], v[4:5], v[10:11]
	v_fma_f32 v13, -v0, v12, 1.0
	v_fmac_f32_e32 v12, v13, v12
	v_div_scale_f32 v13, vcc, 1.0, v9, 1.0
	v_mul_f32_e32 v14, v13, v12
	v_fma_f32 v15, -v0, v14, v13
	v_fmac_f32_e32 v14, v15, v12
	v_fma_f32 v0, -v0, v14, v13
	v_div_fmas_f32 v0, v0, v12, v14
	v_div_fixup_f32 v9, v0, v9, 1.0
	v_div_scale_f32 v0, s[2:3], v8, v8, 1.0
	v_rcp_f32_e32 v12, v0
	v_cvt_pk_bf16_f32 v4, v4, v5
	s_mov_b64 s[2:3], -1
	v_fma_f32 v13, -v0, v12, 1.0
	v_fmac_f32_e32 v12, v13, v12
	v_div_scale_f32 v13, vcc, 1.0, v8, 1.0
	v_mul_f32_e32 v14, v13, v12
	v_fma_f32 v15, -v0, v14, v13
	v_fmac_f32_e32 v14, v15, v12
	v_fma_f32 v0, -v0, v14, v13
	v_div_fmas_f32 v0, v0, v12, v14
	v_div_fixup_f32 v8, v0, v8, 1.0
	v_pk_mul_f32 v[6:7], v[6:7], v[8:9]
	s_and_b64 vcc, exec, s[40:41]
	v_cvt_pk_bf16_f32 v5, v6, v7
	global_store_dwordx2 v[2:3], v[4:5], off offset:288
	s_cbranch_vccnz .LBB0_1122
	s_andn2_b64 vcc, exec, s[44:45]
	s_cbranch_vccnz .LBB0_1121
	s_barrier
	s_branch .LBB0_1121

.LBB0_1504:
	v_lshl_add_u64 v[54:55], s[2:3], 0, v[32:33]
	v_lshl_add_u64 v[74:75], s[2:3], 0, v[34:35]
	v_lshl_add_u64 v[76:77], v[54:55], 0, s[12:13]
	v_add_co_u32_e32 v78, vcc, 0x38e00000, v54
	v_lshl_add_u64 v[80:81], v[54:55], 0, s[14:15]
	v_add_co_u32_e64 v82, s[0:1], s19, v74
	global_load_dwordx4 v[38:41], v[76:77], off offset:16
	global_load_dwordx4 v[42:45], v[76:77], off offset:32
	global_load_dwordx4 v[46:49], v[80:81], off offset:48
	global_load_dwordx4 v[50:53], v[80:81], off offset:32
	v_addc_co_u32_e32 v79, vcc, 0, v55, vcc
	v_addc_co_u32_e64 v83, s[0:1], 0, v75, s[0:1]
	global_load_dwordx4 v[54:57], v[78:79], off
	global_load_dwordx4 v[58:61], v[76:77], off offset:48
	global_load_dwordx4 v[62:65], v[78:79], off offset:64
	global_load_dwordx4 v[66:69], v[80:81], off offset:16
	global_load_dwordx4 v[70:73], v[82:83], off offset:-4096
	v_add_co_u32_e32 v74, vcc, s18, v74
	v_lshl_add_u64 v[76:77], s[6:7], 0, v[34:35]
	s_nop 0
	v_addc_co_u32_e32 v75, vcc, 0, v75, vcc
	global_load_dwordx4 v[86:89], v[74:75], off offset:1024
	global_load_dwordx4 v[90:93], v[74:75], off offset:2048
	global_load_dwordx4 v[94:97], v[74:75], off offset:3072
	global_load_dwordx4 v[98:101], v[82:83], off
	global_load_dwordx4 v[102:105], v[82:83], off offset:1024
	global_load_dwordx4 v[106:109], v[82:83], off offset:2048
	global_load_dwordx4 v[110:113], v[82:83], off offset:3072
	v_add_u32_e32 v36, s22, v36
	v_lshl_add_u64 v[32:33], v[32:33], 0, s[4:5]
	v_lshl_add_u64 v[34:35], v[34:35], 0, s[8:9]
	s_waitcnt vmcnt(15)
	v_mov_b32_e32 v79, v38
	v_mov_b32_e32 v81, v40
	s_waitcnt vmcnt(14)
	v_mov_b32_e32 v84, v43
	v_mov_b32_e32 v85, v44
	s_waitcnt vmcnt(11)
	v_mov_b32_e32 v78, v54
	v_mov_b32_e32 v38, v55
	v_mov_b32_e32 v80, v56
	v_mov_b32_e32 v40, v57
	v_mov_b32_e32 v43, v45
	v_pk_add_f32 v[38:39], v[78:79], v[38:39]
	v_pk_add_f32 v[40:41], v[80:81], v[40:41]
	v_pk_add_f32 v[42:43], v[84:85], v[42:43]
	v_pk_add_f32 v[38:39], v[38:39], v[40:41]
	v_pk_add_f32 v[42:43], v[42:43], v[42:43] op_sel:[0,1] op_sel_hi:[1,0]
	v_add_f32_e32 v38, 0, v38
	v_add_f32_e32 v44, v50, v51
	v_add_f32_e32 v50, v52, v53
	v_mov_b32_e32 v45, v48
	v_mov_b32_e32 v51, v49
	s_waitcnt vmcnt(10)
	v_add_f32_e32 v48, v58, v59
	v_add_f32_e32 v52, v60, v61
	s_waitcnt vmcnt(9)
	v_mov_b32_e32 v55, v62
	v_mov_b32_e32 v49, v64
	v_mov_b32_e32 v53, v65
	v_mov_b32_e32 v43, v63
	v_add_f32_e32 v54, v38, v39
	s_waitcnt vmcnt(8)
	v_mov_b32_e32 v56, v67
	v_mov_b32_e32 v57, v68
	v_mov_b32_e32 v67, v69
	v_pk_add_f32 v[48:49], v[48:49], v[52:53]
	v_pk_add_f32 v[38:39], v[54:55], v[42:43]
	v_pk_add_f32 v[44:45], v[44:45], v[50:51]
	v_pk_add_f32 v[50:51], v[56:57], v[66:67]
	v_pk_add_f32 v[38:39], v[38:39], v[48:49]
	v_pk_add_f32 v[40:41], v[50:51], v[50:51] op_sel:[0,1] op_sel_hi:[1,0]
	v_pk_add_f32 v[38:39], v[38:39], v[38:39] op_sel:[0,1] op_sel_hi:[1,0]
	v_mov_b32_e32 v41, v47
	v_mov_b32_e32 v39, v46
	v_pk_add_f32 v[38:39], v[38:39], v[40:41]
	s_nop 0
	v_pk_add_f32 v[38:39], v[38:39], v[44:45]
	s_nop 0
	v_add_f32_e32 v38, v38, v39
	v_fmamk_f32 v38, v38, 0x3a000000, v37
	v_mul_f32_e32 v39, 0x4b800000, v38
	v_cmp_gt_f32_e32 vcc, s17, v38
	s_nop 1
	v_cndmask_b32_e32 v38, v38, v39, vcc
	v_rsq_f32_e32 v38, v38
	s_nop 0
	v_mul_f32_e32 v39, 0x45800000, v38
	v_cndmask_b32_e32 v42, v38, v39, vcc
	s_waitcnt vmcnt(7)
	v_pk_mul_f32 v[38:39], v[70:71], v[42:43] op_sel_hi:[1,0]
	v_pk_mul_f32 v[40:41], v[72:73], v[42:43] op_sel_hi:[1,0]
	v_pk_mul_f32 v[38:39], v[0:1], v[38:39]
	v_pk_mul_f32 v[40:41], v[2:3], v[40:41]
	global_store_dwordx4 v[76:77], v[38:41], off
	v_add_co_u32_e32 v44, vcc, s16, v76
	s_waitcnt vmcnt(7)
	s_nop 1
	v_pk_mul_f32 v[40:41], v[88:89], v[42:43] op_sel_hi:[1,0]
	v_pk_mul_f32 v[38:39], v[86:87], v[42:43] op_sel_hi:[1,0]
	v_pk_mul_f32 v[40:41], v[6:7], v[40:41]
	v_pk_mul_f32 v[38:39], v[4:5], v[38:39]
	global_store_dwordx4 v[76:77], v[38:41], off offset:1024
	v_addc_co_u32_e32 v45, vcc, 0, v77, vcc
	v_cmp_lt_i32_e32 vcc, s20, v36
	s_or_b64 s[10:11], vcc, s[10:11]
	s_waitcnt vmcnt(7)
	s_nop 1
	v_pk_mul_f32 v[40:41], v[92:93], v[42:43] op_sel_hi:[1,0]
	v_pk_mul_f32 v[38:39], v[90:91], v[42:43] op_sel_hi:[1,0]
	v_pk_mul_f32 v[40:41], v[10:11], v[40:41]
	v_pk_mul_f32 v[38:39], v[8:9], v[38:39]
	global_store_dwordx4 v[76:77], v[38:41], off offset:2048
	s_waitcnt vmcnt(7)
	s_nop 1
	v_pk_mul_f32 v[40:41], v[96:97], v[42:43] op_sel_hi:[1,0]
	v_pk_mul_f32 v[38:39], v[94:95], v[42:43] op_sel_hi:[1,0]
	v_pk_mul_f32 v[40:41], v[14:15], v[40:41]
	v_pk_mul_f32 v[38:39], v[12:13], v[38:39]
	global_store_dwordx4 v[76:77], v[38:41], off offset:3072
	s_waitcnt vmcnt(7)
	s_nop 1
	v_pk_mul_f32 v[40:41], v[100:101], v[42:43] op_sel_hi:[1,0]
	v_pk_mul_f32 v[38:39], v[98:99], v[42:43] op_sel_hi:[1,0]
	v_pk_mul_f32 v[40:41], v[18:19], v[40:41]
	v_pk_mul_f32 v[38:39], v[16:17], v[38:39]
	global_store_dwordx4 v[44:45], v[38:41], off
	s_waitcnt vmcnt(7)
	s_nop 1
	v_pk_mul_f32 v[40:41], v[104:105], v[42:43] op_sel_hi:[1,0]
	v_pk_mul_f32 v[38:39], v[102:103], v[42:43] op_sel_hi:[1,0]
	v_pk_mul_f32 v[40:41], v[22:23], v[40:41]
	v_pk_mul_f32 v[38:39], v[20:21], v[38:39]
	global_store_dwordx4 v[44:45], v[38:41], off offset:1024
	s_waitcnt vmcnt(7)
	s_nop 1
	v_pk_mul_f32 v[40:41], v[42:43], v[108:109] op_sel_hi:[0,1]
	v_pk_mul_f32 v[38:39], v[42:43], v[106:107] op_sel_hi:[0,1]
	v_pk_mul_f32 v[38:39], v[24:25], v[38:39]
	v_pk_mul_f32 v[40:41], v[26:27], v[40:41]
	global_store_dwordx4 v[44:45], v[38:41], off offset:2048
	s_waitcnt vmcnt(7)
	s_nop 1
	v_pk_mul_f32 v[40:41], v[42:43], v[112:113] op_sel_hi:[0,1]
	v_pk_mul_f32 v[38:39], v[42:43], v[110:111] op_sel_hi:[0,1]
	v_pk_mul_f32 v[38:39], v[28:29], v[38:39]
	v_pk_mul_f32 v[40:41], v[30:31], v[40:41]
	global_store_dwordx4 v[44:45], v[38:41], off offset:3072
	s_andn2_b64 exec, exec, s[10:11]
	s_cbranch_execnz .LBB0_1504
